# s_sleep 1 before the vmcnt wait in every GEMM load segment (48 sites)
# speedup vs baseline: 1.0038x; 1.0038x over previous
; #define PG8_STAGE(bufoff, gbase, voff) do { _Pragma("unroll") for (int _i = 0; _i < 2; ++_i) \
;         __builtin_amdgcn_global_load_lds((const unsigned*)((const char*)(gbase) + (voff)[_i]), (PG8_LAS unsigned*)(lds + (bufoff) + ldsw + _i * 8192), 16, 0, 0); } while (0)
; #define PG8_LDA(dst, b, h) do { _Pragma("unroll") for (int m = 0; m < 4; ++m) _Pragma("unroll") for (int k = 0; k < 2; ++k) dst[m][k] = *(const PG8_LAS bf16x8*)(lds + PG8_SA(b, h) + aoff + m * 2048 + k * 1024); } while (0)
; #define PG8_LDB(dst, b, h) do { _Pragma("unroll") for (int n = 0; n < 2; ++n) _Pragma("unroll") for (int k = 0; k < 2; ++k) dst[n][k] = *(const PG8_LAS bf16x8*)(lds + PG8_SB(b, h) + boff + n * 2048 + k * 1024); } while (0)
; #define PG8_MMA(ai, bj, At, Bt) do { __builtin_amdgcn_s_setprio(1); _Pragma("unroll") for (int m = 0; m < 4; ++m) _Pragma("unroll") for (int n = 0; n < 2; ++n) _Pragma("unroll") for (int k = 0; k < 2; ++k) \
;         acc[ai][bj][m][n] = __builtin_amdgcn_mfma_f32_16x16x32_bf16(Bt[n][k], At[m][k], acc[ai][bj][m][n], 0, 0, 0); __builtin_amdgcn_s_setprio(0); } while (0)
; #define PG8_WAIT_V(n) asm volatile("s_waitcnt vmcnt(" #n ")" ::: "memory")
; #define PG8_WAIT_L(n) asm volatile("s_waitcnt lgkmcnt(" #n ")" ::: "memory")
; template <class Epi, class Sched, bool ALIGN_EPI = false, bool SP2 = false>
; __device__ __forceinline__ void gemm_phase(PG8_LAS unsigned char* lds, const Gemm g, const Sched& S, const Epi& E) {
;     ...
;             const bool last = (t == nt - 2);
;             const char* a1 = cA + (size_t)(t + 1) * kstep;
;             const char* a2 = last ? nA : cA + (size_t)(t + 2) * kstep; const char* b2 = last ? nB : cB + (size_t)(t + 2) * kstep;
;             const char* a3 = a2 + kstep; const char* b3 = b2 + kstep;
;             if (last && has_next) S.a_ready(nxt);
;             if constexpr (SP2) {
;             PG8_LDB(B0, 0, 0); PG8_LDB(B1, 0, 1); PG8_SCHED; PG8_LDA(At, 0, 0); PG8_STAGE(PG8_SA(1, 1), a1 + hstep, voffA);
;             PG8_WAIT_V(8); PG8_WAIT_L(0); PG8_BAR; PG8_MMA(0, 0, At, B0); PG8_MMA(0, 1, At, B1); PG8_BAR; PG8_SCHED;
;             PG8_LDA(At, 0, 1); PG8_STAGE(PG8_SB(0, 0), b2, voffB); PG8_STAGE(PG8_SB(0, 1), b2 + hstep, voffB); PG8_STAGE(PG8_SA(0, 0), a2, voffA);
;             PG8_WAIT_V(8); PG8_WAIT_L(0); PG8_BAR; PG8_MMA(1, 0, At, B0); PG8_MMA(1, 1, At, B1); PG8_BAR; PG8_SCHED;
.LBB0_220:
	ds_read_b128 v[152:155], v148
	ds_read_b128 v[156:159], v148 offset:1024
	ds_read_b128 v[160:163], v148 offset:2048
	ds_read_b128 v[164:167], v148 offset:3072
	ds_read_b128 v[168:171], v149
	ds_read_b128 v[172:175], v149 offset:1024
	ds_read_b128 v[176:179], v149 offset:2048
	ds_read_b128 v[180:183], v149 offset:3072
	s_add_u32 s26, s24, 0xfff80080
	s_addc_u32 s27, s25, -1
	s_cmp_eq_u32 s51, 28
	s_cselect_b32 s29, s19, s27
	s_cselect_b32 s28, s47, s26
	s_cselect_b32 s27, s17, s50
	s_cselect_b32 s26, s48, s49
	v_lshl_add_u64 v[216:217], s[24:25], 0, v[136:137]
	s_add_i32 m0, s15, 0xc000
	ds_read_b128 v[184:187], v150
	ds_read_b128 v[188:191], v150 offset:1024
	ds_read_b128 v[192:195], v150 offset:2048
	ds_read_b128 v[196:199], v150 offset:3072
	ds_read_b128 v[200:203], v150 offset:4096
	ds_read_b128 v[204:207], v150 offset:5120
	ds_read_b128 v[208:211], v150 offset:6144
	ds_read_b128 v[212:215], v150 offset:7168
	global_load_lds_dwordx4 v[216:217], off
	v_lshl_add_u64 v[216:217], s[24:25], 0, v[138:139]
	s_add_i32 m0, s15, 0xe000
	s_nop 0
	global_load_lds_dwordx4 v[216:217], off
	s_sleep 1
	s_waitcnt vmcnt(8)
	s_waitcnt lgkmcnt(0)
	s_barrier
	s_setprio 1
	s_waitcnt lgkmcnt(0)
	v_mfma_f32_16x16x32_bf16 v[124:127], v[152:155], v[184:187], v[124:127]
	v_mfma_f32_16x16x32_bf16 v[120:123], v[160:163], v[184:187], v[120:123]
	v_mfma_f32_16x16x32_bf16 v[116:119], v[152:155], v[192:195], v[116:119]
	v_mfma_f32_16x16x32_bf16 v[112:115], v[160:163], v[192:195], v[112:115]
	v_mfma_f32_16x16x32_bf16 v[100:103], v[152:155], v[200:203], v[100:103]
	v_mfma_f32_16x16x32_bf16 v[96:99], v[160:163], v[200:203], v[96:99]
	v_mfma_f32_16x16x32_bf16 v[84:87], v[152:155], v[208:211], v[84:87]
	v_mfma_f32_16x16x32_bf16 v[80:83], v[160:163], v[208:211], v[80:83]
	v_mfma_f32_16x16x32_bf16 v[124:127], v[156:159], v[188:191], v[124:127]
	v_mfma_f32_16x16x32_bf16 v[120:123], v[164:167], v[188:191], v[120:123]
	v_mfma_f32_16x16x32_bf16 v[116:119], v[156:159], v[196:199], v[116:119]
	v_mfma_f32_16x16x32_bf16 v[112:115], v[164:167], v[196:199], v[112:115]
	v_mfma_f32_16x16x32_bf16 v[100:103], v[156:159], v[204:207], v[100:103]
	v_mfma_f32_16x16x32_bf16 v[96:99], v[164:167], v[204:207], v[96:99]
	v_mfma_f32_16x16x32_bf16 v[84:87], v[156:159], v[212:215], v[84:87]
	v_mfma_f32_16x16x32_bf16 v[80:83], v[164:167], v[212:215], v[80:83]
	s_setprio 0
	s_setprio 1
	v_mfma_f32_16x16x32_bf16 v[108:111], v[168:171], v[184:187], v[108:111]
	v_mfma_f32_16x16x32_bf16 v[104:107], v[176:179], v[184:187], v[104:107]
	v_mfma_f32_16x16x32_bf16 v[92:95], v[168:171], v[192:195], v[92:95]
	v_mfma_f32_16x16x32_bf16 v[88:91], v[176:179], v[192:195], v[88:91]
	v_mfma_f32_16x16x32_bf16 v[76:79], v[168:171], v[200:203], v[76:79]
	v_mfma_f32_16x16x32_bf16 v[72:75], v[176:179], v[200:203], v[72:75]
	v_mfma_f32_16x16x32_bf16 v[68:71], v[168:171], v[208:211], v[68:71]
	v_mfma_f32_16x16x32_bf16 v[64:67], v[176:179], v[208:211], v[64:67]
	v_mfma_f32_16x16x32_bf16 v[108:111], v[172:175], v[188:191], v[108:111]
	v_mfma_f32_16x16x32_bf16 v[104:107], v[180:183], v[188:191], v[104:107]
	v_mfma_f32_16x16x32_bf16 v[92:95], v[172:175], v[196:199], v[92:95]
	v_mfma_f32_16x16x32_bf16 v[88:91], v[180:183], v[196:199], v[88:91]
	v_mfma_f32_16x16x32_bf16 v[76:79], v[172:175], v[204:207], v[76:79]
	v_mfma_f32_16x16x32_bf16 v[72:75], v[180:183], v[204:207], v[72:75]
	v_mfma_f32_16x16x32_bf16 v[68:71], v[172:175], v[212:215], v[68:71]
	v_mfma_f32_16x16x32_bf16 v[64:67], v[180:183], v[212:215], v[64:67]
	s_setprio 0
	s_barrier
	s_add_i32 s52, s43, s36
	v_lshl_add_u64 v[216:217], s[26:27], 0, v[132:133]
	s_mov_b32 m0, s52
	ds_read_b128 v[184:187], v150 offset:16384
	ds_read_b128 v[188:191], v150 offset:17408
	ds_read_b128 v[192:195], v150 offset:18432
	ds_read_b128 v[196:199], v150 offset:19456
	ds_read_b128 v[200:203], v150 offset:20480
	ds_read_b128 v[204:207], v150 offset:21504
	ds_read_b128 v[208:211], v150 offset:22528
	ds_read_b128 v[212:215], v150 offset:23552
	global_load_lds_dwordx4 v[216:217], off
	s_add_i32 m0, s52, 0x2000
	s_add_u32 s52, s26, 0x80000
	v_lshl_add_u64 v[218:219], s[26:27], 0, v[128:129]
	s_addc_u32 s53, s27, 0
	s_add_i32 s54, s44, s36
	global_load_lds_dwordx4 v[218:219], off
	v_lshl_add_u64 v[222:223], s[52:53], 0, v[132:133]
	s_mov_b32 m0, s54
	v_lshl_add_u64 v[224:225], s[28:29], 0, v[130:131]
	global_load_lds_dwordx4 v[222:223], off
	v_lshl_add_u64 v[222:223], s[52:53], 0, v[128:129]
	s_add_i32 m0, s54, 0x2000
	s_nop 0
	global_load_lds_dwordx4 v[222:223], off
	v_lshl_add_u64 v[222:223], s[28:29], 0, v[134:135]
	s_mov_b32 m0, s15
	s_nop 0
	global_load_lds_dwordx4 v[222:223], off
	s_mov_b32 m0, s37
	s_nop 0
	global_load_lds_dwordx4 v[224:225], off
	s_sleep 1
	s_waitcnt vmcnt(8)
	s_waitcnt lgkmcnt(0)
	s_barrier
; #define PG8_STAGE(bufoff, gbase, voff) do { _Pragma("unroll") for (int _i = 0; _i < 2; ++_i) \
;         __builtin_amdgcn_global_load_lds((const unsigned*)((const char*)(gbase) + (voff)[_i]), (PG8_LAS unsigned*)(lds + (bufoff) + ldsw + _i * 8192), 16, 0, 0); } while (0)
; #define PG8_LDA(dst, b, h) do { _Pragma("unroll") for (int m = 0; m < 4; ++m) _Pragma("unroll") for (int k = 0; k < 2; ++k) dst[m][k] = *(const PG8_LAS bf16x8*)(lds + PG8_SA(b, h) + aoff + m * 2048 + k * 1024); } while (0)
; #define PG8_LDB(dst, b, h) do { _Pragma("unroll") for (int n = 0; n < 2; ++n) _Pragma("unroll") for (int k = 0; k < 2; ++k) dst[n][k] = *(const PG8_LAS bf16x8*)(lds + PG8_SB(b, h) + boff + n * 2048 + k * 1024); } while (0)
; #define PG8_MMA(ai, bj, At, Bt) do { __builtin_amdgcn_s_setprio(1); _Pragma("unroll") for (int m = 0; m < 4; ++m) _Pragma("unroll") for (int n = 0; n < 2; ++n) _Pragma("unroll") for (int k = 0; k < 2; ++k) \
;         acc[ai][bj][m][n] = __builtin_amdgcn_mfma_f32_16x16x32_bf16(Bt[n][k], At[m][k], acc[ai][bj][m][n], 0, 0, 0); __builtin_amdgcn_s_setprio(0); } while (0)
; #define PG8_WAIT_V(n) asm volatile("s_waitcnt vmcnt(" #n ")" ::: "memory")
; #define PG8_WAIT_L(n) asm volatile("s_waitcnt lgkmcnt(" #n ")" ::: "memory")
; #define PG8_BAR __builtin_amdgcn_s_barrier()
; #define PG8_SCHED __builtin_amdgcn_sched_barrier(0)
; template <class Epi, class Sched, bool ALIGN_EPI = false, bool SP2 = false>
; __device__ __forceinline__ void gemm_phase(PG8_LAS unsigned char* lds, const Gemm g, const Sched& S, const Epi& E) {
;     ...
;             PG8_WAIT_V(8); PG8_WAIT_L(0); PG8_BAR; PG8_MMA(1, 0, At, B0); PG8_MMA(1, 1, At, B1); PG8_BAR; PG8_SCHED;
;             PG8_LDB(B0, 1, 0); PG8_LDB(B1, 1, 1); PG8_SCHED; PG8_LDA(At, 1, 0); PG8_STAGE(PG8_SA(0, 1), a2 + hstep, voffA);
;             PG8_WAIT_V(8); PG8_WAIT_L(0); PG8_BAR; PG8_MMA(0, 0, At, B0); PG8_MMA(0, 1, At, B1); PG8_BAR; PG8_SCHED;
	s_setprio 1
	s_waitcnt lgkmcnt(0)
	v_mfma_f32_16x16x32_bf16 v[60:63], v[152:155], v[184:187], v[60:63]
	v_mfma_f32_16x16x32_bf16 v[56:59], v[160:163], v[184:187], v[56:59]
	v_mfma_f32_16x16x32_bf16 v[52:55], v[152:155], v[192:195], v[52:55]
	v_mfma_f32_16x16x32_bf16 v[48:51], v[160:163], v[192:195], v[48:51]
	v_mfma_f32_16x16x32_bf16 v[36:39], v[152:155], v[200:203], v[36:39]
	v_mfma_f32_16x16x32_bf16 v[32:35], v[160:163], v[200:203], v[32:35]
	v_mfma_f32_16x16x32_bf16 v[20:23], v[152:155], v[208:211], v[20:23]
	v_mfma_f32_16x16x32_bf16 v[16:19], v[160:163], v[208:211], v[16:19]
	v_mfma_f32_16x16x32_bf16 v[60:63], v[156:159], v[188:191], v[60:63]
	v_mfma_f32_16x16x32_bf16 v[56:59], v[164:167], v[188:191], v[56:59]
	v_mfma_f32_16x16x32_bf16 v[52:55], v[156:159], v[196:199], v[52:55]
	v_mfma_f32_16x16x32_bf16 v[48:51], v[164:167], v[196:199], v[48:51]
	v_mfma_f32_16x16x32_bf16 v[36:39], v[156:159], v[204:207], v[36:39]
	v_mfma_f32_16x16x32_bf16 v[32:35], v[164:167], v[204:207], v[32:35]
	v_mfma_f32_16x16x32_bf16 v[20:23], v[156:159], v[212:215], v[20:23]
	v_mfma_f32_16x16x32_bf16 v[16:19], v[164:167], v[212:215], v[16:19]
	s_setprio 0
	s_setprio 1
	v_mfma_f32_16x16x32_bf16 v[44:47], v[168:171], v[184:187], v[44:47]
	v_mfma_f32_16x16x32_bf16 v[40:43], v[176:179], v[184:187], v[40:43]
	v_mfma_f32_16x16x32_bf16 v[28:31], v[168:171], v[192:195], v[28:31]
	v_mfma_f32_16x16x32_bf16 v[24:27], v[176:179], v[192:195], v[24:27]
	v_mfma_f32_16x16x32_bf16 v[12:15], v[168:171], v[200:203], v[12:15]
	v_mfma_f32_16x16x32_bf16 v[8:11], v[176:179], v[200:203], v[8:11]
	v_mfma_f32_16x16x32_bf16 v[4:7], v[168:171], v[208:211], v[4:7]
	v_mfma_f32_16x16x32_bf16 v[0:3], v[176:179], v[208:211], v[0:3]
	v_mfma_f32_16x16x32_bf16 v[44:47], v[172:175], v[188:191], v[44:47]
	v_mfma_f32_16x16x32_bf16 v[40:43], v[180:183], v[188:191], v[40:43]
	v_mfma_f32_16x16x32_bf16 v[28:31], v[172:175], v[196:199], v[28:31]
	v_mfma_f32_16x16x32_bf16 v[24:27], v[180:183], v[196:199], v[24:27]
	v_mfma_f32_16x16x32_bf16 v[12:15], v[172:175], v[204:207], v[12:15]
	v_mfma_f32_16x16x32_bf16 v[8:11], v[180:183], v[204:207], v[8:11]
	v_mfma_f32_16x16x32_bf16 v[4:7], v[172:175], v[212:215], v[4:7]
	v_mfma_f32_16x16x32_bf16 v[0:3], v[180:183], v[212:215], v[0:3]
	s_setprio 0
	s_barrier
	s_add_i32 s52, 0, 0x18000
	v_add_u32_e32 v151, s52, v146
	s_add_i32 s53, 0, 0x1c000
	ds_read_b128 v[152:155], v151
	ds_read_b128 v[156:159], v151 offset:1024
	ds_read_b128 v[160:163], v151 offset:2048
	ds_read_b128 v[164:167], v151 offset:3072
	v_add_u32_e32 v151, s53, v146
	ds_read_b128 v[168:171], v151
	ds_read_b128 v[172:175], v151 offset:1024
	ds_read_b128 v[176:179], v151 offset:2048
	ds_read_b128 v[180:183], v151 offset:3072
	s_add_u32 s28, s28, 0x80000
	s_addc_u32 s29, s29, 0
	s_mov_b32 m0, s38
	v_lshl_add_u64 v[226:227], s[28:29], 0, v[134:135]
	ds_read_b128 v[184:187], v150 offset:32768
	ds_read_b128 v[188:191], v150 offset:33792
	ds_read_b128 v[192:195], v150 offset:34816
	ds_read_b128 v[196:199], v150 offset:35840
	ds_read_b128 v[200:203], v150 offset:36864
	ds_read_b128 v[204:207], v150 offset:37888
	ds_read_b128 v[208:211], v150 offset:38912
	ds_read_b128 v[212:215], v150 offset:39936
	global_load_lds_dwordx4 v[226:227], off
	v_lshl_add_u64 v[226:227], s[28:29], 0, v[130:131]
	s_mov_b32 m0, s39
	s_nop 0
	global_load_lds_dwordx4 v[226:227], off
	s_sleep 1
	s_waitcnt vmcnt(8)
	s_waitcnt lgkmcnt(0)
	s_barrier
	s_setprio 1
	s_waitcnt lgkmcnt(0)
	v_mfma_f32_16x16x32_bf16 v[124:127], v[152:155], v[184:187], v[124:127]
	v_mfma_f32_16x16x32_bf16 v[120:123], v[160:163], v[184:187], v[120:123]
	v_mfma_f32_16x16x32_bf16 v[116:119], v[152:155], v[192:195], v[116:119]
	v_mfma_f32_16x16x32_bf16 v[112:115], v[160:163], v[192:195], v[112:115]
	v_mfma_f32_16x16x32_bf16 v[100:103], v[152:155], v[200:203], v[100:103]
	v_mfma_f32_16x16x32_bf16 v[96:99], v[160:163], v[200:203], v[96:99]
	v_mfma_f32_16x16x32_bf16 v[84:87], v[152:155], v[208:211], v[84:87]
	v_mfma_f32_16x16x32_bf16 v[80:83], v[160:163], v[208:211], v[80:83]
	v_mfma_f32_16x16x32_bf16 v[124:127], v[156:159], v[188:191], v[124:127]
	v_mfma_f32_16x16x32_bf16 v[120:123], v[164:167], v[188:191], v[120:123]
	v_mfma_f32_16x16x32_bf16 v[116:119], v[156:159], v[196:199], v[116:119]
	v_mfma_f32_16x16x32_bf16 v[112:115], v[164:167], v[196:199], v[112:115]
	v_mfma_f32_16x16x32_bf16 v[100:103], v[156:159], v[204:207], v[100:103]
	v_mfma_f32_16x16x32_bf16 v[96:99], v[164:167], v[204:207], v[96:99]
	v_mfma_f32_16x16x32_bf16 v[84:87], v[156:159], v[212:215], v[84:87]
	v_mfma_f32_16x16x32_bf16 v[80:83], v[164:167], v[212:215], v[80:83]
	s_setprio 0
	s_setprio 1
	v_mfma_f32_16x16x32_bf16 v[108:111], v[168:171], v[184:187], v[108:111]
	v_mfma_f32_16x16x32_bf16 v[104:107], v[176:179], v[184:187], v[104:107]
	v_mfma_f32_16x16x32_bf16 v[92:95], v[168:171], v[192:195], v[92:95]
	v_mfma_f32_16x16x32_bf16 v[88:91], v[176:179], v[192:195], v[88:91]
	v_mfma_f32_16x16x32_bf16 v[76:79], v[168:171], v[200:203], v[76:79]
	v_mfma_f32_16x16x32_bf16 v[72:75], v[176:179], v[200:203], v[72:75]
	v_mfma_f32_16x16x32_bf16 v[68:71], v[168:171], v[208:211], v[68:71]
	v_mfma_f32_16x16x32_bf16 v[64:67], v[176:179], v[208:211], v[64:67]
	v_mfma_f32_16x16x32_bf16 v[108:111], v[172:175], v[188:191], v[108:111]
	v_mfma_f32_16x16x32_bf16 v[104:107], v[180:183], v[188:191], v[104:107]
	v_mfma_f32_16x16x32_bf16 v[92:95], v[172:175], v[196:199], v[92:95]
	v_mfma_f32_16x16x32_bf16 v[88:91], v[180:183], v[196:199], v[88:91]
	v_mfma_f32_16x16x32_bf16 v[76:79], v[172:175], v[204:207], v[76:79]
	v_mfma_f32_16x16x32_bf16 v[72:75], v[180:183], v[204:207], v[72:75]
	v_mfma_f32_16x16x32_bf16 v[68:71], v[172:175], v[212:215], v[68:71]
	v_mfma_f32_16x16x32_bf16 v[64:67], v[180:183], v[212:215], v[64:67]
	s_setprio 0
	s_barrier
; #define PG8_STAGE(bufoff, gbase, voff) do { _Pragma("unroll") for (int _i = 0; _i < 2; ++_i) \
;         __builtin_amdgcn_global_load_lds((const unsigned*)((const char*)(gbase) + (voff)[_i]), (PG8_LAS unsigned*)(lds + (bufoff) + ldsw + _i * 8192), 16, 0, 0); } while (0)
; #define PG8_LDA(dst, b, h) do { _Pragma("unroll") for (int m = 0; m < 4; ++m) _Pragma("unroll") for (int k = 0; k < 2; ++k) dst[m][k] = *(const PG8_LAS bf16x8*)(lds + PG8_SA(b, h) + aoff + m * 2048 + k * 1024); } while (0)
; #define PG8_MMA(ai, bj, At, Bt) do { __builtin_amdgcn_s_setprio(1); _Pragma("unroll") for (int m = 0; m < 4; ++m) _Pragma("unroll") for (int n = 0; n < 2; ++n) _Pragma("unroll") for (int k = 0; k < 2; ++k) \
;         acc[ai][bj][m][n] = __builtin_amdgcn_mfma_f32_16x16x32_bf16(Bt[n][k], At[m][k], acc[ai][bj][m][n], 0, 0, 0); __builtin_amdgcn_s_setprio(0); } while (0)
; #define PG8_WAIT_V(n) asm volatile("s_waitcnt vmcnt(" #n ")" ::: "memory")
; #define PG8_WAIT_L(n) asm volatile("s_waitcnt lgkmcnt(" #n ")" ::: "memory")
; #define PG8_BAR __builtin_amdgcn_s_barrier()
; #define PG8_SCHED __builtin_amdgcn_sched_barrier(0)
; template <class Epi, class Sched, bool ALIGN_EPI = false, bool SP2 = false>
; __device__ __forceinline__ void gemm_phase(PG8_LAS unsigned char* lds, const Gemm g, const Sched& S, const Epi& E) {
;     ...
;             PG8_LDA(At, 1, 1); PG8_STAGE(PG8_SB(1, 0), b3, voffB); PG8_STAGE(PG8_SB(1, 1), b3 + hstep, voffB); PG8_STAGE(PG8_SA(1, 0), a3, voffA);
;             PG8_WAIT_V(8); PG8_WAIT_L(0); PG8_BAR; PG8_MMA(1, 0, At, B0); PG8_MMA(1, 1, At, B1); PG8_BAR; PG8_SCHED;
;     ...
;         if constexpr (ALIGN_EPI) { if (wr == 0) PG8_BAR; }
	s_add_i32 s28, s52, s36
	v_lshl_add_u64 v[216:217], v[216:217], 0, s[10:11]
	s_mov_b32 m0, s28
	ds_read_b128 v[184:187], v150 offset:49152
	ds_read_b128 v[188:191], v150 offset:50176
	ds_read_b128 v[192:195], v150 offset:51200
	ds_read_b128 v[196:199], v150 offset:52224
	ds_read_b128 v[200:203], v150 offset:53248
	ds_read_b128 v[204:207], v150 offset:54272
	ds_read_b128 v[208:211], v150 offset:55296
	ds_read_b128 v[212:215], v150 offset:56320
	global_load_lds_dwordx4 v[216:217], off
	s_add_i32 m0, s28, 0x2000
	s_add_u32 s26, s26, 0x80080
	v_lshl_add_u64 v[216:217], v[218:219], 0, s[10:11]
	s_addc_u32 s27, s27, 0
	s_add_i32 s28, s53, s36
	global_load_lds_dwordx4 v[216:217], off
	v_lshl_add_u64 v[216:217], s[26:27], 0, v[132:133]
	s_mov_b32 m0, s28
	s_nop 0
	global_load_lds_dwordx4 v[216:217], off
	v_lshl_add_u64 v[216:217], s[26:27], 0, v[128:129]
	s_add_i32 m0, s28, 0x2000
	s_nop 0
	global_load_lds_dwordx4 v[216:217], off
	v_lshl_add_u64 v[216:217], v[222:223], 0, s[10:11]
	s_mov_b32 m0, s41
	s_nop 0
	global_load_lds_dwordx4 v[216:217], off
	v_lshl_add_u64 v[216:217], v[224:225], 0, s[10:11]
	s_mov_b32 m0, s42
	s_nop 0
	global_load_lds_dwordx4 v[216:217], off
	s_sleep 1
	s_waitcnt vmcnt(8)
	s_waitcnt lgkmcnt(0)
	s_barrier
	s_setprio 1
	s_waitcnt lgkmcnt(0)
	v_mfma_f32_16x16x32_bf16 v[60:63], v[152:155], v[184:187], v[60:63]
	v_mfma_f32_16x16x32_bf16 v[56:59], v[160:163], v[184:187], v[56:59]
	v_mfma_f32_16x16x32_bf16 v[52:55], v[152:155], v[192:195], v[52:55]
	v_mfma_f32_16x16x32_bf16 v[48:51], v[160:163], v[192:195], v[48:51]
	v_mfma_f32_16x16x32_bf16 v[36:39], v[152:155], v[200:203], v[36:39]
	v_mfma_f32_16x16x32_bf16 v[32:35], v[160:163], v[200:203], v[32:35]
	v_mfma_f32_16x16x32_bf16 v[20:23], v[152:155], v[208:211], v[20:23]
	v_mfma_f32_16x16x32_bf16 v[16:19], v[160:163], v[208:211], v[16:19]
	v_mfma_f32_16x16x32_bf16 v[60:63], v[156:159], v[188:191], v[60:63]
	v_mfma_f32_16x16x32_bf16 v[56:59], v[164:167], v[188:191], v[56:59]
	v_mfma_f32_16x16x32_bf16 v[52:55], v[156:159], v[196:199], v[52:55]
	v_mfma_f32_16x16x32_bf16 v[48:51], v[164:167], v[196:199], v[48:51]
	v_mfma_f32_16x16x32_bf16 v[36:39], v[156:159], v[204:207], v[36:39]
	v_mfma_f32_16x16x32_bf16 v[32:35], v[164:167], v[204:207], v[32:35]
	v_mfma_f32_16x16x32_bf16 v[20:23], v[156:159], v[212:215], v[20:23]
	v_mfma_f32_16x16x32_bf16 v[16:19], v[164:167], v[212:215], v[16:19]
	s_setprio 0
	s_setprio 1
	v_mfma_f32_16x16x32_bf16 v[44:47], v[168:171], v[184:187], v[44:47]
	v_mfma_f32_16x16x32_bf16 v[40:43], v[176:179], v[184:187], v[40:43]
	v_mfma_f32_16x16x32_bf16 v[28:31], v[168:171], v[192:195], v[28:31]
	v_mfma_f32_16x16x32_bf16 v[24:27], v[176:179], v[192:195], v[24:27]
	v_mfma_f32_16x16x32_bf16 v[12:15], v[168:171], v[200:203], v[12:15]
	v_mfma_f32_16x16x32_bf16 v[8:11], v[176:179], v[200:203], v[8:11]
	v_mfma_f32_16x16x32_bf16 v[4:7], v[168:171], v[208:211], v[4:7]
	v_mfma_f32_16x16x32_bf16 v[0:3], v[176:179], v[208:211], v[0:3]
	v_mfma_f32_16x16x32_bf16 v[44:47], v[172:175], v[188:191], v[44:47]
	v_mfma_f32_16x16x32_bf16 v[40:43], v[180:183], v[188:191], v[40:43]
	v_mfma_f32_16x16x32_bf16 v[28:31], v[172:175], v[196:199], v[28:31]
	v_mfma_f32_16x16x32_bf16 v[24:27], v[180:183], v[196:199], v[24:27]
	v_mfma_f32_16x16x32_bf16 v[12:15], v[172:175], v[204:207], v[12:15]
	v_mfma_f32_16x16x32_bf16 v[8:11], v[180:183], v[204:207], v[8:11]
	v_mfma_f32_16x16x32_bf16 v[4:7], v[172:175], v[212:215], v[4:7]
	v_mfma_f32_16x16x32_bf16 v[0:3], v[180:183], v[212:215], v[0:3]
	s_setprio 0
	s_barrier
	s_add_i32 s51, s51, 2
	s_add_u32 s24, s24, 0x100
	s_addc_u32 s25, s25, 0
	s_add_u32 s49, s49, 0x100
	s_addc_u32 s50, s50, 0
	s_cmp_gt_u32 s51, 29
	s_cbranch_scc0 .LBB0_220
	s_and_b64 vcc, exec, s[12:13]
	s_cbranch_vccz .LBB0_223
	s_barrier

; #define PG8_STAGE(bufoff, gbase, voff) do { _Pragma("unroll") for (int _i = 0; _i < 2; ++_i) \
;         __builtin_amdgcn_global_load_lds((const unsigned*)((const char*)(gbase) + (voff)[_i]), (PG8_LAS unsigned*)(lds + (bufoff) + ldsw + _i * 8192), 16, 0, 0); } while (0)
; #define PG8_LDA(dst, b, h) do { _Pragma("unroll") for (int m = 0; m < 4; ++m) _Pragma("unroll") for (int k = 0; k < 2; ++k) dst[m][k] = *(const PG8_LAS bf16x8*)(lds + PG8_SA(b, h) + aoff + m * 2048 + k * 1024); } while (0)
; #define PG8_LDB(dst, b, h) do { _Pragma("unroll") for (int n = 0; n < 2; ++n) _Pragma("unroll") for (int k = 0; k < 2; ++k) dst[n][k] = *(const PG8_LAS bf16x8*)(lds + PG8_SB(b, h) + boff + n * 2048 + k * 1024); } while (0)
; #define PG8_MMA(ai, bj, At, Bt) do { __builtin_amdgcn_s_setprio(1); _Pragma("unroll") for (int m = 0; m < 4; ++m) _Pragma("unroll") for (int n = 0; n < 2; ++n) _Pragma("unroll") for (int k = 0; k < 2; ++k) \
;         acc[ai][bj][m][n] = __builtin_amdgcn_mfma_f32_16x16x32_bf16(Bt[n][k], At[m][k], acc[ai][bj][m][n], 0, 0, 0); __builtin_amdgcn_s_setprio(0); } while (0)
; #define PG8_WAIT_V(n) asm volatile("s_waitcnt vmcnt(" #n ")" ::: "memory")
; #define PG8_WAIT_L(n) asm volatile("s_waitcnt lgkmcnt(" #n ")" ::: "memory")
; template <class Epi, class Sched, bool ALIGN_EPI = false, bool SP2 = false>
; __device__ __forceinline__ void gemm_phase(PG8_LAS unsigned char* lds, const Gemm g, const Sched& S, const Epi& E) {
;     ...
;             const bool last = (t == nt - 2);
;             const char* a1 = cA + (size_t)(t + 1) * kstep;
;             const char* a2 = last ? nA : cA + (size_t)(t + 2) * kstep; const char* b2 = last ? nB : cB + (size_t)(t + 2) * kstep;
;             const char* a3 = a2 + kstep; const char* b3 = b2 + kstep;
;             if (last && has_next) S.a_ready(nxt);
;             if constexpr (SP2) {
;             PG8_LDB(B0, 0, 0); PG8_LDB(B1, 0, 1); PG8_SCHED; PG8_LDA(At, 0, 0); PG8_STAGE(PG8_SA(1, 1), a1 + hstep, voffA);
;             PG8_WAIT_V(8); PG8_WAIT_L(0); PG8_BAR; PG8_MMA(0, 0, At, B0); PG8_MMA(0, 1, At, B1); PG8_BAR; PG8_SCHED;
;             PG8_LDA(At, 0, 1); PG8_STAGE(PG8_SB(0, 0), b2, voffB); PG8_STAGE(PG8_SB(0, 1), b2 + hstep, voffB); PG8_STAGE(PG8_SA(0, 0), a2, voffA);
;             PG8_WAIT_V(8); PG8_WAIT_L(0); PG8_BAR; PG8_MMA(1, 0, At, B0); PG8_MMA(1, 1, At, B1); PG8_BAR; PG8_SCHED;
.LBB0_502:
	ds_read_b128 v[108:111], v223
	ds_read_b128 v[116:119], v223 offset:1024
	ds_read_b128 v[120:123], v223 offset:2048
	ds_read_b128 v[124:127], v223 offset:3072
	ds_read_b128 v[144:147], v224
	ds_read_b128 v[148:151], v224 offset:1024
	ds_read_b128 v[152:155], v224 offset:2048
	ds_read_b128 v[156:159], v224 offset:3072
	s_add_u32 s44, s40, 0xfff80080
	s_addc_u32 s45, s41, -1
	s_cmp_eq_u32 s67, 28
	s_cselect_b32 s47, s65, s45
	s_cselect_b32 s46, s66, s44
	s_cselect_b32 s45, s21, s43
	s_cselect_b32 s44, s20, s42
	s_mov_b32 m0, s58
	v_lshl_add_u64 v[216:217], s[40:41], 0, v[180:181]
	ds_read_b128 v[184:187], v225
	ds_read_b128 v[188:191], v225 offset:1024
	ds_read_b128 v[192:195], v225 offset:2048
	ds_read_b128 v[196:199], v225 offset:3072
	ds_read_b128 v[200:203], v225 offset:4096
	ds_read_b128 v[204:207], v225 offset:5120
	ds_read_b128 v[208:211], v225 offset:6144
	ds_read_b128 v[212:215], v225 offset:7168
	global_load_lds_dwordx4 v[216:217], off
	v_lshl_add_u64 v[216:217], s[40:41], 0, v[182:183]
	s_mov_b32 m0, s59
	s_nop 0
	global_load_lds_dwordx4 v[216:217], off
	s_sleep 1
	s_waitcnt vmcnt(8)
	s_waitcnt lgkmcnt(0)
	s_barrier
	s_setprio 1
	s_waitcnt lgkmcnt(0)
	v_mfma_f32_16x16x32_bf16 v[140:143], v[108:111], v[184:187], v[140:143]
	v_mfma_f32_16x16x32_bf16 v[136:139], v[120:123], v[184:187], v[136:139]
	v_mfma_f32_16x16x32_bf16 v[112:115], v[108:111], v[192:195], v[112:115]
	v_mfma_f32_16x16x32_bf16 v[104:107], v[120:123], v[192:195], v[104:107]
	v_mfma_f32_16x16x32_bf16 v[92:95], v[108:111], v[200:203], v[92:95]
	v_mfma_f32_16x16x32_bf16 v[88:91], v[120:123], v[200:203], v[88:91]
	v_mfma_f32_16x16x32_bf16 v[76:79], v[108:111], v[208:211], v[76:79]
	v_mfma_f32_16x16x32_bf16 v[72:75], v[120:123], v[208:211], v[72:75]
	v_mfma_f32_16x16x32_bf16 v[140:143], v[116:119], v[188:191], v[140:143]
	v_mfma_f32_16x16x32_bf16 v[136:139], v[124:127], v[188:191], v[136:139]
	v_mfma_f32_16x16x32_bf16 v[112:115], v[116:119], v[196:199], v[112:115]
	v_mfma_f32_16x16x32_bf16 v[104:107], v[124:127], v[196:199], v[104:107]
	v_mfma_f32_16x16x32_bf16 v[92:95], v[116:119], v[204:207], v[92:95]
	v_mfma_f32_16x16x32_bf16 v[88:91], v[124:127], v[204:207], v[88:91]
	v_mfma_f32_16x16x32_bf16 v[76:79], v[116:119], v[212:215], v[76:79]
	v_mfma_f32_16x16x32_bf16 v[72:75], v[124:127], v[212:215], v[72:75]
	s_setprio 0
	s_setprio 1
	v_mfma_f32_16x16x32_bf16 v[132:135], v[144:147], v[184:187], v[132:135]
	v_mfma_f32_16x16x32_bf16 v[128:131], v[152:155], v[184:187], v[128:131]
	v_mfma_f32_16x16x32_bf16 v[100:103], v[144:147], v[192:195], v[100:103]
	v_mfma_f32_16x16x32_bf16 v[96:99], v[152:155], v[192:195], v[96:99]
	v_mfma_f32_16x16x32_bf16 v[84:87], v[144:147], v[200:203], v[84:87]
	v_mfma_f32_16x16x32_bf16 v[80:83], v[152:155], v[200:203], v[80:83]
	v_mfma_f32_16x16x32_bf16 v[68:71], v[144:147], v[208:211], v[68:71]
	v_mfma_f32_16x16x32_bf16 v[64:67], v[152:155], v[208:211], v[64:67]
	v_mfma_f32_16x16x32_bf16 v[132:135], v[148:151], v[188:191], v[132:135]
	v_mfma_f32_16x16x32_bf16 v[128:131], v[156:159], v[188:191], v[128:131]
	v_mfma_f32_16x16x32_bf16 v[100:103], v[148:151], v[196:199], v[100:103]
	v_mfma_f32_16x16x32_bf16 v[96:99], v[156:159], v[196:199], v[96:99]
	v_mfma_f32_16x16x32_bf16 v[84:87], v[148:151], v[204:207], v[84:87]
	v_mfma_f32_16x16x32_bf16 v[80:83], v[156:159], v[204:207], v[80:83]
	v_mfma_f32_16x16x32_bf16 v[68:71], v[148:151], v[212:215], v[68:71]
	v_mfma_f32_16x16x32_bf16 v[64:67], v[156:159], v[212:215], v[64:67]
	s_setprio 0
	s_barrier
	s_mov_b32 m0, s60
	v_lshl_add_u64 v[216:217], s[44:45], 0, v[162:163]
	s_add_u32 s68, s44, 0x80000
	ds_read_b128 v[184:187], v225 offset:16384
	ds_read_b128 v[188:191], v225 offset:17408
	ds_read_b128 v[192:195], v225 offset:18432
	ds_read_b128 v[196:199], v225 offset:19456
	ds_read_b128 v[200:203], v225 offset:20480
	ds_read_b128 v[204:207], v225 offset:21504
	ds_read_b128 v[208:211], v225 offset:22528
	ds_read_b128 v[212:215], v225 offset:23552
	global_load_lds_dwordx4 v[216:217], off
	v_lshl_add_u64 v[218:219], s[44:45], 0, v[160:161]
	s_mov_b32 m0, s61
	s_addc_u32 s69, s45, 0
	global_load_lds_dwordx4 v[218:219], off
	v_lshl_add_u64 v[228:229], s[68:69], 0, v[162:163]
	s_mov_b32 m0, s62
	v_lshl_add_u64 v[230:231], s[46:47], 0, v[160:161]
	global_load_lds_dwordx4 v[228:229], off
	v_lshl_add_u64 v[228:229], s[68:69], 0, v[160:161]
	s_add_i32 m0, s62, 0x2000
	s_nop 0
	global_load_lds_dwordx4 v[228:229], off
	v_lshl_add_u64 v[228:229], s[46:47], 0, v[162:163]
	s_mov_b32 m0, s19
	s_nop 0
	global_load_lds_dwordx4 v[228:229], off
	s_mov_b32 m0, s49
	s_nop 0
	global_load_lds_dwordx4 v[230:231], off
	s_sleep 1
	s_waitcnt vmcnt(8)
	s_waitcnt lgkmcnt(0)
	s_barrier
; #define PG8_STAGE(bufoff, gbase, voff) do { _Pragma("unroll") for (int _i = 0; _i < 2; ++_i) \
;         __builtin_amdgcn_global_load_lds((const unsigned*)((const char*)(gbase) + (voff)[_i]), (PG8_LAS unsigned*)(lds + (bufoff) + ldsw + _i * 8192), 16, 0, 0); } while (0)
; #define PG8_LDA(dst, b, h) do { _Pragma("unroll") for (int m = 0; m < 4; ++m) _Pragma("unroll") for (int k = 0; k < 2; ++k) dst[m][k] = *(const PG8_LAS bf16x8*)(lds + PG8_SA(b, h) + aoff + m * 2048 + k * 1024); } while (0)
; #define PG8_LDB(dst, b, h) do { _Pragma("unroll") for (int n = 0; n < 2; ++n) _Pragma("unroll") for (int k = 0; k < 2; ++k) dst[n][k] = *(const PG8_LAS bf16x8*)(lds + PG8_SB(b, h) + boff + n * 2048 + k * 1024); } while (0)
; #define PG8_MMA(ai, bj, At, Bt) do { __builtin_amdgcn_s_setprio(1); _Pragma("unroll") for (int m = 0; m < 4; ++m) _Pragma("unroll") for (int n = 0; n < 2; ++n) _Pragma("unroll") for (int k = 0; k < 2; ++k) \
;         acc[ai][bj][m][n] = __builtin_amdgcn_mfma_f32_16x16x32_bf16(Bt[n][k], At[m][k], acc[ai][bj][m][n], 0, 0, 0); __builtin_amdgcn_s_setprio(0); } while (0)
; #define PG8_WAIT_V(n) asm volatile("s_waitcnt vmcnt(" #n ")" ::: "memory")
; #define PG8_WAIT_L(n) asm volatile("s_waitcnt lgkmcnt(" #n ")" ::: "memory")
; #define PG8_BAR __builtin_amdgcn_s_barrier()
; #define PG8_SCHED __builtin_amdgcn_sched_barrier(0)
; template <class Epi, class Sched, bool ALIGN_EPI = false, bool SP2 = false>
; __device__ __forceinline__ void gemm_phase(PG8_LAS unsigned char* lds, const Gemm g, const Sched& S, const Epi& E) {
;     ...
;             PG8_WAIT_V(8); PG8_WAIT_L(0); PG8_BAR; PG8_MMA(1, 0, At, B0); PG8_MMA(1, 1, At, B1); PG8_BAR; PG8_SCHED;
;             PG8_LDB(B0, 1, 0); PG8_LDB(B1, 1, 1); PG8_SCHED; PG8_LDA(At, 1, 0); PG8_STAGE(PG8_SA(0, 1), a2 + hstep, voffA);
;             PG8_WAIT_V(8); PG8_WAIT_L(0); PG8_BAR; PG8_MMA(0, 0, At, B0); PG8_MMA(0, 1, At, B1); PG8_BAR; PG8_SCHED;
	s_setprio 1
	s_waitcnt lgkmcnt(0)
	v_mfma_f32_16x16x32_bf16 v[60:63], v[108:111], v[184:187], v[60:63]
	v_mfma_f32_16x16x32_bf16 v[56:59], v[120:123], v[184:187], v[56:59]
	v_mfma_f32_16x16x32_bf16 v[44:47], v[108:111], v[192:195], v[44:47]
	v_mfma_f32_16x16x32_bf16 v[40:43], v[120:123], v[192:195], v[40:43]
	v_mfma_f32_16x16x32_bf16 v[28:31], v[108:111], v[200:203], v[28:31]
	v_mfma_f32_16x16x32_bf16 v[24:27], v[120:123], v[200:203], v[24:27]
	v_mfma_f32_16x16x32_bf16 v[12:15], v[108:111], v[208:211], v[12:15]
	v_mfma_f32_16x16x32_bf16 v[8:11], v[120:123], v[208:211], v[8:11]
	v_mfma_f32_16x16x32_bf16 v[60:63], v[116:119], v[188:191], v[60:63]
	v_mfma_f32_16x16x32_bf16 v[56:59], v[124:127], v[188:191], v[56:59]
	v_mfma_f32_16x16x32_bf16 v[44:47], v[116:119], v[196:199], v[44:47]
	v_mfma_f32_16x16x32_bf16 v[40:43], v[124:127], v[196:199], v[40:43]
	v_mfma_f32_16x16x32_bf16 v[28:31], v[116:119], v[204:207], v[28:31]
	v_mfma_f32_16x16x32_bf16 v[24:27], v[124:127], v[204:207], v[24:27]
	v_mfma_f32_16x16x32_bf16 v[12:15], v[116:119], v[212:215], v[12:15]
	v_mfma_f32_16x16x32_bf16 v[8:11], v[124:127], v[212:215], v[8:11]
	s_setprio 0
	s_setprio 1
	v_mfma_f32_16x16x32_bf16 v[52:55], v[144:147], v[184:187], v[52:55]
	v_mfma_f32_16x16x32_bf16 v[48:51], v[152:155], v[184:187], v[48:51]
	v_mfma_f32_16x16x32_bf16 v[36:39], v[144:147], v[192:195], v[36:39]
	v_mfma_f32_16x16x32_bf16 v[32:35], v[152:155], v[192:195], v[32:35]
	v_mfma_f32_16x16x32_bf16 v[20:23], v[144:147], v[200:203], v[20:23]
	v_mfma_f32_16x16x32_bf16 v[16:19], v[152:155], v[200:203], v[16:19]
	v_mfma_f32_16x16x32_bf16 v[4:7], v[144:147], v[208:211], v[4:7]
	v_mfma_f32_16x16x32_bf16 v[0:3], v[152:155], v[208:211], v[0:3]
	v_mfma_f32_16x16x32_bf16 v[52:55], v[148:151], v[188:191], v[52:55]
	v_mfma_f32_16x16x32_bf16 v[48:51], v[156:159], v[188:191], v[48:51]
	v_mfma_f32_16x16x32_bf16 v[36:39], v[148:151], v[196:199], v[36:39]
	v_mfma_f32_16x16x32_bf16 v[32:35], v[156:159], v[196:199], v[32:35]
	v_mfma_f32_16x16x32_bf16 v[20:23], v[148:151], v[204:207], v[20:23]
	v_mfma_f32_16x16x32_bf16 v[16:19], v[156:159], v[204:207], v[16:19]
	v_mfma_f32_16x16x32_bf16 v[4:7], v[148:151], v[212:215], v[4:7]
	v_mfma_f32_16x16x32_bf16 v[0:3], v[156:159], v[212:215], v[0:3]
	s_setprio 0
	s_barrier
	s_add_i32 s68, 0, 0x18000
	s_add_i32 s69, 0, 0x1c000
	v_add_u32_e32 v124, s68, v222
	v_add_u32_e32 v156, s69, v222
	ds_read_b128 v[108:111], v124
	ds_read_b128 v[116:119], v124 offset:1024
	ds_read_b128 v[120:123], v124 offset:2048
	ds_read_b128 v[124:127], v124 offset:3072
	ds_read_b128 v[144:147], v156
	ds_read_b128 v[148:151], v156 offset:1024
	ds_read_b128 v[152:155], v156 offset:2048
	ds_read_b128 v[156:159], v156 offset:3072
	s_add_u32 s46, s46, 0x80000
	s_addc_u32 s47, s47, 0
	s_mov_b32 m0, s50
	v_lshl_add_u64 v[232:233], s[46:47], 0, v[162:163]
	ds_read_b128 v[184:187], v225 offset:32768
	ds_read_b128 v[188:191], v225 offset:33792
	ds_read_b128 v[192:195], v225 offset:34816
	ds_read_b128 v[196:199], v225 offset:35840
	ds_read_b128 v[200:203], v225 offset:36864
	ds_read_b128 v[204:207], v225 offset:37888
	ds_read_b128 v[208:211], v225 offset:38912
	ds_read_b128 v[212:215], v225 offset:39936
	global_load_lds_dwordx4 v[232:233], off
	v_lshl_add_u64 v[232:233], s[46:47], 0, v[160:161]
	s_mov_b32 m0, s51
	s_nop 0
	global_load_lds_dwordx4 v[232:233], off
	s_sleep 1
	s_waitcnt vmcnt(8)
	s_waitcnt lgkmcnt(0)
	s_barrier
	s_setprio 1
	s_waitcnt lgkmcnt(0)
	v_mfma_f32_16x16x32_bf16 v[140:143], v[108:111], v[184:187], v[140:143]
	v_mfma_f32_16x16x32_bf16 v[136:139], v[120:123], v[184:187], v[136:139]
	v_mfma_f32_16x16x32_bf16 v[112:115], v[108:111], v[192:195], v[112:115]
	v_mfma_f32_16x16x32_bf16 v[104:107], v[120:123], v[192:195], v[104:107]
	v_mfma_f32_16x16x32_bf16 v[92:95], v[108:111], v[200:203], v[92:95]
	v_mfma_f32_16x16x32_bf16 v[88:91], v[120:123], v[200:203], v[88:91]
	v_mfma_f32_16x16x32_bf16 v[76:79], v[108:111], v[208:211], v[76:79]
	v_mfma_f32_16x16x32_bf16 v[72:75], v[120:123], v[208:211], v[72:75]
	v_mfma_f32_16x16x32_bf16 v[140:143], v[116:119], v[188:191], v[140:143]
	v_mfma_f32_16x16x32_bf16 v[136:139], v[124:127], v[188:191], v[136:139]
	v_mfma_f32_16x16x32_bf16 v[112:115], v[116:119], v[196:199], v[112:115]
	v_mfma_f32_16x16x32_bf16 v[104:107], v[124:127], v[196:199], v[104:107]
	v_mfma_f32_16x16x32_bf16 v[92:95], v[116:119], v[204:207], v[92:95]
	v_mfma_f32_16x16x32_bf16 v[88:91], v[124:127], v[204:207], v[88:91]
	v_mfma_f32_16x16x32_bf16 v[76:79], v[116:119], v[212:215], v[76:79]
	v_mfma_f32_16x16x32_bf16 v[72:75], v[124:127], v[212:215], v[72:75]
	s_setprio 0
	s_setprio 1
	v_mfma_f32_16x16x32_bf16 v[132:135], v[144:147], v[184:187], v[132:135]
	v_mfma_f32_16x16x32_bf16 v[128:131], v[152:155], v[184:187], v[128:131]
	v_mfma_f32_16x16x32_bf16 v[100:103], v[144:147], v[192:195], v[100:103]
	v_mfma_f32_16x16x32_bf16 v[96:99], v[152:155], v[192:195], v[96:99]
	v_mfma_f32_16x16x32_bf16 v[84:87], v[144:147], v[200:203], v[84:87]
	v_mfma_f32_16x16x32_bf16 v[80:83], v[152:155], v[200:203], v[80:83]
	v_mfma_f32_16x16x32_bf16 v[68:71], v[144:147], v[208:211], v[68:71]
	v_mfma_f32_16x16x32_bf16 v[64:67], v[152:155], v[208:211], v[64:67]
	v_mfma_f32_16x16x32_bf16 v[132:135], v[148:151], v[188:191], v[132:135]
	v_mfma_f32_16x16x32_bf16 v[128:131], v[156:159], v[188:191], v[128:131]
	v_mfma_f32_16x16x32_bf16 v[100:103], v[148:151], v[196:199], v[100:103]
	v_mfma_f32_16x16x32_bf16 v[96:99], v[156:159], v[196:199], v[96:99]
	v_mfma_f32_16x16x32_bf16 v[84:87], v[148:151], v[204:207], v[84:87]
	v_mfma_f32_16x16x32_bf16 v[80:83], v[156:159], v[204:207], v[80:83]
	v_mfma_f32_16x16x32_bf16 v[68:71], v[148:151], v[212:215], v[68:71]
	v_mfma_f32_16x16x32_bf16 v[64:67], v[156:159], v[212:215], v[64:67]
	s_setprio 0
	s_barrier
; #define PG8_STAGE(bufoff, gbase, voff) do { _Pragma("unroll") for (int _i = 0; _i < 2; ++_i) \
;         __builtin_amdgcn_global_load_lds((const unsigned*)((const char*)(gbase) + (voff)[_i]), (PG8_LAS unsigned*)(lds + (bufoff) + ldsw + _i * 8192), 16, 0, 0); } while (0)
; #define PG8_LDA(dst, b, h) do { _Pragma("unroll") for (int m = 0; m < 4; ++m) _Pragma("unroll") for (int k = 0; k < 2; ++k) dst[m][k] = *(const PG8_LAS bf16x8*)(lds + PG8_SA(b, h) + aoff + m * 2048 + k * 1024); } while (0)
; #define PG8_MMA(ai, bj, At, Bt) do { __builtin_amdgcn_s_setprio(1); _Pragma("unroll") for (int m = 0; m < 4; ++m) _Pragma("unroll") for (int n = 0; n < 2; ++n) _Pragma("unroll") for (int k = 0; k < 2; ++k) \
;         acc[ai][bj][m][n] = __builtin_amdgcn_mfma_f32_16x16x32_bf16(Bt[n][k], At[m][k], acc[ai][bj][m][n], 0, 0, 0); __builtin_amdgcn_s_setprio(0); } while (0)
; #define PG8_WAIT_V(n) asm volatile("s_waitcnt vmcnt(" #n ")" ::: "memory")
; #define PG8_WAIT_L(n) asm volatile("s_waitcnt lgkmcnt(" #n ")" ::: "memory")
; #define PG8_BAR __builtin_amdgcn_s_barrier()
; #define PG8_SCHED __builtin_amdgcn_sched_barrier(0)
; template <class Epi, class Sched, bool ALIGN_EPI = false, bool SP2 = false>
; __device__ __forceinline__ void gemm_phase(PG8_LAS unsigned char* lds, const Gemm g, const Sched& S, const Epi& E) {
;     ...
;             PG8_LDA(At, 1, 1); PG8_STAGE(PG8_SB(1, 0), b3, voffB); PG8_STAGE(PG8_SB(1, 1), b3 + hstep, voffB); PG8_STAGE(PG8_SA(1, 0), a3, voffA);
;             PG8_WAIT_V(8); PG8_WAIT_L(0); PG8_BAR; PG8_MMA(1, 0, At, B0); PG8_MMA(1, 1, At, B1); PG8_BAR; PG8_SCHED;
;     ...
;         if constexpr (ALIGN_EPI) { if (wr == 0) PG8_BAR; }
	s_add_i32 s46, s68, s48
	v_lshl_add_u64 v[216:217], v[216:217], 0, s[30:31]
	s_mov_b32 m0, s46
	ds_read_b128 v[184:187], v225 offset:49152
	ds_read_b128 v[188:191], v225 offset:50176
	ds_read_b128 v[192:195], v225 offset:51200
	ds_read_b128 v[196:199], v225 offset:52224
	ds_read_b128 v[200:203], v225 offset:53248
	ds_read_b128 v[204:207], v225 offset:54272
	ds_read_b128 v[208:211], v225 offset:55296
	ds_read_b128 v[212:215], v225 offset:56320
	global_load_lds_dwordx4 v[216:217], off
	s_add_i32 m0, s46, 0x2000
	s_add_u32 s44, s44, 0x80080
	v_lshl_add_u64 v[216:217], v[218:219], 0, s[30:31]
	s_addc_u32 s45, s45, 0
	s_add_i32 s46, s69, s48
	global_load_lds_dwordx4 v[216:217], off
	v_lshl_add_u64 v[216:217], s[44:45], 0, v[162:163]
	s_mov_b32 m0, s46
	s_nop 0
	global_load_lds_dwordx4 v[216:217], off
	v_lshl_add_u64 v[216:217], s[44:45], 0, v[160:161]
	s_add_i32 m0, s46, 0x2000
	s_nop 0
	global_load_lds_dwordx4 v[216:217], off
	v_lshl_add_u64 v[216:217], v[228:229], 0, s[30:31]
	s_mov_b32 m0, s54
	s_nop 0
	global_load_lds_dwordx4 v[216:217], off
	v_lshl_add_u64 v[216:217], v[230:231], 0, s[30:31]
	s_mov_b32 m0, s55
	s_nop 0
	global_load_lds_dwordx4 v[216:217], off
	s_sleep 1
	s_waitcnt vmcnt(8)
	s_waitcnt lgkmcnt(0)
	s_barrier
	s_setprio 1
	s_waitcnt lgkmcnt(0)
	v_mfma_f32_16x16x32_bf16 v[60:63], v[108:111], v[184:187], v[60:63]
	v_mfma_f32_16x16x32_bf16 v[56:59], v[120:123], v[184:187], v[56:59]
	v_mfma_f32_16x16x32_bf16 v[44:47], v[108:111], v[192:195], v[44:47]
	v_mfma_f32_16x16x32_bf16 v[40:43], v[120:123], v[192:195], v[40:43]
	v_mfma_f32_16x16x32_bf16 v[28:31], v[108:111], v[200:203], v[28:31]
	v_mfma_f32_16x16x32_bf16 v[24:27], v[120:123], v[200:203], v[24:27]
	v_mfma_f32_16x16x32_bf16 v[12:15], v[108:111], v[208:211], v[12:15]
	v_mfma_f32_16x16x32_bf16 v[8:11], v[120:123], v[208:211], v[8:11]
	v_mfma_f32_16x16x32_bf16 v[60:63], v[116:119], v[188:191], v[60:63]
	v_mfma_f32_16x16x32_bf16 v[56:59], v[124:127], v[188:191], v[56:59]
	v_mfma_f32_16x16x32_bf16 v[44:47], v[116:119], v[196:199], v[44:47]
	v_mfma_f32_16x16x32_bf16 v[40:43], v[124:127], v[196:199], v[40:43]
	v_mfma_f32_16x16x32_bf16 v[28:31], v[116:119], v[204:207], v[28:31]
	v_mfma_f32_16x16x32_bf16 v[24:27], v[124:127], v[204:207], v[24:27]
	v_mfma_f32_16x16x32_bf16 v[12:15], v[116:119], v[212:215], v[12:15]
	v_mfma_f32_16x16x32_bf16 v[8:11], v[124:127], v[212:215], v[8:11]
	s_setprio 0
	s_setprio 1
	v_mfma_f32_16x16x32_bf16 v[52:55], v[144:147], v[184:187], v[52:55]
	v_mfma_f32_16x16x32_bf16 v[48:51], v[152:155], v[184:187], v[48:51]
	v_mfma_f32_16x16x32_bf16 v[36:39], v[144:147], v[192:195], v[36:39]
	v_mfma_f32_16x16x32_bf16 v[32:35], v[152:155], v[192:195], v[32:35]
	v_mfma_f32_16x16x32_bf16 v[20:23], v[144:147], v[200:203], v[20:23]
	v_mfma_f32_16x16x32_bf16 v[16:19], v[152:155], v[200:203], v[16:19]
	v_mfma_f32_16x16x32_bf16 v[4:7], v[144:147], v[208:211], v[4:7]
	v_mfma_f32_16x16x32_bf16 v[0:3], v[152:155], v[208:211], v[0:3]
	v_mfma_f32_16x16x32_bf16 v[52:55], v[148:151], v[188:191], v[52:55]
	v_mfma_f32_16x16x32_bf16 v[48:51], v[156:159], v[188:191], v[48:51]
	v_mfma_f32_16x16x32_bf16 v[36:39], v[148:151], v[196:199], v[36:39]
	v_mfma_f32_16x16x32_bf16 v[32:35], v[156:159], v[196:199], v[32:35]
	v_mfma_f32_16x16x32_bf16 v[20:23], v[148:151], v[204:207], v[20:23]
	v_mfma_f32_16x16x32_bf16 v[16:19], v[156:159], v[204:207], v[16:19]
	v_mfma_f32_16x16x32_bf16 v[4:7], v[148:151], v[212:215], v[4:7]
	v_mfma_f32_16x16x32_bf16 v[0:3], v[156:159], v[212:215], v[0:3]
	s_setprio 0
	s_barrier
	s_add_i32 s67, s67, 2
	s_add_u32 s40, s40, 0x100
	s_addc_u32 s41, s41, 0
	s_add_u32 s42, s42, 0x100
	s_addc_u32 s43, s43, 0
	s_cmp_gt_u32 s67, 29
	s_cbranch_scc0 .LBB0_502
	s_and_b64 vcc, exec, s[34:35]
	s_cbranch_vccz .LBB0_505
	s_barrier

; #define PG8_STAGE(bufoff, gbase, voff) do { _Pragma("unroll") for (int _i = 0; _i < 2; ++_i) \
;         __builtin_amdgcn_global_load_lds((const unsigned*)((const char*)(gbase) + (voff)[_i]), (PG8_LAS unsigned*)(lds + (bufoff) + ldsw + _i * 8192), 16, 0, 0); } while (0)
; #define PG8_LDA(dst, b, h) do { _Pragma("unroll") for (int m = 0; m < 4; ++m) _Pragma("unroll") for (int k = 0; k < 2; ++k) dst[m][k] = *(const PG8_LAS bf16x8*)(lds + PG8_SA(b, h) + aoff + m * 2048 + k * 1024); } while (0)
; #define PG8_LDB(dst, b, h) do { _Pragma("unroll") for (int n = 0; n < 2; ++n) _Pragma("unroll") for (int k = 0; k < 2; ++k) dst[n][k] = *(const PG8_LAS bf16x8*)(lds + PG8_SB(b, h) + boff + n * 2048 + k * 1024); } while (0)
; #define PG8_MMA(ai, bj, At, Bt) do { __builtin_amdgcn_s_setprio(1); _Pragma("unroll") for (int m = 0; m < 4; ++m) _Pragma("unroll") for (int n = 0; n < 2; ++n) _Pragma("unroll") for (int k = 0; k < 2; ++k) \
;         acc[ai][bj][m][n] = __builtin_amdgcn_mfma_f32_16x16x32_bf16(Bt[n][k], At[m][k], acc[ai][bj][m][n], 0, 0, 0); __builtin_amdgcn_s_setprio(0); } while (0)
; #define PG8_WAIT_V(n) asm volatile("s_waitcnt vmcnt(" #n ")" ::: "memory")
; #define PG8_WAIT_L(n) asm volatile("s_waitcnt lgkmcnt(" #n ")" ::: "memory")
; template <class Epi, class Sched, bool ALIGN_EPI = false, bool SP2 = false>
; __device__ __forceinline__ void gemm_phase(PG8_LAS unsigned char* lds, const Gemm g, const Sched& S, const Epi& E) {
;     ...
;             const bool last = (t == nt - 2);
;             const char* a1 = cA + (size_t)(t + 1) * kstep;
;             const char* a2 = last ? nA : cA + (size_t)(t + 2) * kstep; const char* b2 = last ? nB : cB + (size_t)(t + 2) * kstep;
;             const char* a3 = a2 + kstep; const char* b3 = b2 + kstep;
;             if (last && has_next) S.a_ready(nxt);
;             if constexpr (SP2) {
;             PG8_LDB(B0, 0, 0); PG8_LDB(B1, 0, 1); PG8_SCHED; PG8_LDA(At, 0, 0); PG8_STAGE(PG8_SA(1, 1), a1 + hstep, voffA);
;             PG8_WAIT_V(8); PG8_WAIT_L(0); PG8_BAR; PG8_MMA(0, 0, At, B0); PG8_MMA(0, 1, At, B1); PG8_BAR; PG8_SCHED;
;             PG8_LDA(At, 0, 1); PG8_STAGE(PG8_SB(0, 0), b2, voffB); PG8_STAGE(PG8_SB(0, 1), b2 + hstep, voffB); PG8_STAGE(PG8_SA(0, 0), a2, voffA);
;             PG8_WAIT_V(8); PG8_WAIT_L(0); PG8_BAR; PG8_MMA(1, 0, At, B0); PG8_MMA(1, 1, At, B1); PG8_BAR; PG8_SCHED;
.LBB0_554:
	ds_read_b128 v[128:131], v167
	ds_read_b128 v[132:135], v167 offset:1024
	ds_read_b128 v[136:139], v167 offset:2048
	ds_read_b128 v[140:143], v167 offset:3072
	ds_read_b128 v[156:159], v168
	ds_read_b128 v[160:163], v168 offset:1024
	ds_read_b128 v[170:173], v168 offset:2048
	ds_read_b128 v[174:177], v168 offset:3072
	s_add_u32 s34, s30, 0x100
	s_addc_u32 s35, s31, 0
	s_cmp_eq_u32 s62, 28
	s_cselect_b32 s39, s23, s35
	s_cselect_b32 s38, s58, s34
	s_cselect_b32 s37, s21, s61
	s_cselect_b32 s36, s59, s60
	v_lshl_add_u64 v[210:211], s[30:31], 0, v[148:149]
	s_add_i32 m0, s29, 0xc000
	ds_read_b128 v[178:181], v169
	ds_read_b128 v[182:185], v169 offset:1024
	ds_read_b128 v[186:189], v169 offset:2048
	ds_read_b128 v[190:193], v169 offset:3072
	ds_read_b128 v[194:197], v169 offset:4096
	ds_read_b128 v[198:201], v169 offset:5120
	ds_read_b128 v[202:205], v169 offset:6144
	ds_read_b128 v[206:209], v169 offset:7168
	global_load_lds_dwordx4 v[210:211], off
	v_lshl_add_u64 v[210:211], s[30:31], 0, v[150:151]
	s_add_i32 m0, s29, 0xe000
	s_nop 0
	global_load_lds_dwordx4 v[210:211], off
	s_sleep 1
	s_waitcnt vmcnt(8)
	s_waitcnt lgkmcnt(0)
	s_barrier
	s_setprio 1
	s_waitcnt lgkmcnt(0)
	v_mfma_f32_16x16x32_bf16 v[124:127], v[128:131], v[178:181], v[124:127]
	v_mfma_f32_16x16x32_bf16 v[120:123], v[136:139], v[178:181], v[120:123]
	v_mfma_f32_16x16x32_bf16 v[116:119], v[128:131], v[186:189], v[116:119]
	v_mfma_f32_16x16x32_bf16 v[112:115], v[136:139], v[186:189], v[112:115]
	v_mfma_f32_16x16x32_bf16 v[92:95], v[128:131], v[194:197], v[92:95]
	v_mfma_f32_16x16x32_bf16 v[88:91], v[136:139], v[194:197], v[88:91]
	v_mfma_f32_16x16x32_bf16 v[84:87], v[128:131], v[202:205], v[84:87]
	v_mfma_f32_16x16x32_bf16 v[80:83], v[136:139], v[202:205], v[80:83]
	v_mfma_f32_16x16x32_bf16 v[124:127], v[132:135], v[182:185], v[124:127]
	v_mfma_f32_16x16x32_bf16 v[120:123], v[140:143], v[182:185], v[120:123]
	v_mfma_f32_16x16x32_bf16 v[116:119], v[132:135], v[190:193], v[116:119]
	v_mfma_f32_16x16x32_bf16 v[112:115], v[140:143], v[190:193], v[112:115]
	v_mfma_f32_16x16x32_bf16 v[92:95], v[132:135], v[198:201], v[92:95]
	v_mfma_f32_16x16x32_bf16 v[88:91], v[140:143], v[198:201], v[88:91]
	v_mfma_f32_16x16x32_bf16 v[84:87], v[132:135], v[206:209], v[84:87]
	v_mfma_f32_16x16x32_bf16 v[80:83], v[140:143], v[206:209], v[80:83]
	s_setprio 0
	s_setprio 1
	v_mfma_f32_16x16x32_bf16 v[108:111], v[156:159], v[178:181], v[108:111]
	v_mfma_f32_16x16x32_bf16 v[104:107], v[170:173], v[178:181], v[104:107]
	v_mfma_f32_16x16x32_bf16 v[100:103], v[156:159], v[186:189], v[100:103]
	v_mfma_f32_16x16x32_bf16 v[96:99], v[170:173], v[186:189], v[96:99]
	v_mfma_f32_16x16x32_bf16 v[76:79], v[156:159], v[194:197], v[76:79]
	v_mfma_f32_16x16x32_bf16 v[72:75], v[170:173], v[194:197], v[72:75]
	v_mfma_f32_16x16x32_bf16 v[68:71], v[156:159], v[202:205], v[68:71]
	v_mfma_f32_16x16x32_bf16 v[64:67], v[170:173], v[202:205], v[64:67]
	v_mfma_f32_16x16x32_bf16 v[108:111], v[160:163], v[182:185], v[108:111]
	v_mfma_f32_16x16x32_bf16 v[104:107], v[174:177], v[182:185], v[104:107]
	v_mfma_f32_16x16x32_bf16 v[100:103], v[160:163], v[190:193], v[100:103]
	v_mfma_f32_16x16x32_bf16 v[96:99], v[174:177], v[190:193], v[96:99]
	v_mfma_f32_16x16x32_bf16 v[76:79], v[160:163], v[198:201], v[76:79]
	v_mfma_f32_16x16x32_bf16 v[72:75], v[174:177], v[198:201], v[72:75]
	v_mfma_f32_16x16x32_bf16 v[68:71], v[160:163], v[206:209], v[68:71]
	v_mfma_f32_16x16x32_bf16 v[64:67], v[174:177], v[206:209], v[64:67]
	s_setprio 0
	s_barrier
	s_add_i32 s30, s53, s44
	v_lshl_add_u64 v[210:211], s[36:37], 0, v[144:145]
	s_mov_b32 m0, s30
	ds_read_b128 v[178:181], v169 offset:16384
	ds_read_b128 v[182:185], v169 offset:17408
	ds_read_b128 v[186:189], v169 offset:18432
	ds_read_b128 v[190:193], v169 offset:19456
	ds_read_b128 v[194:197], v169 offset:20480
	ds_read_b128 v[198:201], v169 offset:21504
	ds_read_b128 v[202:205], v169 offset:22528
	ds_read_b128 v[206:209], v169 offset:23552
	global_load_lds_dwordx4 v[210:211], off
	s_add_i32 m0, s30, 0x2000
	s_add_u32 s30, s36, 0x80000
	v_lshl_add_u64 v[212:213], s[36:37], 0, v[146:147]
	s_addc_u32 s31, s37, 0
	s_add_i32 s63, s54, s44
	global_load_lds_dwordx4 v[212:213], off
	v_lshl_add_u64 v[214:215], s[30:31], 0, v[144:145]
	s_mov_b32 m0, s63
	v_lshl_add_u64 v[216:217], s[38:39], 0, v[146:147]
	global_load_lds_dwordx4 v[214:215], off
	v_lshl_add_u64 v[214:215], s[30:31], 0, v[146:147]
	s_add_i32 m0, s63, 0x2000
	s_nop 0
	global_load_lds_dwordx4 v[214:215], off
	v_lshl_add_u64 v[214:215], s[38:39], 0, v[144:145]
	s_mov_b32 m0, s29
	s_nop 0
	global_load_lds_dwordx4 v[214:215], off
	s_mov_b32 m0, s45
	s_nop 0
	global_load_lds_dwordx4 v[216:217], off
	s_sleep 1
	s_waitcnt vmcnt(8)
	s_waitcnt lgkmcnt(0)
	s_barrier
; #define PG8_STAGE(bufoff, gbase, voff) do { _Pragma("unroll") for (int _i = 0; _i < 2; ++_i) \
;         __builtin_amdgcn_global_load_lds((const unsigned*)((const char*)(gbase) + (voff)[_i]), (PG8_LAS unsigned*)(lds + (bufoff) + ldsw + _i * 8192), 16, 0, 0); } while (0)
; #define PG8_LDA(dst, b, h) do { _Pragma("unroll") for (int m = 0; m < 4; ++m) _Pragma("unroll") for (int k = 0; k < 2; ++k) dst[m][k] = *(const PG8_LAS bf16x8*)(lds + PG8_SA(b, h) + aoff + m * 2048 + k * 1024); } while (0)
; #define PG8_LDB(dst, b, h) do { _Pragma("unroll") for (int n = 0; n < 2; ++n) _Pragma("unroll") for (int k = 0; k < 2; ++k) dst[n][k] = *(const PG8_LAS bf16x8*)(lds + PG8_SB(b, h) + boff + n * 2048 + k * 1024); } while (0)
; #define PG8_MMA(ai, bj, At, Bt) do { __builtin_amdgcn_s_setprio(1); _Pragma("unroll") for (int m = 0; m < 4; ++m) _Pragma("unroll") for (int n = 0; n < 2; ++n) _Pragma("unroll") for (int k = 0; k < 2; ++k) \
;         acc[ai][bj][m][n] = __builtin_amdgcn_mfma_f32_16x16x32_bf16(Bt[n][k], At[m][k], acc[ai][bj][m][n], 0, 0, 0); __builtin_amdgcn_s_setprio(0); } while (0)
; #define PG8_WAIT_V(n) asm volatile("s_waitcnt vmcnt(" #n ")" ::: "memory")
; #define PG8_WAIT_L(n) asm volatile("s_waitcnt lgkmcnt(" #n ")" ::: "memory")
; #define PG8_BAR __builtin_amdgcn_s_barrier()
; #define PG8_SCHED __builtin_amdgcn_sched_barrier(0)
; template <class Epi, class Sched, bool ALIGN_EPI = false, bool SP2 = false>
; __device__ __forceinline__ void gemm_phase(PG8_LAS unsigned char* lds, const Gemm g, const Sched& S, const Epi& E) {
;     ...
;             PG8_WAIT_V(8); PG8_WAIT_L(0); PG8_BAR; PG8_MMA(1, 0, At, B0); PG8_MMA(1, 1, At, B1); PG8_BAR; PG8_SCHED;
;             PG8_LDB(B0, 1, 0); PG8_LDB(B1, 1, 1); PG8_SCHED; PG8_LDA(At, 1, 0); PG8_STAGE(PG8_SA(0, 1), a2 + hstep, voffA);
;             PG8_WAIT_V(8); PG8_WAIT_L(0); PG8_BAR; PG8_MMA(0, 0, At, B0); PG8_MMA(0, 1, At, B1); PG8_BAR; PG8_SCHED;
	s_setprio 1
	s_waitcnt lgkmcnt(0)
	v_mfma_f32_16x16x32_bf16 v[60:63], v[128:131], v[178:181], v[60:63]
	v_mfma_f32_16x16x32_bf16 v[56:59], v[136:139], v[178:181], v[56:59]
	v_mfma_f32_16x16x32_bf16 v[52:55], v[128:131], v[186:189], v[52:55]
	v_mfma_f32_16x16x32_bf16 v[48:51], v[136:139], v[186:189], v[48:51]
	v_mfma_f32_16x16x32_bf16 v[28:31], v[128:131], v[194:197], v[28:31]
	v_mfma_f32_16x16x32_bf16 v[24:27], v[136:139], v[194:197], v[24:27]
	v_mfma_f32_16x16x32_bf16 v[20:23], v[128:131], v[202:205], v[20:23]
	v_mfma_f32_16x16x32_bf16 v[16:19], v[136:139], v[202:205], v[16:19]
	v_mfma_f32_16x16x32_bf16 v[60:63], v[132:135], v[182:185], v[60:63]
	v_mfma_f32_16x16x32_bf16 v[56:59], v[140:143], v[182:185], v[56:59]
	v_mfma_f32_16x16x32_bf16 v[52:55], v[132:135], v[190:193], v[52:55]
	v_mfma_f32_16x16x32_bf16 v[48:51], v[140:143], v[190:193], v[48:51]
	v_mfma_f32_16x16x32_bf16 v[28:31], v[132:135], v[198:201], v[28:31]
	v_mfma_f32_16x16x32_bf16 v[24:27], v[140:143], v[198:201], v[24:27]
	v_mfma_f32_16x16x32_bf16 v[20:23], v[132:135], v[206:209], v[20:23]
	v_mfma_f32_16x16x32_bf16 v[16:19], v[140:143], v[206:209], v[16:19]
	s_setprio 0
	s_setprio 1
	v_mfma_f32_16x16x32_bf16 v[44:47], v[156:159], v[178:181], v[44:47]
	v_mfma_f32_16x16x32_bf16 v[40:43], v[170:173], v[178:181], v[40:43]
	v_mfma_f32_16x16x32_bf16 v[36:39], v[156:159], v[186:189], v[36:39]
	v_mfma_f32_16x16x32_bf16 v[32:35], v[170:173], v[186:189], v[32:35]
	v_mfma_f32_16x16x32_bf16 v[12:15], v[156:159], v[194:197], v[12:15]
	v_mfma_f32_16x16x32_bf16 v[8:11], v[170:173], v[194:197], v[8:11]
	v_mfma_f32_16x16x32_bf16 v[4:7], v[156:159], v[202:205], v[4:7]
	v_mfma_f32_16x16x32_bf16 v[0:3], v[170:173], v[202:205], v[0:3]
	v_mfma_f32_16x16x32_bf16 v[44:47], v[160:163], v[182:185], v[44:47]
	v_mfma_f32_16x16x32_bf16 v[40:43], v[174:177], v[182:185], v[40:43]
	v_mfma_f32_16x16x32_bf16 v[36:39], v[160:163], v[190:193], v[36:39]
	v_mfma_f32_16x16x32_bf16 v[32:35], v[174:177], v[190:193], v[32:35]
	v_mfma_f32_16x16x32_bf16 v[12:15], v[160:163], v[198:201], v[12:15]
	v_mfma_f32_16x16x32_bf16 v[8:11], v[174:177], v[198:201], v[8:11]
	v_mfma_f32_16x16x32_bf16 v[4:7], v[160:163], v[206:209], v[4:7]
	v_mfma_f32_16x16x32_bf16 v[0:3], v[174:177], v[206:209], v[0:3]
	s_setprio 0
	s_barrier
	s_add_i32 s63, 0, 0x18000
	s_add_i32 s64, 0, 0x1c000
	v_add_u32_e32 v140, s63, v165
	v_add_u32_e32 v174, s64, v165
	ds_read_b128 v[128:131], v140
	ds_read_b128 v[132:135], v140 offset:1024
	ds_read_b128 v[136:139], v140 offset:2048
	ds_read_b128 v[140:143], v140 offset:3072
	ds_read_b128 v[156:159], v174
	ds_read_b128 v[160:163], v174 offset:1024
	ds_read_b128 v[170:173], v174 offset:2048
	ds_read_b128 v[174:177], v174 offset:3072
	s_add_u32 s30, s38, 0x80000
	s_addc_u32 s31, s39, 0
	s_mov_b32 m0, s46
	v_lshl_add_u64 v[218:219], s[30:31], 0, v[144:145]
	ds_read_b128 v[178:181], v169 offset:32768
	ds_read_b128 v[182:185], v169 offset:33792
	ds_read_b128 v[186:189], v169 offset:34816
	ds_read_b128 v[190:193], v169 offset:35840
	ds_read_b128 v[194:197], v169 offset:36864
	ds_read_b128 v[198:201], v169 offset:37888
	ds_read_b128 v[202:205], v169 offset:38912
	ds_read_b128 v[206:209], v169 offset:39936
	global_load_lds_dwordx4 v[218:219], off
	v_lshl_add_u64 v[218:219], s[30:31], 0, v[146:147]
	s_mov_b32 m0, s47
	s_nop 0
	global_load_lds_dwordx4 v[218:219], off
	s_sleep 1
	s_waitcnt vmcnt(8)
	s_waitcnt lgkmcnt(0)
	s_barrier
	s_setprio 1
	s_waitcnt lgkmcnt(0)
	v_mfma_f32_16x16x32_bf16 v[124:127], v[128:131], v[178:181], v[124:127]
	v_mfma_f32_16x16x32_bf16 v[120:123], v[136:139], v[178:181], v[120:123]
	v_mfma_f32_16x16x32_bf16 v[116:119], v[128:131], v[186:189], v[116:119]
	v_mfma_f32_16x16x32_bf16 v[112:115], v[136:139], v[186:189], v[112:115]
	v_mfma_f32_16x16x32_bf16 v[92:95], v[128:131], v[194:197], v[92:95]
	v_mfma_f32_16x16x32_bf16 v[88:91], v[136:139], v[194:197], v[88:91]
	v_mfma_f32_16x16x32_bf16 v[84:87], v[128:131], v[202:205], v[84:87]
	v_mfma_f32_16x16x32_bf16 v[80:83], v[136:139], v[202:205], v[80:83]
	v_mfma_f32_16x16x32_bf16 v[124:127], v[132:135], v[182:185], v[124:127]
	v_mfma_f32_16x16x32_bf16 v[120:123], v[140:143], v[182:185], v[120:123]
	v_mfma_f32_16x16x32_bf16 v[116:119], v[132:135], v[190:193], v[116:119]
	v_mfma_f32_16x16x32_bf16 v[112:115], v[140:143], v[190:193], v[112:115]
	v_mfma_f32_16x16x32_bf16 v[92:95], v[132:135], v[198:201], v[92:95]
	v_mfma_f32_16x16x32_bf16 v[88:91], v[140:143], v[198:201], v[88:91]
	v_mfma_f32_16x16x32_bf16 v[84:87], v[132:135], v[206:209], v[84:87]
	v_mfma_f32_16x16x32_bf16 v[80:83], v[140:143], v[206:209], v[80:83]
	s_setprio 0
	s_setprio 1
	v_mfma_f32_16x16x32_bf16 v[108:111], v[156:159], v[178:181], v[108:111]
	v_mfma_f32_16x16x32_bf16 v[104:107], v[170:173], v[178:181], v[104:107]
	v_mfma_f32_16x16x32_bf16 v[100:103], v[156:159], v[186:189], v[100:103]
	v_mfma_f32_16x16x32_bf16 v[96:99], v[170:173], v[186:189], v[96:99]
	v_mfma_f32_16x16x32_bf16 v[76:79], v[156:159], v[194:197], v[76:79]
	v_mfma_f32_16x16x32_bf16 v[72:75], v[170:173], v[194:197], v[72:75]
	v_mfma_f32_16x16x32_bf16 v[68:71], v[156:159], v[202:205], v[68:71]
	v_mfma_f32_16x16x32_bf16 v[64:67], v[170:173], v[202:205], v[64:67]
	v_mfma_f32_16x16x32_bf16 v[108:111], v[160:163], v[182:185], v[108:111]
	v_mfma_f32_16x16x32_bf16 v[104:107], v[174:177], v[182:185], v[104:107]
	v_mfma_f32_16x16x32_bf16 v[100:103], v[160:163], v[190:193], v[100:103]
	v_mfma_f32_16x16x32_bf16 v[96:99], v[174:177], v[190:193], v[96:99]
	v_mfma_f32_16x16x32_bf16 v[76:79], v[160:163], v[198:201], v[76:79]
	v_mfma_f32_16x16x32_bf16 v[72:75], v[174:177], v[198:201], v[72:75]
	v_mfma_f32_16x16x32_bf16 v[68:71], v[160:163], v[206:209], v[68:71]
	v_mfma_f32_16x16x32_bf16 v[64:67], v[174:177], v[206:209], v[64:67]
	s_setprio 0
	s_barrier
; #define PG8_STAGE(bufoff, gbase, voff) do { _Pragma("unroll") for (int _i = 0; _i < 2; ++_i) \
;         __builtin_amdgcn_global_load_lds((const unsigned*)((const char*)(gbase) + (voff)[_i]), (PG8_LAS unsigned*)(lds + (bufoff) + ldsw + _i * 8192), 16, 0, 0); } while (0)
; #define PG8_LDA(dst, b, h) do { _Pragma("unroll") for (int m = 0; m < 4; ++m) _Pragma("unroll") for (int k = 0; k < 2; ++k) dst[m][k] = *(const PG8_LAS bf16x8*)(lds + PG8_SA(b, h) + aoff + m * 2048 + k * 1024); } while (0)
; #define PG8_MMA(ai, bj, At, Bt) do { __builtin_amdgcn_s_setprio(1); _Pragma("unroll") for (int m = 0; m < 4; ++m) _Pragma("unroll") for (int n = 0; n < 2; ++n) _Pragma("unroll") for (int k = 0; k < 2; ++k) \
;         acc[ai][bj][m][n] = __builtin_amdgcn_mfma_f32_16x16x32_bf16(Bt[n][k], At[m][k], acc[ai][bj][m][n], 0, 0, 0); __builtin_amdgcn_s_setprio(0); } while (0)
; #define PG8_WAIT_V(n) asm volatile("s_waitcnt vmcnt(" #n ")" ::: "memory")
; #define PG8_WAIT_L(n) asm volatile("s_waitcnt lgkmcnt(" #n ")" ::: "memory")
; #define PG8_BAR __builtin_amdgcn_s_barrier()
; #define PG8_SCHED __builtin_amdgcn_sched_barrier(0)
; template <class Epi, class Sched, bool ALIGN_EPI = false, bool SP2 = false>
; __device__ __forceinline__ void gemm_phase(PG8_LAS unsigned char* lds, const Gemm g, const Sched& S, const Epi& E) {
;     ...
;             PG8_LDA(At, 1, 1); PG8_STAGE(PG8_SB(1, 0), b3, voffB); PG8_STAGE(PG8_SB(1, 1), b3 + hstep, voffB); PG8_STAGE(PG8_SA(1, 0), a3, voffA);
;             PG8_WAIT_V(8); PG8_WAIT_L(0); PG8_BAR; PG8_MMA(1, 0, At, B0); PG8_MMA(1, 1, At, B1); PG8_BAR; PG8_SCHED;
;     ...
;         if constexpr (ALIGN_EPI) { if (wr == 0) PG8_BAR; }
	s_add_i32 s30, s63, s44
	v_lshl_add_u64 v[210:211], v[210:211], 0, s[10:11]
	s_mov_b32 m0, s30
	ds_read_b128 v[178:181], v169 offset:49152
	ds_read_b128 v[182:185], v169 offset:50176
	ds_read_b128 v[186:189], v169 offset:51200
	ds_read_b128 v[190:193], v169 offset:52224
	ds_read_b128 v[194:197], v169 offset:53248
	ds_read_b128 v[198:201], v169 offset:54272
	ds_read_b128 v[202:205], v169 offset:55296
	ds_read_b128 v[206:209], v169 offset:56320
	global_load_lds_dwordx4 v[210:211], off
	s_add_i32 m0, s30, 0x2000
	s_add_u32 s30, s36, 0x80080
	v_lshl_add_u64 v[210:211], v[212:213], 0, s[10:11]
	s_addc_u32 s31, s37, 0
	s_add_i32 s36, s64, s44
	global_load_lds_dwordx4 v[210:211], off
	v_lshl_add_u64 v[210:211], s[30:31], 0, v[144:145]
	s_mov_b32 m0, s36
	s_nop 0
	global_load_lds_dwordx4 v[210:211], off
	v_lshl_add_u64 v[210:211], s[30:31], 0, v[146:147]
	s_add_i32 m0, s36, 0x2000
	s_nop 0
	global_load_lds_dwordx4 v[210:211], off
	v_lshl_add_u64 v[210:211], v[214:215], 0, s[10:11]
	s_mov_b32 m0, s51
	s_nop 0
	global_load_lds_dwordx4 v[210:211], off
	v_lshl_add_u64 v[210:211], v[216:217], 0, s[10:11]
	s_mov_b32 m0, s52
	s_nop 0
	global_load_lds_dwordx4 v[210:211], off
	s_sleep 1
	s_waitcnt vmcnt(8)
	s_waitcnt lgkmcnt(0)
	s_barrier
	s_setprio 1
	s_waitcnt lgkmcnt(0)
	v_mfma_f32_16x16x32_bf16 v[60:63], v[128:131], v[178:181], v[60:63]
	v_mfma_f32_16x16x32_bf16 v[56:59], v[136:139], v[178:181], v[56:59]
	v_mfma_f32_16x16x32_bf16 v[52:55], v[128:131], v[186:189], v[52:55]
	v_mfma_f32_16x16x32_bf16 v[48:51], v[136:139], v[186:189], v[48:51]
	v_mfma_f32_16x16x32_bf16 v[28:31], v[128:131], v[194:197], v[28:31]
	v_mfma_f32_16x16x32_bf16 v[24:27], v[136:139], v[194:197], v[24:27]
	v_mfma_f32_16x16x32_bf16 v[20:23], v[128:131], v[202:205], v[20:23]
	v_mfma_f32_16x16x32_bf16 v[16:19], v[136:139], v[202:205], v[16:19]
	v_mfma_f32_16x16x32_bf16 v[60:63], v[132:135], v[182:185], v[60:63]
	v_mfma_f32_16x16x32_bf16 v[56:59], v[140:143], v[182:185], v[56:59]
	v_mfma_f32_16x16x32_bf16 v[52:55], v[132:135], v[190:193], v[52:55]
	v_mfma_f32_16x16x32_bf16 v[48:51], v[140:143], v[190:193], v[48:51]
	v_mfma_f32_16x16x32_bf16 v[28:31], v[132:135], v[198:201], v[28:31]
	v_mfma_f32_16x16x32_bf16 v[24:27], v[140:143], v[198:201], v[24:27]
	v_mfma_f32_16x16x32_bf16 v[20:23], v[132:135], v[206:209], v[20:23]
	v_mfma_f32_16x16x32_bf16 v[16:19], v[140:143], v[206:209], v[16:19]
	s_setprio 0
	s_setprio 1
	v_mfma_f32_16x16x32_bf16 v[44:47], v[156:159], v[178:181], v[44:47]
	v_mfma_f32_16x16x32_bf16 v[40:43], v[170:173], v[178:181], v[40:43]
	v_mfma_f32_16x16x32_bf16 v[36:39], v[156:159], v[186:189], v[36:39]
	v_mfma_f32_16x16x32_bf16 v[32:35], v[170:173], v[186:189], v[32:35]
	v_mfma_f32_16x16x32_bf16 v[12:15], v[156:159], v[194:197], v[12:15]
	v_mfma_f32_16x16x32_bf16 v[8:11], v[170:173], v[194:197], v[8:11]
	v_mfma_f32_16x16x32_bf16 v[4:7], v[156:159], v[202:205], v[4:7]
	v_mfma_f32_16x16x32_bf16 v[0:3], v[170:173], v[202:205], v[0:3]
	v_mfma_f32_16x16x32_bf16 v[44:47], v[160:163], v[182:185], v[44:47]
	v_mfma_f32_16x16x32_bf16 v[40:43], v[174:177], v[182:185], v[40:43]
	v_mfma_f32_16x16x32_bf16 v[36:39], v[160:163], v[190:193], v[36:39]
	v_mfma_f32_16x16x32_bf16 v[32:35], v[174:177], v[190:193], v[32:35]
	v_mfma_f32_16x16x32_bf16 v[12:15], v[160:163], v[198:201], v[12:15]
	v_mfma_f32_16x16x32_bf16 v[8:11], v[174:177], v[198:201], v[8:11]
	v_mfma_f32_16x16x32_bf16 v[4:7], v[160:163], v[206:209], v[4:7]
	v_mfma_f32_16x16x32_bf16 v[0:3], v[174:177], v[206:209], v[0:3]
	s_setprio 0
	s_barrier
	s_add_i32 s62, s62, 2
	s_add_u32 s60, s60, 0x100
	s_addc_u32 s61, s61, 0
	s_cmp_gt_u32 s62, 29
	s_mov_b64 s[30:31], s[34:35]
	s_cbranch_scc0 .LBB0_554
	s_and_b64 vcc, exec, s[14:15]
	s_cbranch_vccz .LBB0_557
	s_barrier

; #define PG8_STAGE(bufoff, gbase, voff) do { _Pragma("unroll") for (int _i = 0; _i < 2; ++_i) \
;         __builtin_amdgcn_global_load_lds((const unsigned*)((const char*)(gbase) + (voff)[_i]), (PG8_LAS unsigned*)(lds + (bufoff) + ldsw + _i * 8192), 16, 0, 0); } while (0)
; #define PG8_LDA(dst, b, h) do { _Pragma("unroll") for (int m = 0; m < 4; ++m) _Pragma("unroll") for (int k = 0; k < 2; ++k) dst[m][k] = *(const PG8_LAS bf16x8*)(lds + PG8_SA(b, h) + aoff + m * 2048 + k * 1024); } while (0)
; #define PG8_LDB(dst, b, h) do { _Pragma("unroll") for (int n = 0; n < 2; ++n) _Pragma("unroll") for (int k = 0; k < 2; ++k) dst[n][k] = *(const PG8_LAS bf16x8*)(lds + PG8_SB(b, h) + boff + n * 2048 + k * 1024); } while (0)
; #define PG8_MMA(ai, bj, At, Bt) do { __builtin_amdgcn_s_setprio(1); _Pragma("unroll") for (int m = 0; m < 4; ++m) _Pragma("unroll") for (int n = 0; n < 2; ++n) _Pragma("unroll") for (int k = 0; k < 2; ++k) \
;         acc[ai][bj][m][n] = __builtin_amdgcn_mfma_f32_16x16x32_bf16(Bt[n][k], At[m][k], acc[ai][bj][m][n], 0, 0, 0); __builtin_amdgcn_s_setprio(0); } while (0)
; #define PG8_WAIT_V(n) asm volatile("s_waitcnt vmcnt(" #n ")" ::: "memory")
; #define PG8_WAIT_L(n) asm volatile("s_waitcnt lgkmcnt(" #n ")" ::: "memory")
; template <class Epi, class Sched, bool ALIGN_EPI = false, bool SP2 = false>
; __device__ __forceinline__ void gemm_phase(PG8_LAS unsigned char* lds, const Gemm g, const Sched& S, const Epi& E) {
;     ...
;             const bool last = (t == nt - 2);
;             const char* a1 = cA + (size_t)(t + 1) * kstep;
;             const char* a2 = last ? nA : cA + (size_t)(t + 2) * kstep; const char* b2 = last ? nB : cB + (size_t)(t + 2) * kstep;
;             const char* a3 = a2 + kstep; const char* b3 = b2 + kstep;
;             if (last && has_next) S.a_ready(nxt);
;             if constexpr (SP2) {
;             PG8_LDB(B0, 0, 0); PG8_LDB(B1, 0, 1); PG8_SCHED; PG8_LDA(At, 0, 0); PG8_STAGE(PG8_SA(1, 1), a1 + hstep, voffA);
;             PG8_WAIT_V(8); PG8_WAIT_L(0); PG8_BAR; PG8_MMA(0, 0, At, B0); PG8_MMA(0, 1, At, B1); PG8_BAR; PG8_SCHED;
;             PG8_LDA(At, 0, 1); PG8_STAGE(PG8_SB(0, 0), b2, voffB); PG8_STAGE(PG8_SB(0, 1), b2 + hstep, voffB); PG8_STAGE(PG8_SA(0, 0), a2, voffA);
;             PG8_WAIT_V(8); PG8_WAIT_L(0); PG8_BAR; PG8_MMA(1, 0, At, B0); PG8_MMA(1, 1, At, B1); PG8_BAR; PG8_SCHED;
.LBB0_679:
	ds_read_b128 v[120:123], v200
	ds_read_b128 v[124:127], v200 offset:1024
	ds_read_b128 v[128:131], v200 offset:2048
	ds_read_b128 v[132:135], v200 offset:3072
	ds_read_b128 v[136:139], v201
	ds_read_b128 v[140:143], v201 offset:1024
	ds_read_b128 v[144:147], v201 offset:2048
	ds_read_b128 v[148:151], v201 offset:3072
	s_add_u32 s58, s54, 0xfff80080
	s_addc_u32 s59, s55, -1
	s_cmp_eq_u32 s91, 28
	s_cselect_b32 s61, s49, s59
	s_cselect_b32 s60, s85, s58
	s_cselect_b32 s59, s47, s90
	s_cselect_b32 s58, s88, s89
	v_lshl_add_u64 v[192:193], s[54:55], 0, v[174:175]
	s_add_i32 m0, s67, 0xc000
	ds_read_b128 v[160:163], v202
	ds_read_b128 v[164:167], v202 offset:1024
	ds_read_b128 v[180:183], v202 offset:2048
	ds_read_b128 v[184:187], v202 offset:3072
	ds_read_b128 v[188:191], v202 offset:4096
	ds_read_b128 v[206:209], v202 offset:5120
	ds_read_b128 v[210:213], v202 offset:6144
	ds_read_b128 v[214:217], v202 offset:7168
	global_load_lds_dwordx4 v[192:193], off
	v_lshl_add_u64 v[192:193], s[54:55], 0, v[172:173]
	s_add_i32 m0, s67, 0xe000
	s_nop 0
	global_load_lds_dwordx4 v[192:193], off
	s_sleep 1
	s_waitcnt vmcnt(8)
	s_waitcnt lgkmcnt(0)
	s_barrier
	s_setprio 1
	s_waitcnt lgkmcnt(0)
	v_mfma_f32_16x16x32_bf16 v[156:159], v[120:123], v[160:163], v[156:159]
	v_mfma_f32_16x16x32_bf16 v[60:63], v[128:131], v[160:163], v[60:63]
	v_mfma_f32_16x16x32_bf16 v[116:119], v[120:123], v[180:183], v[116:119]
	v_mfma_f32_16x16x32_bf16 v[52:55], v[128:131], v[180:183], v[52:55]
	v_mfma_f32_16x16x32_bf16 v[108:111], v[120:123], v[188:191], v[108:111]
	v_mfma_f32_16x16x32_bf16 v[44:47], v[128:131], v[188:191], v[44:47]
	v_mfma_f32_16x16x32_bf16 v[104:107], v[120:123], v[210:213], v[104:107]
	v_mfma_f32_16x16x32_bf16 v[40:43], v[128:131], v[210:213], v[40:43]
	v_mfma_f32_16x16x32_bf16 v[156:159], v[124:127], v[164:167], v[156:159]
	v_mfma_f32_16x16x32_bf16 v[60:63], v[132:135], v[164:167], v[60:63]
	v_mfma_f32_16x16x32_bf16 v[116:119], v[124:127], v[184:187], v[116:119]
	v_mfma_f32_16x16x32_bf16 v[52:55], v[132:135], v[184:187], v[52:55]
	v_mfma_f32_16x16x32_bf16 v[108:111], v[124:127], v[206:209], v[108:111]
	v_mfma_f32_16x16x32_bf16 v[44:47], v[132:135], v[206:209], v[44:47]
	v_mfma_f32_16x16x32_bf16 v[104:107], v[124:127], v[214:217], v[104:107]
	v_mfma_f32_16x16x32_bf16 v[40:43], v[132:135], v[214:217], v[40:43]
	s_setprio 0
	s_setprio 1
	v_mfma_f32_16x16x32_bf16 v[152:155], v[136:139], v[160:163], v[152:155]
	v_mfma_f32_16x16x32_bf16 v[56:59], v[144:147], v[160:163], v[56:59]
	v_mfma_f32_16x16x32_bf16 v[112:115], v[136:139], v[180:183], v[112:115]
	v_mfma_f32_16x16x32_bf16 v[48:51], v[144:147], v[180:183], v[48:51]
	v_mfma_f32_16x16x32_bf16 v[100:103], v[136:139], v[188:191], v[100:103]
	v_mfma_f32_16x16x32_bf16 v[36:39], v[144:147], v[188:191], v[36:39]
	v_mfma_f32_16x16x32_bf16 v[96:99], v[136:139], v[210:213], v[96:99]
	v_mfma_f32_16x16x32_bf16 v[32:35], v[144:147], v[210:213], v[32:35]
	v_mfma_f32_16x16x32_bf16 v[152:155], v[140:143], v[164:167], v[152:155]
	v_mfma_f32_16x16x32_bf16 v[56:59], v[148:151], v[164:167], v[56:59]
	v_mfma_f32_16x16x32_bf16 v[112:115], v[140:143], v[184:187], v[112:115]
	v_mfma_f32_16x16x32_bf16 v[48:51], v[148:151], v[184:187], v[48:51]
	v_mfma_f32_16x16x32_bf16 v[100:103], v[140:143], v[206:209], v[100:103]
	v_mfma_f32_16x16x32_bf16 v[36:39], v[148:151], v[206:209], v[36:39]
	v_mfma_f32_16x16x32_bf16 v[96:99], v[140:143], v[214:217], v[96:99]
	v_mfma_f32_16x16x32_bf16 v[32:35], v[148:151], v[214:217], v[32:35]
	s_setprio 0
	s_barrier
	s_add_i32 s92, s78, s66
	v_lshl_add_u64 v[192:193], s[58:59], 0, v[170:171]
	s_mov_b32 m0, s92
	ds_read_b128 v[160:163], v202 offset:16384
	ds_read_b128 v[164:167], v202 offset:17408
	ds_read_b128 v[180:183], v202 offset:18432
	ds_read_b128 v[184:187], v202 offset:19456
	ds_read_b128 v[188:191], v202 offset:20480
	ds_read_b128 v[206:209], v202 offset:21504
	ds_read_b128 v[210:213], v202 offset:22528
	ds_read_b128 v[214:217], v202 offset:23552
	global_load_lds_dwordx4 v[192:193], off
	s_add_i32 m0, s92, 0x2000
	s_add_u32 s92, s58, 0x80000
	v_lshl_add_u64 v[218:219], s[58:59], 0, v[168:169]
	s_addc_u32 s93, s59, 0
	s_add_i32 s95, s79, s66
	global_load_lds_dwordx4 v[218:219], off
	v_lshl_add_u64 v[222:223], s[92:93], 0, v[170:171]
	s_mov_b32 m0, s95
	v_lshl_add_u64 v[224:225], s[60:61], 0, v[168:169]
	global_load_lds_dwordx4 v[222:223], off
	v_lshl_add_u64 v[222:223], s[92:93], 0, v[168:169]
	s_add_i32 m0, s95, 0x2000
	s_nop 0
	global_load_lds_dwordx4 v[222:223], off
	v_lshl_add_u64 v[222:223], s[60:61], 0, v[170:171]
	s_mov_b32 m0, s67
	s_nop 0
	global_load_lds_dwordx4 v[222:223], off
	s_mov_b32 m0, s68
	s_nop 0
	global_load_lds_dwordx4 v[224:225], off
	s_sleep 1
	s_waitcnt vmcnt(8)
	s_waitcnt lgkmcnt(0)
	s_barrier
; #define PG8_STAGE(bufoff, gbase, voff) do { _Pragma("unroll") for (int _i = 0; _i < 2; ++_i) \
;         __builtin_amdgcn_global_load_lds((const unsigned*)((const char*)(gbase) + (voff)[_i]), (PG8_LAS unsigned*)(lds + (bufoff) + ldsw + _i * 8192), 16, 0, 0); } while (0)
; #define PG8_LDA(dst, b, h) do { _Pragma("unroll") for (int m = 0; m < 4; ++m) _Pragma("unroll") for (int k = 0; k < 2; ++k) dst[m][k] = *(const PG8_LAS bf16x8*)(lds + PG8_SA(b, h) + aoff + m * 2048 + k * 1024); } while (0)
; #define PG8_LDB(dst, b, h) do { _Pragma("unroll") for (int n = 0; n < 2; ++n) _Pragma("unroll") for (int k = 0; k < 2; ++k) dst[n][k] = *(const PG8_LAS bf16x8*)(lds + PG8_SB(b, h) + boff + n * 2048 + k * 1024); } while (0)
; #define PG8_MMA(ai, bj, At, Bt) do { __builtin_amdgcn_s_setprio(1); _Pragma("unroll") for (int m = 0; m < 4; ++m) _Pragma("unroll") for (int n = 0; n < 2; ++n) _Pragma("unroll") for (int k = 0; k < 2; ++k) \
;         acc[ai][bj][m][n] = __builtin_amdgcn_mfma_f32_16x16x32_bf16(Bt[n][k], At[m][k], acc[ai][bj][m][n], 0, 0, 0); __builtin_amdgcn_s_setprio(0); } while (0)
; #define PG8_WAIT_V(n) asm volatile("s_waitcnt vmcnt(" #n ")" ::: "memory")
; #define PG8_WAIT_L(n) asm volatile("s_waitcnt lgkmcnt(" #n ")" ::: "memory")
; #define PG8_BAR __builtin_amdgcn_s_barrier()
; #define PG8_SCHED __builtin_amdgcn_sched_barrier(0)
; template <class Epi, class Sched, bool ALIGN_EPI = false, bool SP2 = false>
; __device__ __forceinline__ void gemm_phase(PG8_LAS unsigned char* lds, const Gemm g, const Sched& S, const Epi& E) {
;     ...
;             PG8_WAIT_V(8); PG8_WAIT_L(0); PG8_BAR; PG8_MMA(1, 0, At, B0); PG8_MMA(1, 1, At, B1); PG8_BAR; PG8_SCHED;
;             PG8_LDB(B0, 1, 0); PG8_LDB(B1, 1, 1); PG8_SCHED; PG8_LDA(At, 1, 0); PG8_STAGE(PG8_SA(0, 1), a2 + hstep, voffA);
;             PG8_WAIT_V(8); PG8_WAIT_L(0); PG8_BAR; PG8_MMA(0, 0, At, B0); PG8_MMA(0, 1, At, B1); PG8_BAR; PG8_SCHED;
	s_setprio 1
	s_waitcnt lgkmcnt(0)
	v_mfma_f32_16x16x32_bf16 v[92:95], v[120:123], v[160:163], v[92:95]
	v_mfma_f32_16x16x32_bf16 v[28:31], v[128:131], v[160:163], v[28:31]
	v_mfma_f32_16x16x32_bf16 v[84:87], v[120:123], v[180:183], v[84:87]
	v_mfma_f32_16x16x32_bf16 v[20:23], v[128:131], v[180:183], v[20:23]
	v_mfma_f32_16x16x32_bf16 v[76:79], v[120:123], v[188:191], v[76:79]
	v_mfma_f32_16x16x32_bf16 v[12:15], v[128:131], v[188:191], v[12:15]
	v_mfma_f32_16x16x32_bf16 v[72:75], v[120:123], v[210:213], v[72:75]
	v_mfma_f32_16x16x32_bf16 v[8:11], v[128:131], v[210:213], v[8:11]
	v_mfma_f32_16x16x32_bf16 v[92:95], v[124:127], v[164:167], v[92:95]
	v_mfma_f32_16x16x32_bf16 v[28:31], v[132:135], v[164:167], v[28:31]
	v_mfma_f32_16x16x32_bf16 v[84:87], v[124:127], v[184:187], v[84:87]
	v_mfma_f32_16x16x32_bf16 v[20:23], v[132:135], v[184:187], v[20:23]
	v_mfma_f32_16x16x32_bf16 v[76:79], v[124:127], v[206:209], v[76:79]
	v_mfma_f32_16x16x32_bf16 v[12:15], v[132:135], v[206:209], v[12:15]
	v_mfma_f32_16x16x32_bf16 v[72:75], v[124:127], v[214:217], v[72:75]
	v_mfma_f32_16x16x32_bf16 v[8:11], v[132:135], v[214:217], v[8:11]
	s_setprio 0
	s_setprio 1
	v_mfma_f32_16x16x32_bf16 v[88:91], v[136:139], v[160:163], v[88:91]
	v_mfma_f32_16x16x32_bf16 v[24:27], v[144:147], v[160:163], v[24:27]
	v_mfma_f32_16x16x32_bf16 v[80:83], v[136:139], v[180:183], v[80:83]
	v_mfma_f32_16x16x32_bf16 v[16:19], v[144:147], v[180:183], v[16:19]
	v_mfma_f32_16x16x32_bf16 v[68:71], v[136:139], v[188:191], v[68:71]
	v_mfma_f32_16x16x32_bf16 v[4:7], v[144:147], v[188:191], v[4:7]
	v_mfma_f32_16x16x32_bf16 v[64:67], v[136:139], v[210:213], v[64:67]
	v_mfma_f32_16x16x32_bf16 v[0:3], v[144:147], v[210:213], v[0:3]
	v_mfma_f32_16x16x32_bf16 v[88:91], v[140:143], v[164:167], v[88:91]
	v_mfma_f32_16x16x32_bf16 v[24:27], v[148:151], v[164:167], v[24:27]
	v_mfma_f32_16x16x32_bf16 v[80:83], v[140:143], v[184:187], v[80:83]
	v_mfma_f32_16x16x32_bf16 v[16:19], v[148:151], v[184:187], v[16:19]
	v_mfma_f32_16x16x32_bf16 v[68:71], v[140:143], v[206:209], v[68:71]
	v_mfma_f32_16x16x32_bf16 v[4:7], v[148:151], v[206:209], v[4:7]
	v_mfma_f32_16x16x32_bf16 v[64:67], v[140:143], v[214:217], v[64:67]
	v_mfma_f32_16x16x32_bf16 v[0:3], v[148:151], v[214:217], v[0:3]
	s_setprio 0
	s_barrier
	s_add_i32 s92, 0, 0x18000
	s_add_i32 s93, 0, 0x1c000
	v_add_u32_e32 v132, s92, v196
	v_add_u32_e32 v148, s93, v196
	ds_read_b128 v[120:123], v132
	ds_read_b128 v[124:127], v132 offset:1024
	ds_read_b128 v[128:131], v132 offset:2048
	ds_read_b128 v[132:135], v132 offset:3072
	ds_read_b128 v[136:139], v148
	ds_read_b128 v[140:143], v148 offset:1024
	ds_read_b128 v[144:147], v148 offset:2048
	ds_read_b128 v[148:151], v148 offset:3072
	s_add_u32 s60, s60, 0x80000
	s_addc_u32 s61, s61, 0
	s_mov_b32 m0, s69
	v_lshl_add_u64 v[226:227], s[60:61], 0, v[170:171]
	ds_read_b128 v[160:163], v202 offset:32768
	ds_read_b128 v[164:167], v202 offset:33792
	ds_read_b128 v[180:183], v202 offset:34816
	ds_read_b128 v[184:187], v202 offset:35840
	ds_read_b128 v[188:191], v202 offset:36864
	ds_read_b128 v[206:209], v202 offset:37888
	ds_read_b128 v[210:213], v202 offset:38912
	ds_read_b128 v[214:217], v202 offset:39936
	global_load_lds_dwordx4 v[226:227], off
	v_lshl_add_u64 v[226:227], s[60:61], 0, v[168:169]
	s_mov_b32 m0, s70
	s_nop 0
	global_load_lds_dwordx4 v[226:227], off
	s_sleep 1
	s_waitcnt vmcnt(8)
	s_waitcnt lgkmcnt(0)
	s_barrier
	s_setprio 1
	s_waitcnt lgkmcnt(0)
	v_mfma_f32_16x16x32_bf16 v[156:159], v[120:123], v[160:163], v[156:159]
	v_mfma_f32_16x16x32_bf16 v[60:63], v[128:131], v[160:163], v[60:63]
	v_mfma_f32_16x16x32_bf16 v[116:119], v[120:123], v[180:183], v[116:119]
	v_mfma_f32_16x16x32_bf16 v[52:55], v[128:131], v[180:183], v[52:55]
	v_mfma_f32_16x16x32_bf16 v[108:111], v[120:123], v[188:191], v[108:111]
	v_mfma_f32_16x16x32_bf16 v[44:47], v[128:131], v[188:191], v[44:47]
	v_mfma_f32_16x16x32_bf16 v[104:107], v[120:123], v[210:213], v[104:107]
	v_mfma_f32_16x16x32_bf16 v[40:43], v[128:131], v[210:213], v[40:43]
	v_mfma_f32_16x16x32_bf16 v[156:159], v[124:127], v[164:167], v[156:159]
	v_mfma_f32_16x16x32_bf16 v[60:63], v[132:135], v[164:167], v[60:63]
	v_mfma_f32_16x16x32_bf16 v[116:119], v[124:127], v[184:187], v[116:119]
	v_mfma_f32_16x16x32_bf16 v[52:55], v[132:135], v[184:187], v[52:55]
	v_mfma_f32_16x16x32_bf16 v[108:111], v[124:127], v[206:209], v[108:111]
	v_mfma_f32_16x16x32_bf16 v[44:47], v[132:135], v[206:209], v[44:47]
	v_mfma_f32_16x16x32_bf16 v[104:107], v[124:127], v[214:217], v[104:107]
	v_mfma_f32_16x16x32_bf16 v[40:43], v[132:135], v[214:217], v[40:43]
	s_setprio 0
	s_setprio 1
	v_mfma_f32_16x16x32_bf16 v[152:155], v[136:139], v[160:163], v[152:155]
	v_mfma_f32_16x16x32_bf16 v[56:59], v[144:147], v[160:163], v[56:59]
	v_mfma_f32_16x16x32_bf16 v[112:115], v[136:139], v[180:183], v[112:115]
	v_mfma_f32_16x16x32_bf16 v[48:51], v[144:147], v[180:183], v[48:51]
	v_mfma_f32_16x16x32_bf16 v[100:103], v[136:139], v[188:191], v[100:103]
	v_mfma_f32_16x16x32_bf16 v[36:39], v[144:147], v[188:191], v[36:39]
	v_mfma_f32_16x16x32_bf16 v[96:99], v[136:139], v[210:213], v[96:99]
	v_mfma_f32_16x16x32_bf16 v[32:35], v[144:147], v[210:213], v[32:35]
	v_mfma_f32_16x16x32_bf16 v[152:155], v[140:143], v[164:167], v[152:155]
	v_mfma_f32_16x16x32_bf16 v[56:59], v[148:151], v[164:167], v[56:59]
	v_mfma_f32_16x16x32_bf16 v[112:115], v[140:143], v[184:187], v[112:115]
	v_mfma_f32_16x16x32_bf16 v[48:51], v[148:151], v[184:187], v[48:51]
	v_mfma_f32_16x16x32_bf16 v[100:103], v[140:143], v[206:209], v[100:103]
	v_mfma_f32_16x16x32_bf16 v[36:39], v[148:151], v[206:209], v[36:39]
	v_mfma_f32_16x16x32_bf16 v[96:99], v[140:143], v[214:217], v[96:99]
	v_mfma_f32_16x16x32_bf16 v[32:35], v[148:151], v[214:217], v[32:35]
	s_setprio 0
	s_barrier
; #define PG8_STAGE(bufoff, gbase, voff) do { _Pragma("unroll") for (int _i = 0; _i < 2; ++_i) \
;         __builtin_amdgcn_global_load_lds((const unsigned*)((const char*)(gbase) + (voff)[_i]), (PG8_LAS unsigned*)(lds + (bufoff) + ldsw + _i * 8192), 16, 0, 0); } while (0)
; #define PG8_LDA(dst, b, h) do { _Pragma("unroll") for (int m = 0; m < 4; ++m) _Pragma("unroll") for (int k = 0; k < 2; ++k) dst[m][k] = *(const PG8_LAS bf16x8*)(lds + PG8_SA(b, h) + aoff + m * 2048 + k * 1024); } while (0)
; #define PG8_MMA(ai, bj, At, Bt) do { __builtin_amdgcn_s_setprio(1); _Pragma("unroll") for (int m = 0; m < 4; ++m) _Pragma("unroll") for (int n = 0; n < 2; ++n) _Pragma("unroll") for (int k = 0; k < 2; ++k) \
;         acc[ai][bj][m][n] = __builtin_amdgcn_mfma_f32_16x16x32_bf16(Bt[n][k], At[m][k], acc[ai][bj][m][n], 0, 0, 0); __builtin_amdgcn_s_setprio(0); } while (0)
; #define PG8_WAIT_V(n) asm volatile("s_waitcnt vmcnt(" #n ")" ::: "memory")
; #define PG8_WAIT_L(n) asm volatile("s_waitcnt lgkmcnt(" #n ")" ::: "memory")
; #define PG8_BAR __builtin_amdgcn_s_barrier()
; #define PG8_SCHED __builtin_amdgcn_sched_barrier(0)
; template <class Epi, class Sched, bool ALIGN_EPI = false, bool SP2 = false>
; __device__ __forceinline__ void gemm_phase(PG8_LAS unsigned char* lds, const Gemm g, const Sched& S, const Epi& E) {
;     ...
;             PG8_LDA(At, 1, 1); PG8_STAGE(PG8_SB(1, 0), b3, voffB); PG8_STAGE(PG8_SB(1, 1), b3 + hstep, voffB); PG8_STAGE(PG8_SA(1, 0), a3, voffA);
;             PG8_WAIT_V(8); PG8_WAIT_L(0); PG8_BAR; PG8_MMA(1, 0, At, B0); PG8_MMA(1, 1, At, B1); PG8_BAR; PG8_SCHED;
;     ...
;         if constexpr (ALIGN_EPI) { if (wr == 0) PG8_BAR; }
	s_add_i32 s60, s92, s66
	v_lshl_add_u64 v[192:193], v[192:193], 0, s[22:23]
	s_mov_b32 m0, s60
	ds_read_b128 v[160:163], v202 offset:49152
	ds_read_b128 v[164:167], v202 offset:50176
	ds_read_b128 v[180:183], v202 offset:51200
	ds_read_b128 v[184:187], v202 offset:52224
	ds_read_b128 v[188:191], v202 offset:53248
	ds_read_b128 v[206:209], v202 offset:54272
	ds_read_b128 v[210:213], v202 offset:55296
	ds_read_b128 v[214:217], v202 offset:56320
	global_load_lds_dwordx4 v[192:193], off
	s_add_i32 m0, s60, 0x2000
	s_add_u32 s58, s58, 0x80080
	v_lshl_add_u64 v[192:193], v[218:219], 0, s[22:23]
	s_addc_u32 s59, s59, 0
	s_add_i32 s60, s93, s66
	global_load_lds_dwordx4 v[192:193], off
	v_lshl_add_u64 v[192:193], s[58:59], 0, v[170:171]
	s_mov_b32 m0, s60
	s_nop 0
	global_load_lds_dwordx4 v[192:193], off
	v_lshl_add_u64 v[192:193], s[58:59], 0, v[168:169]
	s_add_i32 m0, s60, 0x2000
	s_nop 0
	global_load_lds_dwordx4 v[192:193], off
	v_lshl_add_u64 v[192:193], v[222:223], 0, s[22:23]
	s_mov_b32 m0, s71
	s_nop 0
	global_load_lds_dwordx4 v[192:193], off
	v_lshl_add_u64 v[192:193], v[224:225], 0, s[22:23]
	s_mov_b32 m0, s72
	s_nop 0
	global_load_lds_dwordx4 v[192:193], off
	s_sleep 1
	s_waitcnt vmcnt(8)
	s_waitcnt lgkmcnt(0)
	s_barrier
	s_setprio 1
	s_waitcnt lgkmcnt(0)
	v_mfma_f32_16x16x32_bf16 v[92:95], v[120:123], v[160:163], v[92:95]
	v_mfma_f32_16x16x32_bf16 v[28:31], v[128:131], v[160:163], v[28:31]
	v_mfma_f32_16x16x32_bf16 v[84:87], v[120:123], v[180:183], v[84:87]
	v_mfma_f32_16x16x32_bf16 v[20:23], v[128:131], v[180:183], v[20:23]
	v_mfma_f32_16x16x32_bf16 v[76:79], v[120:123], v[188:191], v[76:79]
	v_mfma_f32_16x16x32_bf16 v[12:15], v[128:131], v[188:191], v[12:15]
	v_mfma_f32_16x16x32_bf16 v[72:75], v[120:123], v[210:213], v[72:75]
	v_mfma_f32_16x16x32_bf16 v[8:11], v[128:131], v[210:213], v[8:11]
	v_mfma_f32_16x16x32_bf16 v[92:95], v[124:127], v[164:167], v[92:95]
	v_mfma_f32_16x16x32_bf16 v[28:31], v[132:135], v[164:167], v[28:31]
	v_mfma_f32_16x16x32_bf16 v[84:87], v[124:127], v[184:187], v[84:87]
	v_mfma_f32_16x16x32_bf16 v[20:23], v[132:135], v[184:187], v[20:23]
	v_mfma_f32_16x16x32_bf16 v[76:79], v[124:127], v[206:209], v[76:79]
	v_mfma_f32_16x16x32_bf16 v[12:15], v[132:135], v[206:209], v[12:15]
	v_mfma_f32_16x16x32_bf16 v[72:75], v[124:127], v[214:217], v[72:75]
	v_mfma_f32_16x16x32_bf16 v[8:11], v[132:135], v[214:217], v[8:11]
	s_setprio 0
	s_setprio 1
	v_mfma_f32_16x16x32_bf16 v[88:91], v[136:139], v[160:163], v[88:91]
	v_mfma_f32_16x16x32_bf16 v[24:27], v[144:147], v[160:163], v[24:27]
	v_mfma_f32_16x16x32_bf16 v[80:83], v[136:139], v[180:183], v[80:83]
	v_mfma_f32_16x16x32_bf16 v[16:19], v[144:147], v[180:183], v[16:19]
	v_mfma_f32_16x16x32_bf16 v[68:71], v[136:139], v[188:191], v[68:71]
	v_mfma_f32_16x16x32_bf16 v[4:7], v[144:147], v[188:191], v[4:7]
	v_mfma_f32_16x16x32_bf16 v[64:67], v[136:139], v[210:213], v[64:67]
	v_mfma_f32_16x16x32_bf16 v[0:3], v[144:147], v[210:213], v[0:3]
	v_mfma_f32_16x16x32_bf16 v[88:91], v[140:143], v[164:167], v[88:91]
	v_mfma_f32_16x16x32_bf16 v[24:27], v[148:151], v[164:167], v[24:27]
	v_mfma_f32_16x16x32_bf16 v[80:83], v[140:143], v[184:187], v[80:83]
	v_mfma_f32_16x16x32_bf16 v[16:19], v[148:151], v[184:187], v[16:19]
	v_mfma_f32_16x16x32_bf16 v[68:71], v[140:143], v[206:209], v[68:71]
	v_mfma_f32_16x16x32_bf16 v[4:7], v[148:151], v[206:209], v[4:7]
	v_mfma_f32_16x16x32_bf16 v[64:67], v[140:143], v[214:217], v[64:67]
	v_mfma_f32_16x16x32_bf16 v[0:3], v[148:151], v[214:217], v[0:3]
	s_setprio 0
	s_barrier
	s_add_i32 s91, s91, 2
	s_add_u32 s89, s89, 0x100
	s_addc_u32 s90, s90, 0
	s_add_u32 s54, s54, 0x100
	s_addc_u32 s55, s55, 0
	s_cmp_gt_u32 s91, 29
	s_cbranch_scc0 .LBB0_679
	s_and_b64 vcc, exec, s[24:25]
	s_cbranch_vccz .LBB0_682
	s_barrier

; #define PG8_STAGE(bufoff, gbase, voff) do { _Pragma("unroll") for (int _i = 0; _i < 2; ++_i) \
;         __builtin_amdgcn_global_load_lds((const unsigned*)((const char*)(gbase) + (voff)[_i]), (PG8_LAS unsigned*)(lds + (bufoff) + ldsw + _i * 8192), 16, 0, 0); } while (0)
; #define PG8_LDA(dst, b, h) do { _Pragma("unroll") for (int m = 0; m < 4; ++m) _Pragma("unroll") for (int k = 0; k < 2; ++k) dst[m][k] = *(const PG8_LAS bf16x8*)(lds + PG8_SA(b, h) + aoff + m * 2048 + k * 1024); } while (0)
; #define PG8_LDB(dst, b, h) do { _Pragma("unroll") for (int n = 0; n < 2; ++n) _Pragma("unroll") for (int k = 0; k < 2; ++k) dst[n][k] = *(const PG8_LAS bf16x8*)(lds + PG8_SB(b, h) + boff + n * 2048 + k * 1024); } while (0)
; #define PG8_MMA(ai, bj, At, Bt) do { __builtin_amdgcn_s_setprio(1); _Pragma("unroll") for (int m = 0; m < 4; ++m) _Pragma("unroll") for (int n = 0; n < 2; ++n) _Pragma("unroll") for (int k = 0; k < 2; ++k) \
;         acc[ai][bj][m][n] = __builtin_amdgcn_mfma_f32_16x16x32_bf16(Bt[n][k], At[m][k], acc[ai][bj][m][n], 0, 0, 0); __builtin_amdgcn_s_setprio(0); } while (0)
; #define PG8_WAIT_V(n) asm volatile("s_waitcnt vmcnt(" #n ")" ::: "memory")
; #define PG8_WAIT_L(n) asm volatile("s_waitcnt lgkmcnt(" #n ")" ::: "memory")
; template <class Epi, class Sched, bool ALIGN_EPI = false, bool SP2 = false>
; __device__ __forceinline__ void gemm_phase(PG8_LAS unsigned char* lds, const Gemm g, const Sched& S, const Epi& E) {
;     ...
;             const bool last = (t == nt - 2);
;             const char* a1 = cA + (size_t)(t + 1) * kstep;
;             const char* a2 = last ? nA : cA + (size_t)(t + 2) * kstep; const char* b2 = last ? nB : cB + (size_t)(t + 2) * kstep;
;             const char* a3 = a2 + kstep; const char* b3 = b2 + kstep;
;             if (last && has_next) S.a_ready(nxt);
;             if constexpr (SP2) {
;             PG8_LDB(B0, 0, 0); PG8_LDB(B1, 0, 1); PG8_SCHED; PG8_LDA(At, 0, 0); PG8_STAGE(PG8_SA(1, 1), a1 + hstep, voffA);
;             PG8_WAIT_V(8); PG8_WAIT_L(0); PG8_BAR; PG8_MMA(0, 0, At, B0); PG8_MMA(0, 1, At, B1); PG8_BAR; PG8_SCHED;
;             PG8_LDA(At, 0, 1); PG8_STAGE(PG8_SB(0, 0), b2, voffB); PG8_STAGE(PG8_SB(0, 1), b2 + hstep, voffB); PG8_STAGE(PG8_SA(0, 0), a2, voffA);
;             PG8_WAIT_V(8); PG8_WAIT_L(0); PG8_BAR; PG8_MMA(1, 0, At, B0); PG8_MMA(1, 1, At, B1); PG8_BAR; PG8_SCHED;
.LBB0_821:
	ds_read_b128 v[92:95], v214
	ds_read_b128 v[100:103], v214 offset:1024
	ds_read_b128 v[104:107], v214 offset:2048
	ds_read_b128 v[172:175], v214 offset:3072
	ds_read_b128 v[176:179], v215
	ds_read_b128 v[180:183], v215 offset:1024
	ds_read_b128 v[184:187], v215 offset:2048
	ds_read_b128 v[188:191], v215 offset:3072
	s_add_u32 s34, s30, 0x100
	s_addc_u32 s35, s31, 0
	s_add_u32 s36, s64, s30
	s_addc_u32 s37, s65, s31
	s_cmpk_eq_i32 s66, 0x54
	s_cselect_b32 s38, s28, s36
	s_cselect_b32 s36, 0, s34
	s_cselect_b32 s39, s29, s37
	s_cselect_b32 s37, 0, s35
	s_add_u32 s36, s16, s36
	s_addc_u32 s37, s17, s37
	s_mov_b32 m0, s52
	v_lshl_add_u64 v[234:235], v[90:91], 0, s[30:31]
	ds_read_b128 v[192:195], v212
	ds_read_b128 v[196:199], v212 offset:1024
	ds_read_b128 v[200:203], v212 offset:2048
	ds_read_b128 v[204:207], v212 offset:3072
	ds_read_b128 v[208:211], v212 offset:4096
	ds_read_b128 v[222:225], v212 offset:5120
	ds_read_b128 v[226:229], v212 offset:6144
	ds_read_b128 v[230:233], v212 offset:7168
	global_load_lds_dwordx4 v[234:235], off
	v_lshl_add_u64 v[234:235], v[88:89], 0, s[30:31]
	s_mov_b32 m0, s53
	s_nop 0
	global_load_lds_dwordx4 v[234:235], off
	s_sleep 1
	s_waitcnt vmcnt(8)
	s_waitcnt lgkmcnt(0)
	s_barrier
	s_setprio 1
	s_waitcnt lgkmcnt(0)
	v_mfma_f32_16x16x32_bf16 v[140:143], v[92:95], v[192:195], v[140:143]
	v_mfma_f32_16x16x32_bf16 v[136:139], v[104:107], v[192:195], v[136:139]
	v_mfma_f32_16x16x32_bf16 v[124:127], v[92:95], v[200:203], v[124:127]
	v_mfma_f32_16x16x32_bf16 v[120:123], v[104:107], v[200:203], v[120:123]
	v_mfma_f32_16x16x32_bf16 v[108:111], v[92:95], v[208:211], v[108:111]
	v_mfma_f32_16x16x32_bf16 v[96:99], v[104:107], v[208:211], v[96:99]
	v_mfma_f32_16x16x32_bf16 v[76:79], v[92:95], v[226:229], v[76:79]
	v_mfma_f32_16x16x32_bf16 v[72:75], v[104:107], v[226:229], v[72:75]
	v_mfma_f32_16x16x32_bf16 v[140:143], v[100:103], v[196:199], v[140:143]
	v_mfma_f32_16x16x32_bf16 v[136:139], v[172:175], v[196:199], v[136:139]
	v_mfma_f32_16x16x32_bf16 v[124:127], v[100:103], v[204:207], v[124:127]
	v_mfma_f32_16x16x32_bf16 v[120:123], v[172:175], v[204:207], v[120:123]
	v_mfma_f32_16x16x32_bf16 v[108:111], v[100:103], v[222:225], v[108:111]
	v_mfma_f32_16x16x32_bf16 v[96:99], v[172:175], v[222:225], v[96:99]
	v_mfma_f32_16x16x32_bf16 v[76:79], v[100:103], v[230:233], v[76:79]
	v_mfma_f32_16x16x32_bf16 v[72:75], v[172:175], v[230:233], v[72:75]
	s_setprio 0
	s_setprio 1
	v_mfma_f32_16x16x32_bf16 v[132:135], v[176:179], v[192:195], v[132:135]
	v_mfma_f32_16x16x32_bf16 v[128:131], v[184:187], v[192:195], v[128:131]
	v_mfma_f32_16x16x32_bf16 v[116:119], v[176:179], v[200:203], v[116:119]
	v_mfma_f32_16x16x32_bf16 v[112:115], v[184:187], v[200:203], v[112:115]
	v_mfma_f32_16x16x32_bf16 v[84:87], v[176:179], v[208:211], v[84:87]
	v_mfma_f32_16x16x32_bf16 v[80:83], v[184:187], v[208:211], v[80:83]
	v_mfma_f32_16x16x32_bf16 v[68:71], v[176:179], v[226:229], v[68:71]
	v_mfma_f32_16x16x32_bf16 v[64:67], v[184:187], v[226:229], v[64:67]
	v_mfma_f32_16x16x32_bf16 v[132:135], v[180:183], v[196:199], v[132:135]
	v_mfma_f32_16x16x32_bf16 v[128:131], v[188:191], v[196:199], v[128:131]
	v_mfma_f32_16x16x32_bf16 v[116:119], v[180:183], v[204:207], v[116:119]
	v_mfma_f32_16x16x32_bf16 v[112:115], v[188:191], v[204:207], v[112:115]
	v_mfma_f32_16x16x32_bf16 v[84:87], v[180:183], v[222:225], v[84:87]
	v_mfma_f32_16x16x32_bf16 v[80:83], v[188:191], v[222:225], v[80:83]
	v_mfma_f32_16x16x32_bf16 v[68:71], v[180:183], v[230:233], v[68:71]
	v_mfma_f32_16x16x32_bf16 v[64:67], v[188:191], v[230:233], v[64:67]
	s_setprio 0
	s_barrier
	s_mov_b32 m0, s54
	v_lshl_add_u64 v[234:235], s[36:37], 0, v[146:147]
	s_add_u32 s30, s36, 0x160000
	ds_read_b128 v[192:195], v212 offset:16384
	ds_read_b128 v[196:199], v212 offset:17408
	ds_read_b128 v[200:203], v212 offset:18432
	ds_read_b128 v[204:207], v212 offset:19456
	ds_read_b128 v[208:211], v212 offset:20480
	ds_read_b128 v[222:225], v212 offset:21504
	ds_read_b128 v[226:229], v212 offset:22528
	ds_read_b128 v[230:233], v212 offset:23552
	global_load_lds_dwordx4 v[234:235], off
	v_lshl_add_u64 v[236:237], s[36:37], 0, v[144:145]
	s_mov_b32 m0, s55
	s_addc_u32 s31, s37, 0
	global_load_lds_dwordx4 v[236:237], off
	v_lshl_add_u64 v[238:239], s[30:31], 0, v[146:147]
	s_mov_b32 m0, s58
	v_lshl_add_u64 v[240:241], s[38:39], 0, v[144:145]
	global_load_lds_dwordx4 v[238:239], off
	v_lshl_add_u64 v[238:239], s[30:31], 0, v[144:145]
	s_mov_b32 m0, s59
	s_nop 0
	global_load_lds_dwordx4 v[238:239], off
	v_lshl_add_u64 v[238:239], s[38:39], 0, v[146:147]
	s_mov_b32 m0, s44
	s_nop 0
	global_load_lds_dwordx4 v[238:239], off
	s_mov_b32 m0, s45
	s_nop 0
	global_load_lds_dwordx4 v[240:241], off
	s_sleep 1
	s_waitcnt vmcnt(8)
	s_waitcnt lgkmcnt(0)
	s_barrier
; #define PG8_STAGE(bufoff, gbase, voff) do { _Pragma("unroll") for (int _i = 0; _i < 2; ++_i) \
;         __builtin_amdgcn_global_load_lds((const unsigned*)((const char*)(gbase) + (voff)[_i]), (PG8_LAS unsigned*)(lds + (bufoff) + ldsw + _i * 8192), 16, 0, 0); } while (0)
; #define PG8_LDA(dst, b, h) do { _Pragma("unroll") for (int m = 0; m < 4; ++m) _Pragma("unroll") for (int k = 0; k < 2; ++k) dst[m][k] = *(const PG8_LAS bf16x8*)(lds + PG8_SA(b, h) + aoff + m * 2048 + k * 1024); } while (0)
; #define PG8_LDB(dst, b, h) do { _Pragma("unroll") for (int n = 0; n < 2; ++n) _Pragma("unroll") for (int k = 0; k < 2; ++k) dst[n][k] = *(const PG8_LAS bf16x8*)(lds + PG8_SB(b, h) + boff + n * 2048 + k * 1024); } while (0)
; #define PG8_MMA(ai, bj, At, Bt) do { __builtin_amdgcn_s_setprio(1); _Pragma("unroll") for (int m = 0; m < 4; ++m) _Pragma("unroll") for (int n = 0; n < 2; ++n) _Pragma("unroll") for (int k = 0; k < 2; ++k) \
;         acc[ai][bj][m][n] = __builtin_amdgcn_mfma_f32_16x16x32_bf16(Bt[n][k], At[m][k], acc[ai][bj][m][n], 0, 0, 0); __builtin_amdgcn_s_setprio(0); } while (0)
; #define PG8_WAIT_V(n) asm volatile("s_waitcnt vmcnt(" #n ")" ::: "memory")
; #define PG8_WAIT_L(n) asm volatile("s_waitcnt lgkmcnt(" #n ")" ::: "memory")
; #define PG8_BAR __builtin_amdgcn_s_barrier()
; #define PG8_SCHED __builtin_amdgcn_sched_barrier(0)
; template <class Epi, class Sched, bool ALIGN_EPI = false, bool SP2 = false>
; __device__ __forceinline__ void gemm_phase(PG8_LAS unsigned char* lds, const Gemm g, const Sched& S, const Epi& E) {
;     ...
;             PG8_WAIT_V(8); PG8_WAIT_L(0); PG8_BAR; PG8_MMA(1, 0, At, B0); PG8_MMA(1, 1, At, B1); PG8_BAR; PG8_SCHED;
;             PG8_LDB(B0, 1, 0); PG8_LDB(B1, 1, 1); PG8_SCHED; PG8_LDA(At, 1, 0); PG8_STAGE(PG8_SA(0, 1), a2 + hstep, voffA);
;             PG8_WAIT_V(8); PG8_WAIT_L(0); PG8_BAR; PG8_MMA(0, 0, At, B0); PG8_MMA(0, 1, At, B1); PG8_BAR; PG8_SCHED;
	s_setprio 1
	s_waitcnt lgkmcnt(0)
	v_mfma_f32_16x16x32_bf16 v[60:63], v[92:95], v[192:195], v[60:63]
	v_mfma_f32_16x16x32_bf16 v[56:59], v[104:107], v[192:195], v[56:59]
	v_mfma_f32_16x16x32_bf16 v[44:47], v[92:95], v[200:203], v[44:47]
	v_mfma_f32_16x16x32_bf16 v[40:43], v[104:107], v[200:203], v[40:43]
	v_mfma_f32_16x16x32_bf16 v[28:31], v[92:95], v[208:211], v[28:31]
	v_mfma_f32_16x16x32_bf16 v[24:27], v[104:107], v[208:211], v[24:27]
	v_mfma_f32_16x16x32_bf16 v[12:15], v[92:95], v[226:229], v[12:15]
	v_mfma_f32_16x16x32_bf16 v[8:11], v[104:107], v[226:229], v[8:11]
	v_mfma_f32_16x16x32_bf16 v[60:63], v[100:103], v[196:199], v[60:63]
	v_mfma_f32_16x16x32_bf16 v[56:59], v[172:175], v[196:199], v[56:59]
	v_mfma_f32_16x16x32_bf16 v[44:47], v[100:103], v[204:207], v[44:47]
	v_mfma_f32_16x16x32_bf16 v[40:43], v[172:175], v[204:207], v[40:43]
	v_mfma_f32_16x16x32_bf16 v[28:31], v[100:103], v[222:225], v[28:31]
	v_mfma_f32_16x16x32_bf16 v[24:27], v[172:175], v[222:225], v[24:27]
	v_mfma_f32_16x16x32_bf16 v[12:15], v[100:103], v[230:233], v[12:15]
	v_mfma_f32_16x16x32_bf16 v[8:11], v[172:175], v[230:233], v[8:11]
	s_setprio 0
	s_setprio 1
	v_mfma_f32_16x16x32_bf16 v[52:55], v[176:179], v[192:195], v[52:55]
	v_mfma_f32_16x16x32_bf16 v[48:51], v[184:187], v[192:195], v[48:51]
	v_mfma_f32_16x16x32_bf16 v[36:39], v[176:179], v[200:203], v[36:39]
	v_mfma_f32_16x16x32_bf16 v[32:35], v[184:187], v[200:203], v[32:35]
	v_mfma_f32_16x16x32_bf16 v[20:23], v[176:179], v[208:211], v[20:23]
	v_mfma_f32_16x16x32_bf16 v[16:19], v[184:187], v[208:211], v[16:19]
	v_mfma_f32_16x16x32_bf16 v[4:7], v[176:179], v[226:229], v[4:7]
	v_mfma_f32_16x16x32_bf16 v[0:3], v[184:187], v[226:229], v[0:3]
	v_mfma_f32_16x16x32_bf16 v[52:55], v[180:183], v[196:199], v[52:55]
	v_mfma_f32_16x16x32_bf16 v[48:51], v[188:191], v[196:199], v[48:51]
	v_mfma_f32_16x16x32_bf16 v[36:39], v[180:183], v[204:207], v[36:39]
	v_mfma_f32_16x16x32_bf16 v[32:35], v[188:191], v[204:207], v[32:35]
	v_mfma_f32_16x16x32_bf16 v[20:23], v[180:183], v[222:225], v[20:23]
	v_mfma_f32_16x16x32_bf16 v[16:19], v[188:191], v[222:225], v[16:19]
	v_mfma_f32_16x16x32_bf16 v[4:7], v[180:183], v[230:233], v[4:7]
	v_mfma_f32_16x16x32_bf16 v[0:3], v[188:191], v[230:233], v[0:3]
	s_setprio 0
	s_barrier
	ds_read_b128 v[92:95], v216
	ds_read_b128 v[100:103], v216 offset:1024
	ds_read_b128 v[104:107], v216 offset:2048
	ds_read_b128 v[172:175], v216 offset:3072
	ds_read_b128 v[176:179], v217
	ds_read_b128 v[180:183], v217 offset:1024
	ds_read_b128 v[184:187], v217 offset:2048
	ds_read_b128 v[188:191], v217 offset:3072
	s_add_u32 s30, s38, 0x160000
	s_addc_u32 s31, s39, 0
	s_mov_b32 m0, s46
	v_lshl_add_u64 v[242:243], s[30:31], 0, v[146:147]
	ds_read_b128 v[192:195], v212 offset:32768
	ds_read_b128 v[196:199], v212 offset:33792
	ds_read_b128 v[200:203], v212 offset:34816
	ds_read_b128 v[204:207], v212 offset:35840
	ds_read_b128 v[208:211], v212 offset:36864
	ds_read_b128 v[222:225], v212 offset:37888
	ds_read_b128 v[226:229], v212 offset:38912
	ds_read_b128 v[230:233], v212 offset:39936
	global_load_lds_dwordx4 v[242:243], off
	v_lshl_add_u64 v[242:243], s[30:31], 0, v[144:145]
	s_mov_b32 m0, s47
	s_nop 0
	global_load_lds_dwordx4 v[242:243], off
	s_sleep 1
	s_waitcnt vmcnt(8)
	s_waitcnt lgkmcnt(0)
	s_barrier
	s_setprio 1
	s_waitcnt lgkmcnt(0)
	v_mfma_f32_16x16x32_bf16 v[140:143], v[92:95], v[192:195], v[140:143]
	v_mfma_f32_16x16x32_bf16 v[136:139], v[104:107], v[192:195], v[136:139]
	v_mfma_f32_16x16x32_bf16 v[124:127], v[92:95], v[200:203], v[124:127]
	v_mfma_f32_16x16x32_bf16 v[120:123], v[104:107], v[200:203], v[120:123]
	v_mfma_f32_16x16x32_bf16 v[108:111], v[92:95], v[208:211], v[108:111]
	v_mfma_f32_16x16x32_bf16 v[96:99], v[104:107], v[208:211], v[96:99]
	v_mfma_f32_16x16x32_bf16 v[76:79], v[92:95], v[226:229], v[76:79]
	v_mfma_f32_16x16x32_bf16 v[72:75], v[104:107], v[226:229], v[72:75]
	v_mfma_f32_16x16x32_bf16 v[140:143], v[100:103], v[196:199], v[140:143]
	v_mfma_f32_16x16x32_bf16 v[136:139], v[172:175], v[196:199], v[136:139]
	v_mfma_f32_16x16x32_bf16 v[124:127], v[100:103], v[204:207], v[124:127]
	v_mfma_f32_16x16x32_bf16 v[120:123], v[172:175], v[204:207], v[120:123]
	v_mfma_f32_16x16x32_bf16 v[108:111], v[100:103], v[222:225], v[108:111]
	v_mfma_f32_16x16x32_bf16 v[96:99], v[172:175], v[222:225], v[96:99]
	v_mfma_f32_16x16x32_bf16 v[76:79], v[100:103], v[230:233], v[76:79]
	v_mfma_f32_16x16x32_bf16 v[72:75], v[172:175], v[230:233], v[72:75]
	s_setprio 0
	s_setprio 1
	v_mfma_f32_16x16x32_bf16 v[132:135], v[176:179], v[192:195], v[132:135]
	v_mfma_f32_16x16x32_bf16 v[128:131], v[184:187], v[192:195], v[128:131]
	v_mfma_f32_16x16x32_bf16 v[116:119], v[176:179], v[200:203], v[116:119]
	v_mfma_f32_16x16x32_bf16 v[112:115], v[184:187], v[200:203], v[112:115]
	v_mfma_f32_16x16x32_bf16 v[84:87], v[176:179], v[208:211], v[84:87]
	v_mfma_f32_16x16x32_bf16 v[80:83], v[184:187], v[208:211], v[80:83]
	v_mfma_f32_16x16x32_bf16 v[68:71], v[176:179], v[226:229], v[68:71]
	v_mfma_f32_16x16x32_bf16 v[64:67], v[184:187], v[226:229], v[64:67]
	v_mfma_f32_16x16x32_bf16 v[132:135], v[180:183], v[196:199], v[132:135]
	v_mfma_f32_16x16x32_bf16 v[128:131], v[188:191], v[196:199], v[128:131]
	v_mfma_f32_16x16x32_bf16 v[116:119], v[180:183], v[204:207], v[116:119]
	v_mfma_f32_16x16x32_bf16 v[112:115], v[188:191], v[204:207], v[112:115]
	v_mfma_f32_16x16x32_bf16 v[84:87], v[180:183], v[222:225], v[84:87]
	v_mfma_f32_16x16x32_bf16 v[80:83], v[188:191], v[222:225], v[80:83]
	v_mfma_f32_16x16x32_bf16 v[68:71], v[180:183], v[230:233], v[68:71]
	v_mfma_f32_16x16x32_bf16 v[64:67], v[188:191], v[230:233], v[64:67]
	s_setprio 0
	s_barrier
; #define PG8_STAGE(bufoff, gbase, voff) do { _Pragma("unroll") for (int _i = 0; _i < 2; ++_i) \
;         __builtin_amdgcn_global_load_lds((const unsigned*)((const char*)(gbase) + (voff)[_i]), (PG8_LAS unsigned*)(lds + (bufoff) + ldsw + _i * 8192), 16, 0, 0); } while (0)
; #define PG8_LDA(dst, b, h) do { _Pragma("unroll") for (int m = 0; m < 4; ++m) _Pragma("unroll") for (int k = 0; k < 2; ++k) dst[m][k] = *(const PG8_LAS bf16x8*)(lds + PG8_SA(b, h) + aoff + m * 2048 + k * 1024); } while (0)
; #define PG8_MMA(ai, bj, At, Bt) do { __builtin_amdgcn_s_setprio(1); _Pragma("unroll") for (int m = 0; m < 4; ++m) _Pragma("unroll") for (int n = 0; n < 2; ++n) _Pragma("unroll") for (int k = 0; k < 2; ++k) \
;         acc[ai][bj][m][n] = __builtin_amdgcn_mfma_f32_16x16x32_bf16(Bt[n][k], At[m][k], acc[ai][bj][m][n], 0, 0, 0); __builtin_amdgcn_s_setprio(0); } while (0)
; #define PG8_WAIT_V(n) asm volatile("s_waitcnt vmcnt(" #n ")" ::: "memory")
; #define PG8_WAIT_L(n) asm volatile("s_waitcnt lgkmcnt(" #n ")" ::: "memory")
; #define PG8_BAR __builtin_amdgcn_s_barrier()
; #define PG8_SCHED __builtin_amdgcn_sched_barrier(0)
; template <class Epi, class Sched, bool ALIGN_EPI = false, bool SP2 = false>
; __device__ __forceinline__ void gemm_phase(PG8_LAS unsigned char* lds, const Gemm g, const Sched& S, const Epi& E) {
;     ...
;             PG8_LDA(At, 1, 1); PG8_STAGE(PG8_SB(1, 0), b3, voffB); PG8_STAGE(PG8_SB(1, 1), b3 + hstep, voffB); PG8_STAGE(PG8_SA(1, 0), a3, voffA);
;             PG8_WAIT_V(8); PG8_WAIT_L(0); PG8_BAR; PG8_MMA(1, 0, At, B0); PG8_MMA(1, 1, At, B1); PG8_BAR; PG8_SCHED;
;     ...
;         if constexpr (ALIGN_EPI) { if (wr == 0) PG8_BAR; }
	s_mov_b32 m0, s61
	v_lshl_add_u64 v[234:235], v[234:235], 0, s[26:27]
	ds_read_b128 v[192:195], v212 offset:49152
	ds_read_b128 v[196:199], v212 offset:50176
	ds_read_b128 v[200:203], v212 offset:51200
	ds_read_b128 v[204:207], v212 offset:52224
	ds_read_b128 v[208:211], v212 offset:53248
	ds_read_b128 v[222:225], v212 offset:54272
	ds_read_b128 v[226:229], v212 offset:55296
	ds_read_b128 v[230:233], v212 offset:56320
	global_load_lds_dwordx4 v[234:235], off
	s_add_i32 m0, s61, 0x2000
	s_add_u32 s30, s36, 0x160080
	v_lshl_add_u64 v[234:235], v[236:237], 0, s[26:27]
	s_addc_u32 s31, s37, 0
	s_add_i32 s36, s60, s42
	global_load_lds_dwordx4 v[234:235], off
	v_lshl_add_u64 v[234:235], s[30:31], 0, v[146:147]
	s_mov_b32 m0, s36
	s_nop 0
	global_load_lds_dwordx4 v[234:235], off
	v_lshl_add_u64 v[234:235], s[30:31], 0, v[144:145]
	s_add_i32 m0, s36, 0x2000
	s_nop 0
	global_load_lds_dwordx4 v[234:235], off
	v_lshl_add_u64 v[234:235], v[238:239], 0, s[26:27]
	s_mov_b32 m0, s50
	s_nop 0
	global_load_lds_dwordx4 v[234:235], off
	v_lshl_add_u64 v[234:235], v[240:241], 0, s[26:27]
	s_mov_b32 m0, s51
	s_nop 0
	global_load_lds_dwordx4 v[234:235], off
	s_sleep 1
	s_waitcnt vmcnt(8)
	s_waitcnt lgkmcnt(0)
	s_barrier
	s_setprio 1
	s_waitcnt lgkmcnt(0)
	v_mfma_f32_16x16x32_bf16 v[60:63], v[92:95], v[192:195], v[60:63]
	v_mfma_f32_16x16x32_bf16 v[56:59], v[104:107], v[192:195], v[56:59]
	v_mfma_f32_16x16x32_bf16 v[44:47], v[92:95], v[200:203], v[44:47]
	v_mfma_f32_16x16x32_bf16 v[40:43], v[104:107], v[200:203], v[40:43]
	v_mfma_f32_16x16x32_bf16 v[28:31], v[92:95], v[208:211], v[28:31]
	v_mfma_f32_16x16x32_bf16 v[24:27], v[104:107], v[208:211], v[24:27]
	v_mfma_f32_16x16x32_bf16 v[12:15], v[92:95], v[226:229], v[12:15]
	v_mfma_f32_16x16x32_bf16 v[8:11], v[104:107], v[226:229], v[8:11]
	v_mfma_f32_16x16x32_bf16 v[60:63], v[100:103], v[196:199], v[60:63]
	v_mfma_f32_16x16x32_bf16 v[56:59], v[172:175], v[196:199], v[56:59]
	v_mfma_f32_16x16x32_bf16 v[44:47], v[100:103], v[204:207], v[44:47]
	v_mfma_f32_16x16x32_bf16 v[40:43], v[172:175], v[204:207], v[40:43]
	v_mfma_f32_16x16x32_bf16 v[28:31], v[100:103], v[222:225], v[28:31]
	v_mfma_f32_16x16x32_bf16 v[24:27], v[172:175], v[222:225], v[24:27]
	v_mfma_f32_16x16x32_bf16 v[12:15], v[100:103], v[230:233], v[12:15]
	v_mfma_f32_16x16x32_bf16 v[8:11], v[172:175], v[230:233], v[8:11]
	s_setprio 0
	s_setprio 1
	v_mfma_f32_16x16x32_bf16 v[52:55], v[176:179], v[192:195], v[52:55]
	v_mfma_f32_16x16x32_bf16 v[48:51], v[184:187], v[192:195], v[48:51]
	v_mfma_f32_16x16x32_bf16 v[36:39], v[176:179], v[200:203], v[36:39]
	v_mfma_f32_16x16x32_bf16 v[32:35], v[184:187], v[200:203], v[32:35]
	v_mfma_f32_16x16x32_bf16 v[20:23], v[176:179], v[208:211], v[20:23]
	v_mfma_f32_16x16x32_bf16 v[16:19], v[184:187], v[208:211], v[16:19]
	v_mfma_f32_16x16x32_bf16 v[4:7], v[176:179], v[226:229], v[4:7]
	v_mfma_f32_16x16x32_bf16 v[0:3], v[184:187], v[226:229], v[0:3]
	v_mfma_f32_16x16x32_bf16 v[52:55], v[180:183], v[196:199], v[52:55]
	v_mfma_f32_16x16x32_bf16 v[48:51], v[188:191], v[196:199], v[48:51]
	v_mfma_f32_16x16x32_bf16 v[36:39], v[180:183], v[204:207], v[36:39]
	v_mfma_f32_16x16x32_bf16 v[32:35], v[188:191], v[204:207], v[32:35]
	v_mfma_f32_16x16x32_bf16 v[20:23], v[180:183], v[222:225], v[20:23]
	v_mfma_f32_16x16x32_bf16 v[16:19], v[188:191], v[222:225], v[16:19]
	v_mfma_f32_16x16x32_bf16 v[4:7], v[180:183], v[230:233], v[4:7]
	v_mfma_f32_16x16x32_bf16 v[0:3], v[188:191], v[230:233], v[0:3]
	s_setprio 0
	s_barrier
	s_add_i32 s66, s66, 2
	s_cmpk_gt_u32 s66, 0x55
	s_mov_b64 s[30:31], s[34:35]
	s_cbranch_scc0 .LBB0_821
	s_and_b64 vcc, exec, s[4:5]
	s_cbranch_vccz .LBB0_824
	s_barrier

; #define PG8_STAGE(bufoff, gbase, voff) do { _Pragma("unroll") for (int _i = 0; _i < 2; ++_i) \
;         __builtin_amdgcn_global_load_lds((const unsigned*)((const char*)(gbase) + (voff)[_i]), (PG8_LAS unsigned*)(lds + (bufoff) + ldsw + _i * 8192), 16, 0, 0); } while (0)
; #define PG8_LDA(dst, b, h) do { _Pragma("unroll") for (int m = 0; m < 4; ++m) _Pragma("unroll") for (int k = 0; k < 2; ++k) dst[m][k] = *(const PG8_LAS bf16x8*)(lds + PG8_SA(b, h) + aoff + m * 2048 + k * 1024); } while (0)
; #define PG8_LDB(dst, b, h) do { _Pragma("unroll") for (int n = 0; n < 2; ++n) _Pragma("unroll") for (int k = 0; k < 2; ++k) dst[n][k] = *(const PG8_LAS bf16x8*)(lds + PG8_SB(b, h) + boff + n * 2048 + k * 1024); } while (0)
; #define PG8_MMA(ai, bj, At, Bt) do { __builtin_amdgcn_s_setprio(1); _Pragma("unroll") for (int m = 0; m < 4; ++m) _Pragma("unroll") for (int n = 0; n < 2; ++n) _Pragma("unroll") for (int k = 0; k < 2; ++k) \
;         acc[ai][bj][m][n] = __builtin_amdgcn_mfma_f32_16x16x32_bf16(Bt[n][k], At[m][k], acc[ai][bj][m][n], 0, 0, 0); __builtin_amdgcn_s_setprio(0); } while (0)
; #define PG8_WAIT_V(n) asm volatile("s_waitcnt vmcnt(" #n ")" ::: "memory")
; #define PG8_WAIT_L(n) asm volatile("s_waitcnt lgkmcnt(" #n ")" ::: "memory")
; template <class Epi, class Sched, bool ALIGN_EPI = false, bool SP2 = false>
; __device__ __forceinline__ void gemm_phase(PG8_LAS unsigned char* lds, const Gemm g, const Sched& S, const Epi& E) {
;     ...
;             const bool last = (t == nt - 2);
;             const char* a1 = cA + (size_t)(t + 1) * kstep;
;             const char* a2 = last ? nA : cA + (size_t)(t + 2) * kstep; const char* b2 = last ? nB : cB + (size_t)(t + 2) * kstep;
;             const char* a3 = a2 + kstep; const char* b3 = b2 + kstep;
;             if (last && has_next) S.a_ready(nxt);
;             if constexpr (SP2) {
;             PG8_LDB(B0, 0, 0); PG8_LDB(B1, 0, 1); PG8_SCHED; PG8_LDA(At, 0, 0); PG8_STAGE(PG8_SA(1, 1), a1 + hstep, voffA);
;             PG8_WAIT_V(8); PG8_WAIT_L(0); PG8_BAR; PG8_MMA(0, 0, At, B0); PG8_MMA(0, 1, At, B1); PG8_BAR; PG8_SCHED;
;             PG8_LDA(At, 0, 1); PG8_STAGE(PG8_SB(0, 0), b2, voffB); PG8_STAGE(PG8_SB(0, 1), b2 + hstep, voffB); PG8_STAGE(PG8_SA(0, 0), a2, voffA);
;             PG8_WAIT_V(8); PG8_WAIT_L(0); PG8_BAR; PG8_MMA(1, 0, At, B0); PG8_MMA(1, 1, At, B1); PG8_BAR; PG8_SCHED;
.LBB0_877:
	ds_read_b128 v[128:131], v165
	ds_read_b128 v[132:135], v165 offset:1024
	ds_read_b128 v[136:139], v165 offset:2048
	ds_read_b128 v[140:143], v165 offset:3072
	ds_read_b128 v[156:159], v166
	ds_read_b128 v[168:171], v166 offset:1024
	ds_read_b128 v[172:175], v166 offset:2048
	ds_read_b128 v[176:179], v166 offset:3072
	s_add_u32 s22, s20, 0x100
	s_addc_u32 s23, s21, 0
	s_cmpk_eq_i32 s53, 0x54
	s_cselect_b32 s27, s9, s23
	s_cselect_b32 s26, s8, s22
	s_cselect_b32 s25, s19, s52
	s_cselect_b32 s24, s18, s51
	v_lshl_add_u64 v[160:161], s[20:21], 0, v[150:151]
	s_add_i32 m0, s35, 0xc000
	ds_read_b128 v[180:183], v167
	ds_read_b128 v[184:187], v167 offset:1024
	ds_read_b128 v[188:191], v167 offset:2048
	ds_read_b128 v[192:195], v167 offset:3072
	ds_read_b128 v[196:199], v167 offset:4096
	ds_read_b128 v[200:203], v167 offset:5120
	ds_read_b128 v[204:207], v167 offset:6144
	ds_read_b128 v[208:211], v167 offset:7168
	global_load_lds_dwordx4 v[160:161], off
	v_lshl_add_u64 v[160:161], s[20:21], 0, v[148:149]
	s_add_i32 m0, s35, 0xe000
	s_nop 0
	global_load_lds_dwordx4 v[160:161], off
	s_sleep 1
	s_waitcnt vmcnt(8)
	s_waitcnt lgkmcnt(0)
	s_barrier
	s_setprio 1
	s_waitcnt lgkmcnt(0)
	v_mfma_f32_16x16x32_bf16 v[124:127], v[128:131], v[180:183], v[124:127]
	v_mfma_f32_16x16x32_bf16 v[120:123], v[136:139], v[180:183], v[120:123]
	v_mfma_f32_16x16x32_bf16 v[116:119], v[128:131], v[188:191], v[116:119]
	v_mfma_f32_16x16x32_bf16 v[112:115], v[136:139], v[188:191], v[112:115]
	v_mfma_f32_16x16x32_bf16 v[92:95], v[128:131], v[196:199], v[92:95]
	v_mfma_f32_16x16x32_bf16 v[88:91], v[136:139], v[196:199], v[88:91]
	v_mfma_f32_16x16x32_bf16 v[84:87], v[128:131], v[204:207], v[84:87]
	v_mfma_f32_16x16x32_bf16 v[80:83], v[136:139], v[204:207], v[80:83]
	v_mfma_f32_16x16x32_bf16 v[124:127], v[132:135], v[184:187], v[124:127]
	v_mfma_f32_16x16x32_bf16 v[120:123], v[140:143], v[184:187], v[120:123]
	v_mfma_f32_16x16x32_bf16 v[116:119], v[132:135], v[192:195], v[116:119]
	v_mfma_f32_16x16x32_bf16 v[112:115], v[140:143], v[192:195], v[112:115]
	v_mfma_f32_16x16x32_bf16 v[92:95], v[132:135], v[200:203], v[92:95]
	v_mfma_f32_16x16x32_bf16 v[88:91], v[140:143], v[200:203], v[88:91]
	v_mfma_f32_16x16x32_bf16 v[84:87], v[132:135], v[208:211], v[84:87]
	v_mfma_f32_16x16x32_bf16 v[80:83], v[140:143], v[208:211], v[80:83]
	s_setprio 0
	s_setprio 1
	v_mfma_f32_16x16x32_bf16 v[108:111], v[156:159], v[180:183], v[108:111]
	v_mfma_f32_16x16x32_bf16 v[104:107], v[172:175], v[180:183], v[104:107]
	v_mfma_f32_16x16x32_bf16 v[100:103], v[156:159], v[188:191], v[100:103]
	v_mfma_f32_16x16x32_bf16 v[96:99], v[172:175], v[188:191], v[96:99]
	v_mfma_f32_16x16x32_bf16 v[76:79], v[156:159], v[196:199], v[76:79]
	v_mfma_f32_16x16x32_bf16 v[72:75], v[172:175], v[196:199], v[72:75]
	v_mfma_f32_16x16x32_bf16 v[68:71], v[156:159], v[204:207], v[68:71]
	v_mfma_f32_16x16x32_bf16 v[64:67], v[172:175], v[204:207], v[64:67]
	v_mfma_f32_16x16x32_bf16 v[108:111], v[168:171], v[184:187], v[108:111]
	v_mfma_f32_16x16x32_bf16 v[104:107], v[176:179], v[184:187], v[104:107]
	v_mfma_f32_16x16x32_bf16 v[100:103], v[168:171], v[192:195], v[100:103]
	v_mfma_f32_16x16x32_bf16 v[96:99], v[176:179], v[192:195], v[96:99]
	v_mfma_f32_16x16x32_bf16 v[76:79], v[168:171], v[200:203], v[76:79]
	v_mfma_f32_16x16x32_bf16 v[72:75], v[176:179], v[200:203], v[72:75]
	v_mfma_f32_16x16x32_bf16 v[68:71], v[168:171], v[208:211], v[68:71]
	v_mfma_f32_16x16x32_bf16 v[64:67], v[176:179], v[208:211], v[64:67]
	s_setprio 0
	s_barrier
	s_add_i32 s20, s44, s34
	v_lshl_add_u64 v[160:161], s[24:25], 0, v[144:145]
	s_mov_b32 m0, s20
	ds_read_b128 v[180:183], v167 offset:16384
	ds_read_b128 v[184:187], v167 offset:17408
	ds_read_b128 v[188:191], v167 offset:18432
	ds_read_b128 v[192:195], v167 offset:19456
	ds_read_b128 v[196:199], v167 offset:20480
	ds_read_b128 v[200:203], v167 offset:21504
	ds_read_b128 v[204:207], v167 offset:22528
	ds_read_b128 v[208:211], v167 offset:23552
	global_load_lds_dwordx4 v[160:161], off
	s_add_i32 m0, s20, 0x2000
	s_add_u32 s20, s24, 0x160000
	v_lshl_add_u64 v[212:213], s[24:25], 0, v[146:147]
	s_addc_u32 s21, s25, 0
	s_add_i32 s54, s45, s34
	global_load_lds_dwordx4 v[212:213], off
	v_lshl_add_u64 v[214:215], s[20:21], 0, v[144:145]
	s_mov_b32 m0, s54
	v_lshl_add_u64 v[216:217], s[26:27], 0, v[146:147]
	global_load_lds_dwordx4 v[214:215], off
	v_lshl_add_u64 v[214:215], s[20:21], 0, v[146:147]
	s_add_i32 m0, s54, 0x2000
	s_nop 0
	global_load_lds_dwordx4 v[214:215], off
	v_lshl_add_u64 v[214:215], s[26:27], 0, v[144:145]
	s_mov_b32 m0, s35
	s_nop 0
	global_load_lds_dwordx4 v[214:215], off
	s_mov_b32 m0, s36
	s_nop 0
	global_load_lds_dwordx4 v[216:217], off
	s_sleep 1
	s_waitcnt vmcnt(8)
	s_waitcnt lgkmcnt(0)
	s_barrier
; #define PG8_STAGE(bufoff, gbase, voff) do { _Pragma("unroll") for (int _i = 0; _i < 2; ++_i) \
;         __builtin_amdgcn_global_load_lds((const unsigned*)((const char*)(gbase) + (voff)[_i]), (PG8_LAS unsigned*)(lds + (bufoff) + ldsw + _i * 8192), 16, 0, 0); } while (0)
; #define PG8_LDA(dst, b, h) do { _Pragma("unroll") for (int m = 0; m < 4; ++m) _Pragma("unroll") for (int k = 0; k < 2; ++k) dst[m][k] = *(const PG8_LAS bf16x8*)(lds + PG8_SA(b, h) + aoff + m * 2048 + k * 1024); } while (0)
; #define PG8_LDB(dst, b, h) do { _Pragma("unroll") for (int n = 0; n < 2; ++n) _Pragma("unroll") for (int k = 0; k < 2; ++k) dst[n][k] = *(const PG8_LAS bf16x8*)(lds + PG8_SB(b, h) + boff + n * 2048 + k * 1024); } while (0)
; #define PG8_MMA(ai, bj, At, Bt) do { __builtin_amdgcn_s_setprio(1); _Pragma("unroll") for (int m = 0; m < 4; ++m) _Pragma("unroll") for (int n = 0; n < 2; ++n) _Pragma("unroll") for (int k = 0; k < 2; ++k) \
;         acc[ai][bj][m][n] = __builtin_amdgcn_mfma_f32_16x16x32_bf16(Bt[n][k], At[m][k], acc[ai][bj][m][n], 0, 0, 0); __builtin_amdgcn_s_setprio(0); } while (0)
; #define PG8_WAIT_V(n) asm volatile("s_waitcnt vmcnt(" #n ")" ::: "memory")
; #define PG8_WAIT_L(n) asm volatile("s_waitcnt lgkmcnt(" #n ")" ::: "memory")
; #define PG8_BAR __builtin_amdgcn_s_barrier()
; #define PG8_SCHED __builtin_amdgcn_sched_barrier(0)
; template <class Epi, class Sched, bool ALIGN_EPI = false, bool SP2 = false>
; __device__ __forceinline__ void gemm_phase(PG8_LAS unsigned char* lds, const Gemm g, const Sched& S, const Epi& E) {
;     ...
;             PG8_WAIT_V(8); PG8_WAIT_L(0); PG8_BAR; PG8_MMA(1, 0, At, B0); PG8_MMA(1, 1, At, B1); PG8_BAR; PG8_SCHED;
;             PG8_LDB(B0, 1, 0); PG8_LDB(B1, 1, 1); PG8_SCHED; PG8_LDA(At, 1, 0); PG8_STAGE(PG8_SA(0, 1), a2 + hstep, voffA);
;             PG8_WAIT_V(8); PG8_WAIT_L(0); PG8_BAR; PG8_MMA(0, 0, At, B0); PG8_MMA(0, 1, At, B1); PG8_BAR; PG8_SCHED;
	s_setprio 1
	s_waitcnt lgkmcnt(0)
	v_mfma_f32_16x16x32_bf16 v[60:63], v[128:131], v[180:183], v[60:63]
	v_mfma_f32_16x16x32_bf16 v[56:59], v[136:139], v[180:183], v[56:59]
	v_mfma_f32_16x16x32_bf16 v[52:55], v[128:131], v[188:191], v[52:55]
	v_mfma_f32_16x16x32_bf16 v[48:51], v[136:139], v[188:191], v[48:51]
	v_mfma_f32_16x16x32_bf16 v[36:39], v[128:131], v[196:199], v[36:39]
	v_mfma_f32_16x16x32_bf16 v[24:27], v[136:139], v[196:199], v[24:27]
	v_mfma_f32_16x16x32_bf16 v[16:19], v[128:131], v[204:207], v[16:19]
	v_mfma_f32_16x16x32_bf16 v[8:11], v[136:139], v[204:207], v[8:11]
	v_mfma_f32_16x16x32_bf16 v[60:63], v[132:135], v[184:187], v[60:63]
	v_mfma_f32_16x16x32_bf16 v[56:59], v[140:143], v[184:187], v[56:59]
	v_mfma_f32_16x16x32_bf16 v[52:55], v[132:135], v[192:195], v[52:55]
	v_mfma_f32_16x16x32_bf16 v[48:51], v[140:143], v[192:195], v[48:51]
	v_mfma_f32_16x16x32_bf16 v[36:39], v[132:135], v[200:203], v[36:39]
	v_mfma_f32_16x16x32_bf16 v[24:27], v[140:143], v[200:203], v[24:27]
	v_mfma_f32_16x16x32_bf16 v[16:19], v[132:135], v[208:211], v[16:19]
	v_mfma_f32_16x16x32_bf16 v[8:11], v[140:143], v[208:211], v[8:11]
	s_setprio 0
	s_setprio 1
	v_mfma_f32_16x16x32_bf16 v[44:47], v[156:159], v[180:183], v[44:47]
	v_mfma_f32_16x16x32_bf16 v[40:43], v[172:175], v[180:183], v[40:43]
	v_mfma_f32_16x16x32_bf16 v[32:35], v[156:159], v[188:191], v[32:35]
	v_mfma_f32_16x16x32_bf16 v[28:31], v[172:175], v[188:191], v[28:31]
	v_mfma_f32_16x16x32_bf16 v[20:23], v[156:159], v[196:199], v[20:23]
	v_mfma_f32_16x16x32_bf16 v[12:15], v[172:175], v[196:199], v[12:15]
	v_mfma_f32_16x16x32_bf16 v[4:7], v[156:159], v[204:207], v[4:7]
	v_mfma_f32_16x16x32_bf16 v[0:3], v[172:175], v[204:207], v[0:3]
	v_mfma_f32_16x16x32_bf16 v[44:47], v[168:171], v[184:187], v[44:47]
	v_mfma_f32_16x16x32_bf16 v[40:43], v[176:179], v[184:187], v[40:43]
	v_mfma_f32_16x16x32_bf16 v[32:35], v[168:171], v[192:195], v[32:35]
	v_mfma_f32_16x16x32_bf16 v[28:31], v[176:179], v[192:195], v[28:31]
	v_mfma_f32_16x16x32_bf16 v[20:23], v[168:171], v[200:203], v[20:23]
	v_mfma_f32_16x16x32_bf16 v[12:15], v[176:179], v[200:203], v[12:15]
	v_mfma_f32_16x16x32_bf16 v[4:7], v[168:171], v[208:211], v[4:7]
	v_mfma_f32_16x16x32_bf16 v[0:3], v[176:179], v[208:211], v[0:3]
	s_setprio 0
	s_barrier
	s_add_i32 s54, 0, 0x18000
	s_add_i32 s55, 0, 0x1c000
	v_add_u32_e32 v140, s54, v163
	v_add_u32_e32 v176, s55, v163
	ds_read_b128 v[128:131], v140
	ds_read_b128 v[132:135], v140 offset:1024
	ds_read_b128 v[136:139], v140 offset:2048
	ds_read_b128 v[140:143], v140 offset:3072
	ds_read_b128 v[156:159], v176
	ds_read_b128 v[168:171], v176 offset:1024
	ds_read_b128 v[172:175], v176 offset:2048
	ds_read_b128 v[176:179], v176 offset:3072
	s_add_u32 s20, s26, 0x160000
	s_addc_u32 s21, s27, 0
	s_mov_b32 m0, s37
	v_lshl_add_u64 v[218:219], s[20:21], 0, v[144:145]
	ds_read_b128 v[180:183], v167 offset:32768
	ds_read_b128 v[184:187], v167 offset:33792
	ds_read_b128 v[188:191], v167 offset:34816
	ds_read_b128 v[192:195], v167 offset:35840
	ds_read_b128 v[196:199], v167 offset:36864
	ds_read_b128 v[200:203], v167 offset:37888
	ds_read_b128 v[204:207], v167 offset:38912
	ds_read_b128 v[208:211], v167 offset:39936
	global_load_lds_dwordx4 v[218:219], off
	v_lshl_add_u64 v[218:219], s[20:21], 0, v[146:147]
	s_mov_b32 m0, s38
	s_nop 0
	global_load_lds_dwordx4 v[218:219], off
	s_sleep 1
	s_waitcnt vmcnt(8)
	s_waitcnt lgkmcnt(0)
	s_barrier
	s_setprio 1
	s_waitcnt lgkmcnt(0)
	v_mfma_f32_16x16x32_bf16 v[124:127], v[128:131], v[180:183], v[124:127]
	v_mfma_f32_16x16x32_bf16 v[120:123], v[136:139], v[180:183], v[120:123]
	v_mfma_f32_16x16x32_bf16 v[116:119], v[128:131], v[188:191], v[116:119]
	v_mfma_f32_16x16x32_bf16 v[112:115], v[136:139], v[188:191], v[112:115]
	v_mfma_f32_16x16x32_bf16 v[92:95], v[128:131], v[196:199], v[92:95]
	v_mfma_f32_16x16x32_bf16 v[88:91], v[136:139], v[196:199], v[88:91]
	v_mfma_f32_16x16x32_bf16 v[84:87], v[128:131], v[204:207], v[84:87]
	v_mfma_f32_16x16x32_bf16 v[80:83], v[136:139], v[204:207], v[80:83]
	v_mfma_f32_16x16x32_bf16 v[124:127], v[132:135], v[184:187], v[124:127]
	v_mfma_f32_16x16x32_bf16 v[120:123], v[140:143], v[184:187], v[120:123]
	v_mfma_f32_16x16x32_bf16 v[116:119], v[132:135], v[192:195], v[116:119]
	v_mfma_f32_16x16x32_bf16 v[112:115], v[140:143], v[192:195], v[112:115]
	v_mfma_f32_16x16x32_bf16 v[92:95], v[132:135], v[200:203], v[92:95]
	v_mfma_f32_16x16x32_bf16 v[88:91], v[140:143], v[200:203], v[88:91]
	v_mfma_f32_16x16x32_bf16 v[84:87], v[132:135], v[208:211], v[84:87]
	v_mfma_f32_16x16x32_bf16 v[80:83], v[140:143], v[208:211], v[80:83]
	s_setprio 0
	s_setprio 1
	v_mfma_f32_16x16x32_bf16 v[108:111], v[156:159], v[180:183], v[108:111]
	v_mfma_f32_16x16x32_bf16 v[104:107], v[172:175], v[180:183], v[104:107]
	v_mfma_f32_16x16x32_bf16 v[100:103], v[156:159], v[188:191], v[100:103]
	v_mfma_f32_16x16x32_bf16 v[96:99], v[172:175], v[188:191], v[96:99]
	v_mfma_f32_16x16x32_bf16 v[76:79], v[156:159], v[196:199], v[76:79]
	v_mfma_f32_16x16x32_bf16 v[72:75], v[172:175], v[196:199], v[72:75]
	v_mfma_f32_16x16x32_bf16 v[68:71], v[156:159], v[204:207], v[68:71]
	v_mfma_f32_16x16x32_bf16 v[64:67], v[172:175], v[204:207], v[64:67]
	v_mfma_f32_16x16x32_bf16 v[108:111], v[168:171], v[184:187], v[108:111]
	v_mfma_f32_16x16x32_bf16 v[104:107], v[176:179], v[184:187], v[104:107]
	v_mfma_f32_16x16x32_bf16 v[100:103], v[168:171], v[192:195], v[100:103]
	v_mfma_f32_16x16x32_bf16 v[96:99], v[176:179], v[192:195], v[96:99]
	v_mfma_f32_16x16x32_bf16 v[76:79], v[168:171], v[200:203], v[76:79]
	v_mfma_f32_16x16x32_bf16 v[72:75], v[176:179], v[200:203], v[72:75]
	v_mfma_f32_16x16x32_bf16 v[68:71], v[168:171], v[208:211], v[68:71]
	v_mfma_f32_16x16x32_bf16 v[64:67], v[176:179], v[208:211], v[64:67]
	s_setprio 0
	s_barrier
; #define PG8_STAGE(bufoff, gbase, voff) do { _Pragma("unroll") for (int _i = 0; _i < 2; ++_i) \
;         __builtin_amdgcn_global_load_lds((const unsigned*)((const char*)(gbase) + (voff)[_i]), (PG8_LAS unsigned*)(lds + (bufoff) + ldsw + _i * 8192), 16, 0, 0); } while (0)
; #define PG8_LDA(dst, b, h) do { _Pragma("unroll") for (int m = 0; m < 4; ++m) _Pragma("unroll") for (int k = 0; k < 2; ++k) dst[m][k] = *(const PG8_LAS bf16x8*)(lds + PG8_SA(b, h) + aoff + m * 2048 + k * 1024); } while (0)
; #define PG8_MMA(ai, bj, At, Bt) do { __builtin_amdgcn_s_setprio(1); _Pragma("unroll") for (int m = 0; m < 4; ++m) _Pragma("unroll") for (int n = 0; n < 2; ++n) _Pragma("unroll") for (int k = 0; k < 2; ++k) \
;         acc[ai][bj][m][n] = __builtin_amdgcn_mfma_f32_16x16x32_bf16(Bt[n][k], At[m][k], acc[ai][bj][m][n], 0, 0, 0); __builtin_amdgcn_s_setprio(0); } while (0)
; #define PG8_WAIT_V(n) asm volatile("s_waitcnt vmcnt(" #n ")" ::: "memory")
; #define PG8_WAIT_L(n) asm volatile("s_waitcnt lgkmcnt(" #n ")" ::: "memory")
; #define PG8_BAR __builtin_amdgcn_s_barrier()
; #define PG8_SCHED __builtin_amdgcn_sched_barrier(0)
; template <class Epi, class Sched, bool ALIGN_EPI = false, bool SP2 = false>
; __device__ __forceinline__ void gemm_phase(PG8_LAS unsigned char* lds, const Gemm g, const Sched& S, const Epi& E) {
;     ...
;             PG8_LDA(At, 1, 1); PG8_STAGE(PG8_SB(1, 0), b3, voffB); PG8_STAGE(PG8_SB(1, 1), b3 + hstep, voffB); PG8_STAGE(PG8_SA(1, 0), a3, voffA);
;             PG8_WAIT_V(8); PG8_WAIT_L(0); PG8_BAR; PG8_MMA(1, 0, At, B0); PG8_MMA(1, 1, At, B1); PG8_BAR; PG8_SCHED;
;     ...
;         if constexpr (ALIGN_EPI) { if (wr == 0) PG8_BAR; }
	s_add_i32 s20, s54, s34
	v_lshl_add_u64 v[160:161], v[160:161], 0, s[10:11]
	s_mov_b32 m0, s20
	ds_read_b128 v[180:183], v167 offset:49152
	ds_read_b128 v[184:187], v167 offset:50176
	ds_read_b128 v[188:191], v167 offset:51200
	ds_read_b128 v[192:195], v167 offset:52224
	ds_read_b128 v[196:199], v167 offset:53248
	ds_read_b128 v[200:203], v167 offset:54272
	ds_read_b128 v[204:207], v167 offset:55296
	ds_read_b128 v[208:211], v167 offset:56320
	global_load_lds_dwordx4 v[160:161], off
	s_add_i32 m0, s20, 0x2000
	s_add_u32 s20, s24, 0x160080
	v_lshl_add_u64 v[160:161], v[212:213], 0, s[10:11]
	s_addc_u32 s21, s25, 0
	s_add_i32 s24, s55, s34
	global_load_lds_dwordx4 v[160:161], off
	v_lshl_add_u64 v[160:161], s[20:21], 0, v[144:145]
	s_mov_b32 m0, s24
	s_nop 0
	global_load_lds_dwordx4 v[160:161], off
	v_lshl_add_u64 v[160:161], s[20:21], 0, v[146:147]
	s_add_i32 m0, s24, 0x2000
	s_nop 0
	global_load_lds_dwordx4 v[160:161], off
	v_lshl_add_u64 v[160:161], v[214:215], 0, s[10:11]
	s_mov_b32 m0, s42
	s_nop 0
	global_load_lds_dwordx4 v[160:161], off
	v_lshl_add_u64 v[160:161], v[216:217], 0, s[10:11]
	s_mov_b32 m0, s43
	s_nop 0
	global_load_lds_dwordx4 v[160:161], off
	s_sleep 1
	s_waitcnt vmcnt(8)
	s_waitcnt lgkmcnt(0)
	s_barrier
	s_setprio 1
	s_waitcnt lgkmcnt(0)
	v_mfma_f32_16x16x32_bf16 v[60:63], v[128:131], v[180:183], v[60:63]
	v_mfma_f32_16x16x32_bf16 v[56:59], v[136:139], v[180:183], v[56:59]
	v_mfma_f32_16x16x32_bf16 v[52:55], v[128:131], v[188:191], v[52:55]
	v_mfma_f32_16x16x32_bf16 v[48:51], v[136:139], v[188:191], v[48:51]
	v_mfma_f32_16x16x32_bf16 v[36:39], v[128:131], v[196:199], v[36:39]
	v_mfma_f32_16x16x32_bf16 v[24:27], v[136:139], v[196:199], v[24:27]
	v_mfma_f32_16x16x32_bf16 v[16:19], v[128:131], v[204:207], v[16:19]
	v_mfma_f32_16x16x32_bf16 v[8:11], v[136:139], v[204:207], v[8:11]
	v_mfma_f32_16x16x32_bf16 v[60:63], v[132:135], v[184:187], v[60:63]
	v_mfma_f32_16x16x32_bf16 v[56:59], v[140:143], v[184:187], v[56:59]
	v_mfma_f32_16x16x32_bf16 v[52:55], v[132:135], v[192:195], v[52:55]
	v_mfma_f32_16x16x32_bf16 v[48:51], v[140:143], v[192:195], v[48:51]
	v_mfma_f32_16x16x32_bf16 v[36:39], v[132:135], v[200:203], v[36:39]
	v_mfma_f32_16x16x32_bf16 v[24:27], v[140:143], v[200:203], v[24:27]
	v_mfma_f32_16x16x32_bf16 v[16:19], v[132:135], v[208:211], v[16:19]
	v_mfma_f32_16x16x32_bf16 v[8:11], v[140:143], v[208:211], v[8:11]
	s_setprio 0
	s_setprio 1
	v_mfma_f32_16x16x32_bf16 v[44:47], v[156:159], v[180:183], v[44:47]
	v_mfma_f32_16x16x32_bf16 v[40:43], v[172:175], v[180:183], v[40:43]
	v_mfma_f32_16x16x32_bf16 v[32:35], v[156:159], v[188:191], v[32:35]
	v_mfma_f32_16x16x32_bf16 v[28:31], v[172:175], v[188:191], v[28:31]
	v_mfma_f32_16x16x32_bf16 v[20:23], v[156:159], v[196:199], v[20:23]
	v_mfma_f32_16x16x32_bf16 v[12:15], v[172:175], v[196:199], v[12:15]
	v_mfma_f32_16x16x32_bf16 v[4:7], v[156:159], v[204:207], v[4:7]
	v_mfma_f32_16x16x32_bf16 v[0:3], v[172:175], v[204:207], v[0:3]
	v_mfma_f32_16x16x32_bf16 v[44:47], v[168:171], v[184:187], v[44:47]
	v_mfma_f32_16x16x32_bf16 v[40:43], v[176:179], v[184:187], v[40:43]
	v_mfma_f32_16x16x32_bf16 v[32:35], v[168:171], v[192:195], v[32:35]
	v_mfma_f32_16x16x32_bf16 v[28:31], v[176:179], v[192:195], v[28:31]
	v_mfma_f32_16x16x32_bf16 v[20:23], v[168:171], v[200:203], v[20:23]
	v_mfma_f32_16x16x32_bf16 v[12:15], v[176:179], v[200:203], v[12:15]
	v_mfma_f32_16x16x32_bf16 v[4:7], v[168:171], v[208:211], v[4:7]
	v_mfma_f32_16x16x32_bf16 v[0:3], v[176:179], v[208:211], v[0:3]
	s_setprio 0
	s_barrier
	s_add_i32 s53, s53, 2
	s_add_u32 s51, s51, 0x100
	s_addc_u32 s52, s52, 0
	s_cmpk_gt_u32 s53, 0x55
	s_mov_b64 s[20:21], s[22:23]
	s_cbranch_scc0 .LBB0_877
	s_and_b64 vcc, exec, s[14:15]
	s_cbranch_vccz .LBB0_880
	s_barrier

; #define PG8_STAGE(bufoff, gbase, voff) do { _Pragma("unroll") for (int _i = 0; _i < 2; ++_i) \
;         __builtin_amdgcn_global_load_lds((const unsigned*)((const char*)(gbase) + (voff)[_i]), (PG8_LAS unsigned*)(lds + (bufoff) + ldsw + _i * 8192), 16, 0, 0); } while (0)
; #define PG8_LDA(dst, b, h) do { _Pragma("unroll") for (int m = 0; m < 4; ++m) _Pragma("unroll") for (int k = 0; k < 2; ++k) dst[m][k] = *(const PG8_LAS bf16x8*)(lds + PG8_SA(b, h) + aoff + m * 2048 + k * 1024); } while (0)
; #define PG8_LDB(dst, b, h) do { _Pragma("unroll") for (int n = 0; n < 2; ++n) _Pragma("unroll") for (int k = 0; k < 2; ++k) dst[n][k] = *(const PG8_LAS bf16x8*)(lds + PG8_SB(b, h) + boff + n * 2048 + k * 1024); } while (0)
; #define PG8_MMA(ai, bj, At, Bt) do { __builtin_amdgcn_s_setprio(1); _Pragma("unroll") for (int m = 0; m < 4; ++m) _Pragma("unroll") for (int n = 0; n < 2; ++n) _Pragma("unroll") for (int k = 0; k < 2; ++k) \
;         acc[ai][bj][m][n] = __builtin_amdgcn_mfma_f32_16x16x32_bf16(Bt[n][k], At[m][k], acc[ai][bj][m][n], 0, 0, 0); __builtin_amdgcn_s_setprio(0); } while (0)
; #define PG8_WAIT_V(n) asm volatile("s_waitcnt vmcnt(" #n ")" ::: "memory")
; #define PG8_WAIT_L(n) asm volatile("s_waitcnt lgkmcnt(" #n ")" ::: "memory")
; template <class Epi, class Sched, bool ALIGN_EPI = false, bool SP2 = false>
; __device__ __forceinline__ void gemm_phase(PG8_LAS unsigned char* lds, const Gemm g, const Sched& S, const Epi& E) {
;     ...
;             const bool last = (t == nt - 2);
;             const char* a1 = cA + (size_t)(t + 1) * kstep;
;             const char* a2 = last ? nA : cA + (size_t)(t + 2) * kstep; const char* b2 = last ? nB : cB + (size_t)(t + 2) * kstep;
;             const char* a3 = a2 + kstep; const char* b3 = b2 + kstep;
;             if (last && has_next) S.a_ready(nxt);
;             if constexpr (SP2) {
;             PG8_LDB(B0, 0, 0); PG8_LDB(B1, 0, 1); PG8_SCHED; PG8_LDA(At, 0, 0); PG8_STAGE(PG8_SA(1, 1), a1 + hstep, voffA);
;             PG8_WAIT_V(8); PG8_WAIT_L(0); PG8_BAR; PG8_MMA(0, 0, At, B0); PG8_MMA(0, 1, At, B1); PG8_BAR; PG8_SCHED;
;             PG8_LDA(At, 0, 1); PG8_STAGE(PG8_SB(0, 0), b2, voffB); PG8_STAGE(PG8_SB(0, 1), b2 + hstep, voffB); PG8_STAGE(PG8_SA(0, 0), a2, voffA);
;             PG8_WAIT_V(8); PG8_WAIT_L(0); PG8_BAR; PG8_MMA(1, 0, At, B0); PG8_MMA(1, 1, At, B1); PG8_BAR; PG8_SCHED;
.LBB0_1027:
	ds_read_b128 v[144:147], v155
	ds_read_b128 v[148:151], v155 offset:1024
	ds_read_b128 v[158:161], v155 offset:2048
	ds_read_b128 v[162:165], v155 offset:3072
	ds_read_b128 v[166:169], v156
	ds_read_b128 v[170:173], v156 offset:1024
	ds_read_b128 v[174:177], v156 offset:2048
	ds_read_b128 v[178:181], v156 offset:3072
	s_add_u32 s52, s50, 0xfff80080
	s_addc_u32 s53, s51, -1
	s_cmp_eq_u32 s71, 28
	s_cselect_b32 s55, s45, s53
	s_cselect_b32 s54, s67, s52
	s_cselect_b32 s53, s43, s70
	s_cselect_b32 s52, s68, s69
	v_lshl_add_u64 v[214:215], s[50:51], 0, v[136:137]
	s_add_i32 m0, s29, 0xc000
	ds_read_b128 v[182:185], v157
	ds_read_b128 v[186:189], v157 offset:1024
	ds_read_b128 v[190:193], v157 offset:2048
	ds_read_b128 v[194:197], v157 offset:3072
	ds_read_b128 v[198:201], v157 offset:4096
	ds_read_b128 v[202:205], v157 offset:5120
	ds_read_b128 v[206:209], v157 offset:6144
	ds_read_b128 v[210:213], v157 offset:7168
	global_load_lds_dwordx4 v[214:215], off
	v_lshl_add_u64 v[214:215], s[50:51], 0, v[138:139]
	s_add_i32 m0, s29, 0xe000
	s_nop 0
	global_load_lds_dwordx4 v[214:215], off
	s_sleep 1
	s_waitcnt vmcnt(8)
	s_waitcnt lgkmcnt(0)
	s_barrier
	s_setprio 1
	s_waitcnt lgkmcnt(0)
	v_mfma_f32_16x16x32_bf16 v[124:127], v[144:147], v[182:185], v[124:127]
	v_mfma_f32_16x16x32_bf16 v[120:123], v[158:161], v[182:185], v[120:123]
	v_mfma_f32_16x16x32_bf16 v[108:111], v[144:147], v[190:193], v[108:111]
	v_mfma_f32_16x16x32_bf16 v[104:107], v[158:161], v[190:193], v[104:107]
	v_mfma_f32_16x16x32_bf16 v[92:95], v[144:147], v[198:201], v[92:95]
	v_mfma_f32_16x16x32_bf16 v[88:91], v[158:161], v[198:201], v[88:91]
	v_mfma_f32_16x16x32_bf16 v[76:79], v[144:147], v[206:209], v[76:79]
	v_mfma_f32_16x16x32_bf16 v[72:75], v[158:161], v[206:209], v[72:75]
	v_mfma_f32_16x16x32_bf16 v[124:127], v[148:151], v[186:189], v[124:127]
	v_mfma_f32_16x16x32_bf16 v[120:123], v[162:165], v[186:189], v[120:123]
	v_mfma_f32_16x16x32_bf16 v[108:111], v[148:151], v[194:197], v[108:111]
	v_mfma_f32_16x16x32_bf16 v[104:107], v[162:165], v[194:197], v[104:107]
	v_mfma_f32_16x16x32_bf16 v[92:95], v[148:151], v[202:205], v[92:95]
	v_mfma_f32_16x16x32_bf16 v[88:91], v[162:165], v[202:205], v[88:91]
	v_mfma_f32_16x16x32_bf16 v[76:79], v[148:151], v[210:213], v[76:79]
	v_mfma_f32_16x16x32_bf16 v[72:75], v[162:165], v[210:213], v[72:75]
	s_setprio 0
	s_setprio 1
	v_mfma_f32_16x16x32_bf16 v[116:119], v[166:169], v[182:185], v[116:119]
	v_mfma_f32_16x16x32_bf16 v[112:115], v[174:177], v[182:185], v[112:115]
	v_mfma_f32_16x16x32_bf16 v[100:103], v[166:169], v[190:193], v[100:103]
	v_mfma_f32_16x16x32_bf16 v[96:99], v[174:177], v[190:193], v[96:99]
	v_mfma_f32_16x16x32_bf16 v[84:87], v[166:169], v[198:201], v[84:87]
	v_mfma_f32_16x16x32_bf16 v[80:83], v[174:177], v[198:201], v[80:83]
	v_mfma_f32_16x16x32_bf16 v[68:71], v[166:169], v[206:209], v[68:71]
	v_mfma_f32_16x16x32_bf16 v[64:67], v[174:177], v[206:209], v[64:67]
	v_mfma_f32_16x16x32_bf16 v[116:119], v[170:173], v[186:189], v[116:119]
	v_mfma_f32_16x16x32_bf16 v[112:115], v[178:181], v[186:189], v[112:115]
	v_mfma_f32_16x16x32_bf16 v[100:103], v[170:173], v[194:197], v[100:103]
	v_mfma_f32_16x16x32_bf16 v[96:99], v[178:181], v[194:197], v[96:99]
	v_mfma_f32_16x16x32_bf16 v[84:87], v[170:173], v[202:205], v[84:87]
	v_mfma_f32_16x16x32_bf16 v[80:83], v[178:181], v[202:205], v[80:83]
	v_mfma_f32_16x16x32_bf16 v[68:71], v[170:173], v[210:213], v[68:71]
	v_mfma_f32_16x16x32_bf16 v[64:67], v[178:181], v[210:213], v[64:67]
	s_setprio 0
	s_barrier
	s_add_i32 s72, s61, s27
	v_lshl_add_u64 v[214:215], s[52:53], 0, v[132:133]
	s_mov_b32 m0, s72
	ds_read_b128 v[182:185], v157 offset:16384
	ds_read_b128 v[186:189], v157 offset:17408
	ds_read_b128 v[190:193], v157 offset:18432
	ds_read_b128 v[194:197], v157 offset:19456
	ds_read_b128 v[198:201], v157 offset:20480
	ds_read_b128 v[202:205], v157 offset:21504
	ds_read_b128 v[206:209], v157 offset:22528
	ds_read_b128 v[210:213], v157 offset:23552
	global_load_lds_dwordx4 v[214:215], off
	s_add_i32 m0, s72, 0x2000
	s_add_u32 s72, s52, 0x80000
	v_lshl_add_u64 v[216:217], s[52:53], 0, v[128:129]
	s_addc_u32 s73, s53, 0
	s_add_i32 s76, s62, s27
	global_load_lds_dwordx4 v[216:217], off
	v_lshl_add_u64 v[218:219], s[72:73], 0, v[132:133]
	s_mov_b32 m0, s76
	v_lshl_add_u64 v[222:223], s[54:55], 0, v[130:131]
	global_load_lds_dwordx4 v[218:219], off
	v_lshl_add_u64 v[218:219], s[72:73], 0, v[128:129]
	s_add_i32 m0, s76, 0x2000
	s_nop 0
	global_load_lds_dwordx4 v[218:219], off
	v_lshl_add_u64 v[218:219], s[54:55], 0, v[134:135]
	s_mov_b32 m0, s29
	s_nop 0
	global_load_lds_dwordx4 v[218:219], off
	s_mov_b32 m0, s31
	s_nop 0
	global_load_lds_dwordx4 v[222:223], off
	s_sleep 1
	s_waitcnt vmcnt(8)
	s_waitcnt lgkmcnt(0)
	s_barrier
; #define PG8_STAGE(bufoff, gbase, voff) do { _Pragma("unroll") for (int _i = 0; _i < 2; ++_i) \
;         __builtin_amdgcn_global_load_lds((const unsigned*)((const char*)(gbase) + (voff)[_i]), (PG8_LAS unsigned*)(lds + (bufoff) + ldsw + _i * 8192), 16, 0, 0); } while (0)
; #define PG8_LDA(dst, b, h) do { _Pragma("unroll") for (int m = 0; m < 4; ++m) _Pragma("unroll") for (int k = 0; k < 2; ++k) dst[m][k] = *(const PG8_LAS bf16x8*)(lds + PG8_SA(b, h) + aoff + m * 2048 + k * 1024); } while (0)
; #define PG8_LDB(dst, b, h) do { _Pragma("unroll") for (int n = 0; n < 2; ++n) _Pragma("unroll") for (int k = 0; k < 2; ++k) dst[n][k] = *(const PG8_LAS bf16x8*)(lds + PG8_SB(b, h) + boff + n * 2048 + k * 1024); } while (0)
; #define PG8_MMA(ai, bj, At, Bt) do { __builtin_amdgcn_s_setprio(1); _Pragma("unroll") for (int m = 0; m < 4; ++m) _Pragma("unroll") for (int n = 0; n < 2; ++n) _Pragma("unroll") for (int k = 0; k < 2; ++k) \
;         acc[ai][bj][m][n] = __builtin_amdgcn_mfma_f32_16x16x32_bf16(Bt[n][k], At[m][k], acc[ai][bj][m][n], 0, 0, 0); __builtin_amdgcn_s_setprio(0); } while (0)
; #define PG8_WAIT_V(n) asm volatile("s_waitcnt vmcnt(" #n ")" ::: "memory")
; #define PG8_WAIT_L(n) asm volatile("s_waitcnt lgkmcnt(" #n ")" ::: "memory")
; #define PG8_BAR __builtin_amdgcn_s_barrier()
; #define PG8_SCHED __builtin_amdgcn_sched_barrier(0)
; template <class Epi, class Sched, bool ALIGN_EPI = false, bool SP2 = false>
; __device__ __forceinline__ void gemm_phase(PG8_LAS unsigned char* lds, const Gemm g, const Sched& S, const Epi& E) {
;     ...
;             PG8_WAIT_V(8); PG8_WAIT_L(0); PG8_BAR; PG8_MMA(1, 0, At, B0); PG8_MMA(1, 1, At, B1); PG8_BAR; PG8_SCHED;
;             PG8_LDB(B0, 1, 0); PG8_LDB(B1, 1, 1); PG8_SCHED; PG8_LDA(At, 1, 0); PG8_STAGE(PG8_SA(0, 1), a2 + hstep, voffA);
;             PG8_WAIT_V(8); PG8_WAIT_L(0); PG8_BAR; PG8_MMA(0, 0, At, B0); PG8_MMA(0, 1, At, B1); PG8_BAR; PG8_SCHED;
	s_setprio 1
	s_waitcnt lgkmcnt(0)
	v_mfma_f32_16x16x32_bf16 v[60:63], v[144:147], v[182:185], v[60:63]
	v_mfma_f32_16x16x32_bf16 v[56:59], v[158:161], v[182:185], v[56:59]
	v_mfma_f32_16x16x32_bf16 v[44:47], v[144:147], v[190:193], v[44:47]
	v_mfma_f32_16x16x32_bf16 v[40:43], v[158:161], v[190:193], v[40:43]
	v_mfma_f32_16x16x32_bf16 v[28:31], v[144:147], v[198:201], v[28:31]
	v_mfma_f32_16x16x32_bf16 v[24:27], v[158:161], v[198:201], v[24:27]
	v_mfma_f32_16x16x32_bf16 v[12:15], v[144:147], v[206:209], v[12:15]
	v_mfma_f32_16x16x32_bf16 v[8:11], v[158:161], v[206:209], v[8:11]
	v_mfma_f32_16x16x32_bf16 v[60:63], v[148:151], v[186:189], v[60:63]
	v_mfma_f32_16x16x32_bf16 v[56:59], v[162:165], v[186:189], v[56:59]
	v_mfma_f32_16x16x32_bf16 v[44:47], v[148:151], v[194:197], v[44:47]
	v_mfma_f32_16x16x32_bf16 v[40:43], v[162:165], v[194:197], v[40:43]
	v_mfma_f32_16x16x32_bf16 v[28:31], v[148:151], v[202:205], v[28:31]
	v_mfma_f32_16x16x32_bf16 v[24:27], v[162:165], v[202:205], v[24:27]
	v_mfma_f32_16x16x32_bf16 v[12:15], v[148:151], v[210:213], v[12:15]
	v_mfma_f32_16x16x32_bf16 v[8:11], v[162:165], v[210:213], v[8:11]
	s_setprio 0
	s_setprio 1
	v_mfma_f32_16x16x32_bf16 v[52:55], v[166:169], v[182:185], v[52:55]
	v_mfma_f32_16x16x32_bf16 v[48:51], v[174:177], v[182:185], v[48:51]
	v_mfma_f32_16x16x32_bf16 v[36:39], v[166:169], v[190:193], v[36:39]
	v_mfma_f32_16x16x32_bf16 v[32:35], v[174:177], v[190:193], v[32:35]
	v_mfma_f32_16x16x32_bf16 v[20:23], v[166:169], v[198:201], v[20:23]
	v_mfma_f32_16x16x32_bf16 v[16:19], v[174:177], v[198:201], v[16:19]
	v_mfma_f32_16x16x32_bf16 v[4:7], v[166:169], v[206:209], v[4:7]
	v_mfma_f32_16x16x32_bf16 v[0:3], v[174:177], v[206:209], v[0:3]
	v_mfma_f32_16x16x32_bf16 v[52:55], v[170:173], v[186:189], v[52:55]
	v_mfma_f32_16x16x32_bf16 v[48:51], v[178:181], v[186:189], v[48:51]
	v_mfma_f32_16x16x32_bf16 v[36:39], v[170:173], v[194:197], v[36:39]
	v_mfma_f32_16x16x32_bf16 v[32:35], v[178:181], v[194:197], v[32:35]
	v_mfma_f32_16x16x32_bf16 v[20:23], v[170:173], v[202:205], v[20:23]
	v_mfma_f32_16x16x32_bf16 v[16:19], v[178:181], v[202:205], v[16:19]
	v_mfma_f32_16x16x32_bf16 v[4:7], v[170:173], v[210:213], v[4:7]
	v_mfma_f32_16x16x32_bf16 v[0:3], v[178:181], v[210:213], v[0:3]
	s_setprio 0
	s_barrier
	s_add_i32 s72, 0, 0x18000
	s_add_i32 s73, 0, 0x1c000
	v_add_u32_e32 v162, s72, v153
	v_add_u32_e32 v178, s73, v153
	ds_read_b128 v[144:147], v162
	ds_read_b128 v[148:151], v162 offset:1024
	ds_read_b128 v[158:161], v162 offset:2048
	ds_read_b128 v[162:165], v162 offset:3072
	ds_read_b128 v[166:169], v178
	ds_read_b128 v[170:173], v178 offset:1024
	ds_read_b128 v[174:177], v178 offset:2048
	ds_read_b128 v[178:181], v178 offset:3072
	s_add_u32 s54, s54, 0x80000
	s_addc_u32 s55, s55, 0
	s_mov_b32 m0, s56
	v_lshl_add_u64 v[224:225], s[54:55], 0, v[134:135]
	ds_read_b128 v[182:185], v157 offset:32768
	ds_read_b128 v[186:189], v157 offset:33792
	ds_read_b128 v[190:193], v157 offset:34816
	ds_read_b128 v[194:197], v157 offset:35840
	ds_read_b128 v[198:201], v157 offset:36864
	ds_read_b128 v[202:205], v157 offset:37888
	ds_read_b128 v[206:209], v157 offset:38912
	ds_read_b128 v[210:213], v157 offset:39936
	global_load_lds_dwordx4 v[224:225], off
	v_lshl_add_u64 v[224:225], s[54:55], 0, v[130:131]
	s_mov_b32 m0, s57
	s_nop 0
	global_load_lds_dwordx4 v[224:225], off
	s_sleep 1
	s_waitcnt vmcnt(8)
	s_waitcnt lgkmcnt(0)
	s_barrier
	s_setprio 1
	s_waitcnt lgkmcnt(0)
	v_mfma_f32_16x16x32_bf16 v[124:127], v[144:147], v[182:185], v[124:127]
	v_mfma_f32_16x16x32_bf16 v[120:123], v[158:161], v[182:185], v[120:123]
	v_mfma_f32_16x16x32_bf16 v[108:111], v[144:147], v[190:193], v[108:111]
	v_mfma_f32_16x16x32_bf16 v[104:107], v[158:161], v[190:193], v[104:107]
	v_mfma_f32_16x16x32_bf16 v[92:95], v[144:147], v[198:201], v[92:95]
	v_mfma_f32_16x16x32_bf16 v[88:91], v[158:161], v[198:201], v[88:91]
	v_mfma_f32_16x16x32_bf16 v[76:79], v[144:147], v[206:209], v[76:79]
	v_mfma_f32_16x16x32_bf16 v[72:75], v[158:161], v[206:209], v[72:75]
	v_mfma_f32_16x16x32_bf16 v[124:127], v[148:151], v[186:189], v[124:127]
	v_mfma_f32_16x16x32_bf16 v[120:123], v[162:165], v[186:189], v[120:123]
	v_mfma_f32_16x16x32_bf16 v[108:111], v[148:151], v[194:197], v[108:111]
	v_mfma_f32_16x16x32_bf16 v[104:107], v[162:165], v[194:197], v[104:107]
	v_mfma_f32_16x16x32_bf16 v[92:95], v[148:151], v[202:205], v[92:95]
	v_mfma_f32_16x16x32_bf16 v[88:91], v[162:165], v[202:205], v[88:91]
	v_mfma_f32_16x16x32_bf16 v[76:79], v[148:151], v[210:213], v[76:79]
	v_mfma_f32_16x16x32_bf16 v[72:75], v[162:165], v[210:213], v[72:75]
	s_setprio 0
	s_setprio 1
	v_mfma_f32_16x16x32_bf16 v[116:119], v[166:169], v[182:185], v[116:119]
	v_mfma_f32_16x16x32_bf16 v[112:115], v[174:177], v[182:185], v[112:115]
	v_mfma_f32_16x16x32_bf16 v[100:103], v[166:169], v[190:193], v[100:103]
	v_mfma_f32_16x16x32_bf16 v[96:99], v[174:177], v[190:193], v[96:99]
	v_mfma_f32_16x16x32_bf16 v[84:87], v[166:169], v[198:201], v[84:87]
	v_mfma_f32_16x16x32_bf16 v[80:83], v[174:177], v[198:201], v[80:83]
	v_mfma_f32_16x16x32_bf16 v[68:71], v[166:169], v[206:209], v[68:71]
	v_mfma_f32_16x16x32_bf16 v[64:67], v[174:177], v[206:209], v[64:67]
	v_mfma_f32_16x16x32_bf16 v[116:119], v[170:173], v[186:189], v[116:119]
	v_mfma_f32_16x16x32_bf16 v[112:115], v[178:181], v[186:189], v[112:115]
	v_mfma_f32_16x16x32_bf16 v[100:103], v[170:173], v[194:197], v[100:103]
	v_mfma_f32_16x16x32_bf16 v[96:99], v[178:181], v[194:197], v[96:99]
	v_mfma_f32_16x16x32_bf16 v[84:87], v[170:173], v[202:205], v[84:87]
	v_mfma_f32_16x16x32_bf16 v[80:83], v[178:181], v[202:205], v[80:83]
	v_mfma_f32_16x16x32_bf16 v[68:71], v[170:173], v[210:213], v[68:71]
	v_mfma_f32_16x16x32_bf16 v[64:67], v[178:181], v[210:213], v[64:67]
	s_setprio 0
	s_barrier
; #define PG8_STAGE(bufoff, gbase, voff) do { _Pragma("unroll") for (int _i = 0; _i < 2; ++_i) \
;         __builtin_amdgcn_global_load_lds((const unsigned*)((const char*)(gbase) + (voff)[_i]), (PG8_LAS unsigned*)(lds + (bufoff) + ldsw + _i * 8192), 16, 0, 0); } while (0)
; #define PG8_LDA(dst, b, h) do { _Pragma("unroll") for (int m = 0; m < 4; ++m) _Pragma("unroll") for (int k = 0; k < 2; ++k) dst[m][k] = *(const PG8_LAS bf16x8*)(lds + PG8_SA(b, h) + aoff + m * 2048 + k * 1024); } while (0)
; #define PG8_MMA(ai, bj, At, Bt) do { __builtin_amdgcn_s_setprio(1); _Pragma("unroll") for (int m = 0; m < 4; ++m) _Pragma("unroll") for (int n = 0; n < 2; ++n) _Pragma("unroll") for (int k = 0; k < 2; ++k) \
;         acc[ai][bj][m][n] = __builtin_amdgcn_mfma_f32_16x16x32_bf16(Bt[n][k], At[m][k], acc[ai][bj][m][n], 0, 0, 0); __builtin_amdgcn_s_setprio(0); } while (0)
; #define PG8_WAIT_V(n) asm volatile("s_waitcnt vmcnt(" #n ")" ::: "memory")
; #define PG8_WAIT_L(n) asm volatile("s_waitcnt lgkmcnt(" #n ")" ::: "memory")
; #define PG8_BAR __builtin_amdgcn_s_barrier()
; #define PG8_SCHED __builtin_amdgcn_sched_barrier(0)
; template <class Epi, class Sched, bool ALIGN_EPI = false, bool SP2 = false>
; __device__ __forceinline__ void gemm_phase(PG8_LAS unsigned char* lds, const Gemm g, const Sched& S, const Epi& E) {
;     ...
;             PG8_LDA(At, 1, 1); PG8_STAGE(PG8_SB(1, 0), b3, voffB); PG8_STAGE(PG8_SB(1, 1), b3 + hstep, voffB); PG8_STAGE(PG8_SA(1, 0), a3, voffA);
;             PG8_WAIT_V(8); PG8_WAIT_L(0); PG8_BAR; PG8_MMA(1, 0, At, B0); PG8_MMA(1, 1, At, B1); PG8_BAR; PG8_SCHED;
;     ...
;         if constexpr (ALIGN_EPI) { if (wr == 0) PG8_BAR; }
	s_add_i32 s54, s72, s27
	v_lshl_add_u64 v[214:215], v[214:215], 0, s[14:15]
	s_mov_b32 m0, s54
	ds_read_b128 v[182:185], v157 offset:49152
	ds_read_b128 v[186:189], v157 offset:50176
	ds_read_b128 v[190:193], v157 offset:51200
	ds_read_b128 v[194:197], v157 offset:52224
	ds_read_b128 v[198:201], v157 offset:53248
	ds_read_b128 v[202:205], v157 offset:54272
	ds_read_b128 v[206:209], v157 offset:55296
	ds_read_b128 v[210:213], v157 offset:56320
	global_load_lds_dwordx4 v[214:215], off
	s_add_i32 m0, s54, 0x2000
	s_add_u32 s52, s52, 0x80080
	v_lshl_add_u64 v[214:215], v[216:217], 0, s[14:15]
	s_addc_u32 s53, s53, 0
	s_add_i32 s54, s73, s27
	global_load_lds_dwordx4 v[214:215], off
	v_lshl_add_u64 v[214:215], s[52:53], 0, v[132:133]
	s_mov_b32 m0, s54
	s_nop 0
	global_load_lds_dwordx4 v[214:215], off
	v_lshl_add_u64 v[214:215], s[52:53], 0, v[128:129]
	s_add_i32 m0, s54, 0x2000
	s_nop 0
	global_load_lds_dwordx4 v[214:215], off
	v_lshl_add_u64 v[214:215], v[218:219], 0, s[14:15]
	s_mov_b32 m0, s59
	s_nop 0
	global_load_lds_dwordx4 v[214:215], off
	v_lshl_add_u64 v[214:215], v[222:223], 0, s[14:15]
	s_mov_b32 m0, s60
	s_nop 0
	global_load_lds_dwordx4 v[214:215], off
	s_sleep 1
	s_waitcnt vmcnt(8)
	s_waitcnt lgkmcnt(0)
	s_barrier
	s_setprio 1
	s_waitcnt lgkmcnt(0)
	v_mfma_f32_16x16x32_bf16 v[60:63], v[144:147], v[182:185], v[60:63]
	v_mfma_f32_16x16x32_bf16 v[56:59], v[158:161], v[182:185], v[56:59]
	v_mfma_f32_16x16x32_bf16 v[44:47], v[144:147], v[190:193], v[44:47]
	v_mfma_f32_16x16x32_bf16 v[40:43], v[158:161], v[190:193], v[40:43]
	v_mfma_f32_16x16x32_bf16 v[28:31], v[144:147], v[198:201], v[28:31]
	v_mfma_f32_16x16x32_bf16 v[24:27], v[158:161], v[198:201], v[24:27]
	v_mfma_f32_16x16x32_bf16 v[12:15], v[144:147], v[206:209], v[12:15]
	v_mfma_f32_16x16x32_bf16 v[8:11], v[158:161], v[206:209], v[8:11]
	v_mfma_f32_16x16x32_bf16 v[60:63], v[148:151], v[186:189], v[60:63]
	v_mfma_f32_16x16x32_bf16 v[56:59], v[162:165], v[186:189], v[56:59]
	v_mfma_f32_16x16x32_bf16 v[44:47], v[148:151], v[194:197], v[44:47]
	v_mfma_f32_16x16x32_bf16 v[40:43], v[162:165], v[194:197], v[40:43]
	v_mfma_f32_16x16x32_bf16 v[28:31], v[148:151], v[202:205], v[28:31]
	v_mfma_f32_16x16x32_bf16 v[24:27], v[162:165], v[202:205], v[24:27]
	v_mfma_f32_16x16x32_bf16 v[12:15], v[148:151], v[210:213], v[12:15]
	v_mfma_f32_16x16x32_bf16 v[8:11], v[162:165], v[210:213], v[8:11]
	s_setprio 0
	s_setprio 1
	v_mfma_f32_16x16x32_bf16 v[52:55], v[166:169], v[182:185], v[52:55]
	v_mfma_f32_16x16x32_bf16 v[48:51], v[174:177], v[182:185], v[48:51]
	v_mfma_f32_16x16x32_bf16 v[36:39], v[166:169], v[190:193], v[36:39]
	v_mfma_f32_16x16x32_bf16 v[32:35], v[174:177], v[190:193], v[32:35]
	v_mfma_f32_16x16x32_bf16 v[20:23], v[166:169], v[198:201], v[20:23]
	v_mfma_f32_16x16x32_bf16 v[16:19], v[174:177], v[198:201], v[16:19]
	v_mfma_f32_16x16x32_bf16 v[4:7], v[166:169], v[206:209], v[4:7]
	v_mfma_f32_16x16x32_bf16 v[0:3], v[174:177], v[206:209], v[0:3]
	v_mfma_f32_16x16x32_bf16 v[52:55], v[170:173], v[186:189], v[52:55]
	v_mfma_f32_16x16x32_bf16 v[48:51], v[178:181], v[186:189], v[48:51]
	v_mfma_f32_16x16x32_bf16 v[36:39], v[170:173], v[194:197], v[36:39]
	v_mfma_f32_16x16x32_bf16 v[32:35], v[178:181], v[194:197], v[32:35]
	v_mfma_f32_16x16x32_bf16 v[20:23], v[170:173], v[202:205], v[20:23]
	v_mfma_f32_16x16x32_bf16 v[16:19], v[178:181], v[202:205], v[16:19]
	v_mfma_f32_16x16x32_bf16 v[4:7], v[170:173], v[210:213], v[4:7]
	v_mfma_f32_16x16x32_bf16 v[0:3], v[178:181], v[210:213], v[0:3]
	s_setprio 0
	s_barrier
	s_add_i32 s71, s71, 2
	s_add_u32 s50, s50, 0x100
	s_addc_u32 s51, s51, 0
	s_add_u32 s69, s69, 0x100
	s_addc_u32 s70, s70, 0
	s_cmp_gt_u32 s71, 29
	s_cbranch_scc0 .LBB0_1027
	s_and_b64 vcc, exec, s[16:17]
	s_cbranch_vccz .LBB0_1030
	s_barrier

; #define PG8_STAGE(bufoff, gbase, voff) do { _Pragma("unroll") for (int _i = 0; _i < 2; ++_i) \
;         __builtin_amdgcn_global_load_lds((const unsigned*)((const char*)(gbase) + (voff)[_i]), (PG8_LAS unsigned*)(lds + (bufoff) + ldsw + _i * 8192), 16, 0, 0); } while (0)
; #define PG8_LDA(dst, b, h) do { _Pragma("unroll") for (int m = 0; m < 4; ++m) _Pragma("unroll") for (int k = 0; k < 2; ++k) dst[m][k] = *(const PG8_LAS bf16x8*)(lds + PG8_SA(b, h) + aoff + m * 2048 + k * 1024); } while (0)
; #define PG8_LDB(dst, b, h) do { _Pragma("unroll") for (int n = 0; n < 2; ++n) _Pragma("unroll") for (int k = 0; k < 2; ++k) dst[n][k] = *(const PG8_LAS bf16x8*)(lds + PG8_SB(b, h) + boff + n * 2048 + k * 1024); } while (0)
; #define PG8_MMA(ai, bj, At, Bt) do { __builtin_amdgcn_s_setprio(1); _Pragma("unroll") for (int m = 0; m < 4; ++m) _Pragma("unroll") for (int n = 0; n < 2; ++n) _Pragma("unroll") for (int k = 0; k < 2; ++k) \
;         acc[ai][bj][m][n] = __builtin_amdgcn_mfma_f32_16x16x32_bf16(Bt[n][k], At[m][k], acc[ai][bj][m][n], 0, 0, 0); __builtin_amdgcn_s_setprio(0); } while (0)
; #define PG8_WAIT_V(n) asm volatile("s_waitcnt vmcnt(" #n ")" ::: "memory")
; #define PG8_WAIT_L(n) asm volatile("s_waitcnt lgkmcnt(" #n ")" ::: "memory")
; template <class Epi, class Sched, bool ALIGN_EPI = false, bool SP2 = false>
; __device__ __forceinline__ void gemm_phase(PG8_LAS unsigned char* lds, const Gemm g, const Sched& S, const Epi& E) {
;     ...
;             const bool last = (t == nt - 2);
;             const char* a1 = cA + (size_t)(t + 1) * kstep;
;             const char* a2 = last ? nA : cA + (size_t)(t + 2) * kstep; const char* b2 = last ? nB : cB + (size_t)(t + 2) * kstep;
;             const char* a3 = a2 + kstep; const char* b3 = b2 + kstep;
;             if (last && has_next) S.a_ready(nxt);
;             if constexpr (SP2) {
;             PG8_LDB(B0, 0, 0); PG8_LDB(B1, 0, 1); PG8_SCHED; PG8_LDA(At, 0, 0); PG8_STAGE(PG8_SA(1, 1), a1 + hstep, voffA);
;             PG8_WAIT_V(8); PG8_WAIT_L(0); PG8_BAR; PG8_MMA(0, 0, At, B0); PG8_MMA(0, 1, At, B1); PG8_BAR; PG8_SCHED;
;             PG8_LDA(At, 0, 1); PG8_STAGE(PG8_SB(0, 0), b2, voffB); PG8_STAGE(PG8_SB(0, 1), b2 + hstep, voffB); PG8_STAGE(PG8_SA(0, 0), a2, voffA);
;             PG8_WAIT_V(8); PG8_WAIT_L(0); PG8_BAR; PG8_MMA(1, 0, At, B0); PG8_MMA(1, 1, At, B1); PG8_BAR; PG8_SCHED;
.LBB0_1222:
	ds_read_b128 v[92:95], v212
	ds_read_b128 v[100:103], v212 offset:1024
	ds_read_b128 v[104:107], v212 offset:2048
	ds_read_b128 v[172:175], v212 offset:3072
	ds_read_b128 v[176:179], v213
	ds_read_b128 v[180:183], v213 offset:1024
	ds_read_b128 v[184:187], v213 offset:2048
	ds_read_b128 v[188:191], v213 offset:3072
	s_add_u32 s38, s36, 0x100
	s_addc_u32 s39, s37, 0
	s_add_u32 s40, s62, s36
	s_addc_u32 s41, s63, s37
	s_cmp_eq_u32 s64, 28
	s_cselect_b32 s42, s61, s40
	s_cselect_b32 s40, 0, s38
	s_cselect_b32 s43, s31, s41
	s_cselect_b32 s41, 0, s39
	s_add_u32 s40, s18, s40
	s_addc_u32 s41, s19, s41
	s_mov_b32 m0, s52
	v_lshl_add_u64 v[234:235], v[88:89], 0, s[36:37]
	ds_read_b128 v[192:195], v214
	ds_read_b128 v[196:199], v214 offset:1024
	ds_read_b128 v[200:203], v214 offset:2048
	ds_read_b128 v[204:207], v214 offset:3072
	ds_read_b128 v[208:211], v214 offset:4096
	ds_read_b128 v[222:225], v214 offset:5120
	ds_read_b128 v[226:229], v214 offset:6144
	ds_read_b128 v[230:233], v214 offset:7168
	global_load_lds_dwordx4 v[234:235], off
	v_lshl_add_u64 v[234:235], v[90:91], 0, s[36:37]
	s_mov_b32 m0, s53
	s_nop 0
	global_load_lds_dwordx4 v[234:235], off
	s_sleep 1
	s_waitcnt vmcnt(8)
	s_waitcnt lgkmcnt(0)
	s_barrier
	s_setprio 1
	s_waitcnt lgkmcnt(0)
	v_mfma_f32_16x16x32_bf16 v[140:143], v[92:95], v[192:195], v[140:143]
	v_mfma_f32_16x16x32_bf16 v[136:139], v[104:107], v[192:195], v[136:139]
	v_mfma_f32_16x16x32_bf16 v[124:127], v[92:95], v[200:203], v[124:127]
	v_mfma_f32_16x16x32_bf16 v[120:123], v[104:107], v[200:203], v[120:123]
	v_mfma_f32_16x16x32_bf16 v[108:111], v[92:95], v[208:211], v[108:111]
	v_mfma_f32_16x16x32_bf16 v[96:99], v[104:107], v[208:211], v[96:99]
	v_mfma_f32_16x16x32_bf16 v[76:79], v[92:95], v[226:229], v[76:79]
	v_mfma_f32_16x16x32_bf16 v[72:75], v[104:107], v[226:229], v[72:75]
	v_mfma_f32_16x16x32_bf16 v[140:143], v[100:103], v[196:199], v[140:143]
	v_mfma_f32_16x16x32_bf16 v[136:139], v[172:175], v[196:199], v[136:139]
	v_mfma_f32_16x16x32_bf16 v[124:127], v[100:103], v[204:207], v[124:127]
	v_mfma_f32_16x16x32_bf16 v[120:123], v[172:175], v[204:207], v[120:123]
	v_mfma_f32_16x16x32_bf16 v[108:111], v[100:103], v[222:225], v[108:111]
	v_mfma_f32_16x16x32_bf16 v[96:99], v[172:175], v[222:225], v[96:99]
	v_mfma_f32_16x16x32_bf16 v[76:79], v[100:103], v[230:233], v[76:79]
	v_mfma_f32_16x16x32_bf16 v[72:75], v[172:175], v[230:233], v[72:75]
	s_setprio 0
	s_setprio 1
	v_mfma_f32_16x16x32_bf16 v[132:135], v[176:179], v[192:195], v[132:135]
	v_mfma_f32_16x16x32_bf16 v[128:131], v[184:187], v[192:195], v[128:131]
	v_mfma_f32_16x16x32_bf16 v[116:119], v[176:179], v[200:203], v[116:119]
	v_mfma_f32_16x16x32_bf16 v[112:115], v[184:187], v[200:203], v[112:115]
	v_mfma_f32_16x16x32_bf16 v[84:87], v[176:179], v[208:211], v[84:87]
	v_mfma_f32_16x16x32_bf16 v[80:83], v[184:187], v[208:211], v[80:83]
	v_mfma_f32_16x16x32_bf16 v[68:71], v[176:179], v[226:229], v[68:71]
	v_mfma_f32_16x16x32_bf16 v[64:67], v[184:187], v[226:229], v[64:67]
	v_mfma_f32_16x16x32_bf16 v[132:135], v[180:183], v[196:199], v[132:135]
	v_mfma_f32_16x16x32_bf16 v[128:131], v[188:191], v[196:199], v[128:131]
	v_mfma_f32_16x16x32_bf16 v[116:119], v[180:183], v[204:207], v[116:119]
	v_mfma_f32_16x16x32_bf16 v[112:115], v[188:191], v[204:207], v[112:115]
	v_mfma_f32_16x16x32_bf16 v[84:87], v[180:183], v[222:225], v[84:87]
	v_mfma_f32_16x16x32_bf16 v[80:83], v[188:191], v[222:225], v[80:83]
	v_mfma_f32_16x16x32_bf16 v[68:71], v[180:183], v[230:233], v[68:71]
	v_mfma_f32_16x16x32_bf16 v[64:67], v[188:191], v[230:233], v[64:67]
	s_setprio 0
	s_barrier
	s_mov_b32 m0, s54
	v_lshl_add_u64 v[234:235], s[40:41], 0, v[146:147]
	s_add_u32 s36, s40, 0x80000
	ds_read_b128 v[192:195], v214 offset:16384
	ds_read_b128 v[196:199], v214 offset:17408
	ds_read_b128 v[200:203], v214 offset:18432
	ds_read_b128 v[204:207], v214 offset:19456
	ds_read_b128 v[208:211], v214 offset:20480
	ds_read_b128 v[222:225], v214 offset:21504
	ds_read_b128 v[226:229], v214 offset:22528
	ds_read_b128 v[230:233], v214 offset:23552
	global_load_lds_dwordx4 v[234:235], off
	v_lshl_add_u64 v[236:237], s[40:41], 0, v[144:145]
	s_mov_b32 m0, s55
	s_addc_u32 s37, s41, 0
	global_load_lds_dwordx4 v[236:237], off
	v_lshl_add_u64 v[238:239], s[36:37], 0, v[146:147]
	s_mov_b32 m0, s56
	v_lshl_add_u64 v[240:241], s[42:43], 0, v[144:145]
	global_load_lds_dwordx4 v[238:239], off
	v_lshl_add_u64 v[238:239], s[36:37], 0, v[144:145]
	s_mov_b32 m0, s57
	s_nop 0
	global_load_lds_dwordx4 v[238:239], off
	v_lshl_add_u64 v[238:239], s[42:43], 0, v[146:147]
	s_mov_b32 m0, s17
	s_nop 0
	global_load_lds_dwordx4 v[238:239], off
	s_mov_b32 m0, s45
	s_nop 0
	global_load_lds_dwordx4 v[240:241], off
	s_sleep 1
	s_waitcnt vmcnt(8)
	s_waitcnt lgkmcnt(0)
	s_barrier
; #define PG8_STAGE(bufoff, gbase, voff) do { _Pragma("unroll") for (int _i = 0; _i < 2; ++_i) \
;         __builtin_amdgcn_global_load_lds((const unsigned*)((const char*)(gbase) + (voff)[_i]), (PG8_LAS unsigned*)(lds + (bufoff) + ldsw + _i * 8192), 16, 0, 0); } while (0)
; #define PG8_LDA(dst, b, h) do { _Pragma("unroll") for (int m = 0; m < 4; ++m) _Pragma("unroll") for (int k = 0; k < 2; ++k) dst[m][k] = *(const PG8_LAS bf16x8*)(lds + PG8_SA(b, h) + aoff + m * 2048 + k * 1024); } while (0)
; #define PG8_LDB(dst, b, h) do { _Pragma("unroll") for (int n = 0; n < 2; ++n) _Pragma("unroll") for (int k = 0; k < 2; ++k) dst[n][k] = *(const PG8_LAS bf16x8*)(lds + PG8_SB(b, h) + boff + n * 2048 + k * 1024); } while (0)
; #define PG8_MMA(ai, bj, At, Bt) do { __builtin_amdgcn_s_setprio(1); _Pragma("unroll") for (int m = 0; m < 4; ++m) _Pragma("unroll") for (int n = 0; n < 2; ++n) _Pragma("unroll") for (int k = 0; k < 2; ++k) \
;         acc[ai][bj][m][n] = __builtin_amdgcn_mfma_f32_16x16x32_bf16(Bt[n][k], At[m][k], acc[ai][bj][m][n], 0, 0, 0); __builtin_amdgcn_s_setprio(0); } while (0)
; #define PG8_WAIT_V(n) asm volatile("s_waitcnt vmcnt(" #n ")" ::: "memory")
; #define PG8_WAIT_L(n) asm volatile("s_waitcnt lgkmcnt(" #n ")" ::: "memory")
; #define PG8_BAR __builtin_amdgcn_s_barrier()
; #define PG8_SCHED __builtin_amdgcn_sched_barrier(0)
; template <class Epi, class Sched, bool ALIGN_EPI = false, bool SP2 = false>
; __device__ __forceinline__ void gemm_phase(PG8_LAS unsigned char* lds, const Gemm g, const Sched& S, const Epi& E) {
;     ...
;             PG8_WAIT_V(8); PG8_WAIT_L(0); PG8_BAR; PG8_MMA(1, 0, At, B0); PG8_MMA(1, 1, At, B1); PG8_BAR; PG8_SCHED;
;             PG8_LDB(B0, 1, 0); PG8_LDB(B1, 1, 1); PG8_SCHED; PG8_LDA(At, 1, 0); PG8_STAGE(PG8_SA(0, 1), a2 + hstep, voffA);
;             PG8_WAIT_V(8); PG8_WAIT_L(0); PG8_BAR; PG8_MMA(0, 0, At, B0); PG8_MMA(0, 1, At, B1); PG8_BAR; PG8_SCHED;
	s_setprio 1
	s_waitcnt lgkmcnt(0)
	v_mfma_f32_16x16x32_bf16 v[60:63], v[92:95], v[192:195], v[60:63]
	v_mfma_f32_16x16x32_bf16 v[56:59], v[104:107], v[192:195], v[56:59]
	v_mfma_f32_16x16x32_bf16 v[44:47], v[92:95], v[200:203], v[44:47]
	v_mfma_f32_16x16x32_bf16 v[40:43], v[104:107], v[200:203], v[40:43]
	v_mfma_f32_16x16x32_bf16 v[28:31], v[92:95], v[208:211], v[28:31]
	v_mfma_f32_16x16x32_bf16 v[24:27], v[104:107], v[208:211], v[24:27]
	v_mfma_f32_16x16x32_bf16 v[12:15], v[92:95], v[226:229], v[12:15]
	v_mfma_f32_16x16x32_bf16 v[8:11], v[104:107], v[226:229], v[8:11]
	v_mfma_f32_16x16x32_bf16 v[60:63], v[100:103], v[196:199], v[60:63]
	v_mfma_f32_16x16x32_bf16 v[56:59], v[172:175], v[196:199], v[56:59]
	v_mfma_f32_16x16x32_bf16 v[44:47], v[100:103], v[204:207], v[44:47]
	v_mfma_f32_16x16x32_bf16 v[40:43], v[172:175], v[204:207], v[40:43]
	v_mfma_f32_16x16x32_bf16 v[28:31], v[100:103], v[222:225], v[28:31]
	v_mfma_f32_16x16x32_bf16 v[24:27], v[172:175], v[222:225], v[24:27]
	v_mfma_f32_16x16x32_bf16 v[12:15], v[100:103], v[230:233], v[12:15]
	v_mfma_f32_16x16x32_bf16 v[8:11], v[172:175], v[230:233], v[8:11]
	s_setprio 0
	s_setprio 1
	v_mfma_f32_16x16x32_bf16 v[52:55], v[176:179], v[192:195], v[52:55]
	v_mfma_f32_16x16x32_bf16 v[48:51], v[184:187], v[192:195], v[48:51]
	v_mfma_f32_16x16x32_bf16 v[36:39], v[176:179], v[200:203], v[36:39]
	v_mfma_f32_16x16x32_bf16 v[32:35], v[184:187], v[200:203], v[32:35]
	v_mfma_f32_16x16x32_bf16 v[20:23], v[176:179], v[208:211], v[20:23]
	v_mfma_f32_16x16x32_bf16 v[16:19], v[184:187], v[208:211], v[16:19]
	v_mfma_f32_16x16x32_bf16 v[4:7], v[176:179], v[226:229], v[4:7]
	v_mfma_f32_16x16x32_bf16 v[0:3], v[184:187], v[226:229], v[0:3]
	v_mfma_f32_16x16x32_bf16 v[52:55], v[180:183], v[196:199], v[52:55]
	v_mfma_f32_16x16x32_bf16 v[48:51], v[188:191], v[196:199], v[48:51]
	v_mfma_f32_16x16x32_bf16 v[36:39], v[180:183], v[204:207], v[36:39]
	v_mfma_f32_16x16x32_bf16 v[32:35], v[188:191], v[204:207], v[32:35]
	v_mfma_f32_16x16x32_bf16 v[20:23], v[180:183], v[222:225], v[20:23]
	v_mfma_f32_16x16x32_bf16 v[16:19], v[188:191], v[222:225], v[16:19]
	v_mfma_f32_16x16x32_bf16 v[4:7], v[180:183], v[230:233], v[4:7]
	v_mfma_f32_16x16x32_bf16 v[0:3], v[188:191], v[230:233], v[0:3]
	s_setprio 0
	s_barrier
	ds_read_b128 v[92:95], v216
	ds_read_b128 v[100:103], v216 offset:1024
	ds_read_b128 v[104:107], v216 offset:2048
	ds_read_b128 v[172:175], v216 offset:3072
	ds_read_b128 v[176:179], v217
	ds_read_b128 v[180:183], v217 offset:1024
	ds_read_b128 v[184:187], v217 offset:2048
	ds_read_b128 v[188:191], v217 offset:3072
	s_add_u32 s36, s42, 0x80000
	s_addc_u32 s37, s43, 0
	s_mov_b32 m0, s46
	v_lshl_add_u64 v[242:243], s[36:37], 0, v[146:147]
	ds_read_b128 v[192:195], v214 offset:32768
	ds_read_b128 v[196:199], v214 offset:33792
	ds_read_b128 v[200:203], v214 offset:34816
	ds_read_b128 v[204:207], v214 offset:35840
	ds_read_b128 v[208:211], v214 offset:36864
	ds_read_b128 v[222:225], v214 offset:37888
	ds_read_b128 v[226:229], v214 offset:38912
	ds_read_b128 v[230:233], v214 offset:39936
	global_load_lds_dwordx4 v[242:243], off
	v_lshl_add_u64 v[242:243], s[36:37], 0, v[144:145]
	s_mov_b32 m0, s47
	s_nop 0
	global_load_lds_dwordx4 v[242:243], off
	s_sleep 1
	s_waitcnt vmcnt(8)
	s_waitcnt lgkmcnt(0)
	s_barrier
	s_setprio 1
	s_waitcnt lgkmcnt(0)
	v_mfma_f32_16x16x32_bf16 v[140:143], v[92:95], v[192:195], v[140:143]
	v_mfma_f32_16x16x32_bf16 v[136:139], v[104:107], v[192:195], v[136:139]
	v_mfma_f32_16x16x32_bf16 v[124:127], v[92:95], v[200:203], v[124:127]
	v_mfma_f32_16x16x32_bf16 v[120:123], v[104:107], v[200:203], v[120:123]
	v_mfma_f32_16x16x32_bf16 v[108:111], v[92:95], v[208:211], v[108:111]
	v_mfma_f32_16x16x32_bf16 v[96:99], v[104:107], v[208:211], v[96:99]
	v_mfma_f32_16x16x32_bf16 v[76:79], v[92:95], v[226:229], v[76:79]
	v_mfma_f32_16x16x32_bf16 v[72:75], v[104:107], v[226:229], v[72:75]
	v_mfma_f32_16x16x32_bf16 v[140:143], v[100:103], v[196:199], v[140:143]
	v_mfma_f32_16x16x32_bf16 v[136:139], v[172:175], v[196:199], v[136:139]
	v_mfma_f32_16x16x32_bf16 v[124:127], v[100:103], v[204:207], v[124:127]
	v_mfma_f32_16x16x32_bf16 v[120:123], v[172:175], v[204:207], v[120:123]
	v_mfma_f32_16x16x32_bf16 v[108:111], v[100:103], v[222:225], v[108:111]
	v_mfma_f32_16x16x32_bf16 v[96:99], v[172:175], v[222:225], v[96:99]
	v_mfma_f32_16x16x32_bf16 v[76:79], v[100:103], v[230:233], v[76:79]
	v_mfma_f32_16x16x32_bf16 v[72:75], v[172:175], v[230:233], v[72:75]
	s_setprio 0
	s_setprio 1
	v_mfma_f32_16x16x32_bf16 v[132:135], v[176:179], v[192:195], v[132:135]
	v_mfma_f32_16x16x32_bf16 v[128:131], v[184:187], v[192:195], v[128:131]
	v_mfma_f32_16x16x32_bf16 v[116:119], v[176:179], v[200:203], v[116:119]
	v_mfma_f32_16x16x32_bf16 v[112:115], v[184:187], v[200:203], v[112:115]
	v_mfma_f32_16x16x32_bf16 v[84:87], v[176:179], v[208:211], v[84:87]
	v_mfma_f32_16x16x32_bf16 v[80:83], v[184:187], v[208:211], v[80:83]
	v_mfma_f32_16x16x32_bf16 v[68:71], v[176:179], v[226:229], v[68:71]
	v_mfma_f32_16x16x32_bf16 v[64:67], v[184:187], v[226:229], v[64:67]
	v_mfma_f32_16x16x32_bf16 v[132:135], v[180:183], v[196:199], v[132:135]
	v_mfma_f32_16x16x32_bf16 v[128:131], v[188:191], v[196:199], v[128:131]
	v_mfma_f32_16x16x32_bf16 v[116:119], v[180:183], v[204:207], v[116:119]
	v_mfma_f32_16x16x32_bf16 v[112:115], v[188:191], v[204:207], v[112:115]
	v_mfma_f32_16x16x32_bf16 v[84:87], v[180:183], v[222:225], v[84:87]
	v_mfma_f32_16x16x32_bf16 v[80:83], v[188:191], v[222:225], v[80:83]
	v_mfma_f32_16x16x32_bf16 v[68:71], v[180:183], v[230:233], v[68:71]
	v_mfma_f32_16x16x32_bf16 v[64:67], v[188:191], v[230:233], v[64:67]
	s_setprio 0
	s_barrier
; #define PG8_STAGE(bufoff, gbase, voff) do { _Pragma("unroll") for (int _i = 0; _i < 2; ++_i) \
;         __builtin_amdgcn_global_load_lds((const unsigned*)((const char*)(gbase) + (voff)[_i]), (PG8_LAS unsigned*)(lds + (bufoff) + ldsw + _i * 8192), 16, 0, 0); } while (0)
; #define PG8_LDA(dst, b, h) do { _Pragma("unroll") for (int m = 0; m < 4; ++m) _Pragma("unroll") for (int k = 0; k < 2; ++k) dst[m][k] = *(const PG8_LAS bf16x8*)(lds + PG8_SA(b, h) + aoff + m * 2048 + k * 1024); } while (0)
; #define PG8_MMA(ai, bj, At, Bt) do { __builtin_amdgcn_s_setprio(1); _Pragma("unroll") for (int m = 0; m < 4; ++m) _Pragma("unroll") for (int n = 0; n < 2; ++n) _Pragma("unroll") for (int k = 0; k < 2; ++k) \
;         acc[ai][bj][m][n] = __builtin_amdgcn_mfma_f32_16x16x32_bf16(Bt[n][k], At[m][k], acc[ai][bj][m][n], 0, 0, 0); __builtin_amdgcn_s_setprio(0); } while (0)
; #define PG8_WAIT_V(n) asm volatile("s_waitcnt vmcnt(" #n ")" ::: "memory")
; #define PG8_WAIT_L(n) asm volatile("s_waitcnt lgkmcnt(" #n ")" ::: "memory")
; #define PG8_BAR __builtin_amdgcn_s_barrier()
; #define PG8_SCHED __builtin_amdgcn_sched_barrier(0)
; template <class Epi, class Sched, bool ALIGN_EPI = false, bool SP2 = false>
; __device__ __forceinline__ void gemm_phase(PG8_LAS unsigned char* lds, const Gemm g, const Sched& S, const Epi& E) {
;     ...
;             PG8_LDA(At, 1, 1); PG8_STAGE(PG8_SB(1, 0), b3, voffB); PG8_STAGE(PG8_SB(1, 1), b3 + hstep, voffB); PG8_STAGE(PG8_SA(1, 0), a3, voffA);
;             PG8_WAIT_V(8); PG8_WAIT_L(0); PG8_BAR; PG8_MMA(1, 0, At, B0); PG8_MMA(1, 1, At, B1); PG8_BAR; PG8_SCHED;
;     ...
;         if constexpr (ALIGN_EPI) { if (wr == 0) PG8_BAR; }
	s_add_i32 s36, s58, s44
	v_lshl_add_u64 v[234:235], v[234:235], 0, s[28:29]
	s_mov_b32 m0, s36
	ds_read_b128 v[192:195], v214 offset:49152
	ds_read_b128 v[196:199], v214 offset:50176
	ds_read_b128 v[200:203], v214 offset:51200
	ds_read_b128 v[204:207], v214 offset:52224
	ds_read_b128 v[208:211], v214 offset:53248
	ds_read_b128 v[222:225], v214 offset:54272
	ds_read_b128 v[226:229], v214 offset:55296
	ds_read_b128 v[230:233], v214 offset:56320
	global_load_lds_dwordx4 v[234:235], off
	s_add_i32 m0, s36, 0x2000
	s_add_u32 s36, s40, 0x80080
	v_lshl_add_u64 v[234:235], v[236:237], 0, s[28:29]
	s_addc_u32 s37, s41, 0
	s_add_i32 s40, s59, s44
	global_load_lds_dwordx4 v[234:235], off
	v_lshl_add_u64 v[234:235], s[36:37], 0, v[146:147]
	s_mov_b32 m0, s40
	s_nop 0
	global_load_lds_dwordx4 v[234:235], off
	v_lshl_add_u64 v[234:235], s[36:37], 0, v[144:145]
	s_add_i32 m0, s40, 0x2000
	s_nop 0
	global_load_lds_dwordx4 v[234:235], off
	v_lshl_add_u64 v[234:235], v[238:239], 0, s[28:29]
	s_mov_b32 m0, s50
	s_nop 0
	global_load_lds_dwordx4 v[234:235], off
	v_lshl_add_u64 v[234:235], v[240:241], 0, s[28:29]
	s_mov_b32 m0, s51
	s_nop 0
	global_load_lds_dwordx4 v[234:235], off
	s_sleep 1
	s_waitcnt vmcnt(8)
	s_waitcnt lgkmcnt(0)
	s_barrier
	s_setprio 1
	s_waitcnt lgkmcnt(0)
	v_mfma_f32_16x16x32_bf16 v[60:63], v[92:95], v[192:195], v[60:63]
	v_mfma_f32_16x16x32_bf16 v[56:59], v[104:107], v[192:195], v[56:59]
	v_mfma_f32_16x16x32_bf16 v[44:47], v[92:95], v[200:203], v[44:47]
	v_mfma_f32_16x16x32_bf16 v[40:43], v[104:107], v[200:203], v[40:43]
	v_mfma_f32_16x16x32_bf16 v[28:31], v[92:95], v[208:211], v[28:31]
	v_mfma_f32_16x16x32_bf16 v[24:27], v[104:107], v[208:211], v[24:27]
	v_mfma_f32_16x16x32_bf16 v[12:15], v[92:95], v[226:229], v[12:15]
	v_mfma_f32_16x16x32_bf16 v[8:11], v[104:107], v[226:229], v[8:11]
	v_mfma_f32_16x16x32_bf16 v[60:63], v[100:103], v[196:199], v[60:63]
	v_mfma_f32_16x16x32_bf16 v[56:59], v[172:175], v[196:199], v[56:59]
	v_mfma_f32_16x16x32_bf16 v[44:47], v[100:103], v[204:207], v[44:47]
	v_mfma_f32_16x16x32_bf16 v[40:43], v[172:175], v[204:207], v[40:43]
	v_mfma_f32_16x16x32_bf16 v[28:31], v[100:103], v[222:225], v[28:31]
	v_mfma_f32_16x16x32_bf16 v[24:27], v[172:175], v[222:225], v[24:27]
	v_mfma_f32_16x16x32_bf16 v[12:15], v[100:103], v[230:233], v[12:15]
	v_mfma_f32_16x16x32_bf16 v[8:11], v[172:175], v[230:233], v[8:11]
	s_setprio 0
	s_setprio 1
	v_mfma_f32_16x16x32_bf16 v[52:55], v[176:179], v[192:195], v[52:55]
	v_mfma_f32_16x16x32_bf16 v[48:51], v[184:187], v[192:195], v[48:51]
	v_mfma_f32_16x16x32_bf16 v[36:39], v[176:179], v[200:203], v[36:39]
	v_mfma_f32_16x16x32_bf16 v[32:35], v[184:187], v[200:203], v[32:35]
	v_mfma_f32_16x16x32_bf16 v[20:23], v[176:179], v[208:211], v[20:23]
	v_mfma_f32_16x16x32_bf16 v[16:19], v[184:187], v[208:211], v[16:19]
	v_mfma_f32_16x16x32_bf16 v[4:7], v[176:179], v[226:229], v[4:7]
	v_mfma_f32_16x16x32_bf16 v[0:3], v[184:187], v[226:229], v[0:3]
	v_mfma_f32_16x16x32_bf16 v[52:55], v[180:183], v[196:199], v[52:55]
	v_mfma_f32_16x16x32_bf16 v[48:51], v[188:191], v[196:199], v[48:51]
	v_mfma_f32_16x16x32_bf16 v[36:39], v[180:183], v[204:207], v[36:39]
	v_mfma_f32_16x16x32_bf16 v[32:35], v[188:191], v[204:207], v[32:35]
	v_mfma_f32_16x16x32_bf16 v[20:23], v[180:183], v[222:225], v[20:23]
	v_mfma_f32_16x16x32_bf16 v[16:19], v[188:191], v[222:225], v[16:19]
	v_mfma_f32_16x16x32_bf16 v[4:7], v[180:183], v[230:233], v[4:7]
	v_mfma_f32_16x16x32_bf16 v[0:3], v[188:191], v[230:233], v[0:3]
	s_setprio 0
	s_barrier
	s_add_i32 s64, s64, 2
	s_cmp_gt_u32 s64, 29
	s_mov_b64 s[36:37], s[38:39]
	s_cbranch_scc0 .LBB0_1222
	s_and_b64 vcc, exec, s[4:5]
	s_cbranch_vccz .LBB0_1225
	s_barrier

; #define PG8_STAGE(bufoff, gbase, voff) do { _Pragma("unroll") for (int _i = 0; _i < 2; ++_i) \
;         __builtin_amdgcn_global_load_lds((const unsigned*)((const char*)(gbase) + (voff)[_i]), (PG8_LAS unsigned*)(lds + (bufoff) + ldsw + _i * 8192), 16, 0, 0); } while (0)
; #define PG8_LDA(dst, b, h) do { _Pragma("unroll") for (int m = 0; m < 4; ++m) _Pragma("unroll") for (int k = 0; k < 2; ++k) dst[m][k] = *(const PG8_LAS bf16x8*)(lds + PG8_SA(b, h) + aoff + m * 2048 + k * 1024); } while (0)
; #define PG8_LDB(dst, b, h) do { _Pragma("unroll") for (int n = 0; n < 2; ++n) _Pragma("unroll") for (int k = 0; k < 2; ++k) dst[n][k] = *(const PG8_LAS bf16x8*)(lds + PG8_SB(b, h) + boff + n * 2048 + k * 1024); } while (0)
; #define PG8_MMA(ai, bj, At, Bt) do { __builtin_amdgcn_s_setprio(1); _Pragma("unroll") for (int m = 0; m < 4; ++m) _Pragma("unroll") for (int n = 0; n < 2; ++n) _Pragma("unroll") for (int k = 0; k < 2; ++k) \
;         acc[ai][bj][m][n] = __builtin_amdgcn_mfma_f32_16x16x32_bf16(Bt[n][k], At[m][k], acc[ai][bj][m][n], 0, 0, 0); __builtin_amdgcn_s_setprio(0); } while (0)
; #define PG8_WAIT_V(n) asm volatile("s_waitcnt vmcnt(" #n ")" ::: "memory")
; #define PG8_WAIT_L(n) asm volatile("s_waitcnt lgkmcnt(" #n ")" ::: "memory")
; template <class Epi, class Sched, bool ALIGN_EPI = false, bool SP2 = false>
; __device__ __forceinline__ void gemm_phase(PG8_LAS unsigned char* lds, const Gemm g, const Sched& S, const Epi& E) {
;     ...
;             const bool last = (t == nt - 2);
;             const char* a1 = cA + (size_t)(t + 1) * kstep;
;             const char* a2 = last ? nA : cA + (size_t)(t + 2) * kstep; const char* b2 = last ? nB : cB + (size_t)(t + 2) * kstep;
;             const char* a3 = a2 + kstep; const char* b3 = b2 + kstep;
;             if (last && has_next) S.a_ready(nxt);
;             if constexpr (SP2) {
;             PG8_LDB(B0, 0, 0); PG8_LDB(B1, 0, 1); PG8_SCHED; PG8_LDA(At, 0, 0); PG8_STAGE(PG8_SA(1, 1), a1 + hstep, voffA);
;             PG8_WAIT_V(8); PG8_WAIT_L(0); PG8_BAR; PG8_MMA(0, 0, At, B0); PG8_MMA(0, 1, At, B1); PG8_BAR; PG8_SCHED;
;             PG8_LDA(At, 0, 1); PG8_STAGE(PG8_SB(0, 0), b2, voffB); PG8_STAGE(PG8_SB(0, 1), b2 + hstep, voffB); PG8_STAGE(PG8_SA(0, 0), a2, voffA);
;             PG8_WAIT_V(8); PG8_WAIT_L(0); PG8_BAR; PG8_MMA(1, 0, At, B0); PG8_MMA(1, 1, At, B1); PG8_BAR; PG8_SCHED;
.LBB0_1274:
	ds_read_b128 v[128:131], v165
	ds_read_b128 v[132:135], v165 offset:1024
	ds_read_b128 v[136:139], v165 offset:2048
	ds_read_b128 v[140:143], v165 offset:3072
	ds_read_b128 v[156:159], v166
	ds_read_b128 v[168:171], v166 offset:1024
	ds_read_b128 v[172:175], v166 offset:2048
	ds_read_b128 v[176:179], v166 offset:3072
	s_add_u32 s28, s26, 0x100
	s_addc_u32 s29, s27, 0
	s_cmp_eq_u32 s57, 28
	s_cselect_b32 s35, s19, s29
	s_cselect_b32 s34, s53, s28
	s_cselect_b32 s31, s17, s56
	s_cselect_b32 s30, s54, s55
	v_lshl_add_u64 v[160:161], s[26:27], 0, v[148:149]
	s_add_i32 m0, s25, 0xc000
	ds_read_b128 v[180:183], v167
	ds_read_b128 v[184:187], v167 offset:1024
	ds_read_b128 v[188:191], v167 offset:2048
	ds_read_b128 v[192:195], v167 offset:3072
	ds_read_b128 v[196:199], v167 offset:4096
	ds_read_b128 v[200:203], v167 offset:5120
	ds_read_b128 v[204:207], v167 offset:6144
	ds_read_b128 v[208:211], v167 offset:7168
	global_load_lds_dwordx4 v[160:161], off
	v_lshl_add_u64 v[160:161], s[26:27], 0, v[150:151]
	s_add_i32 m0, s25, 0xe000
	s_nop 0
	global_load_lds_dwordx4 v[160:161], off
	s_sleep 1
	s_waitcnt vmcnt(8)
	s_waitcnt lgkmcnt(0)
	s_barrier
	s_setprio 1
	s_waitcnt lgkmcnt(0)
	v_mfma_f32_16x16x32_bf16 v[124:127], v[128:131], v[180:183], v[124:127]
	v_mfma_f32_16x16x32_bf16 v[120:123], v[136:139], v[180:183], v[120:123]
	v_mfma_f32_16x16x32_bf16 v[116:119], v[128:131], v[188:191], v[116:119]
	v_mfma_f32_16x16x32_bf16 v[112:115], v[136:139], v[188:191], v[112:115]
	v_mfma_f32_16x16x32_bf16 v[92:95], v[128:131], v[196:199], v[92:95]
	v_mfma_f32_16x16x32_bf16 v[88:91], v[136:139], v[196:199], v[88:91]
	v_mfma_f32_16x16x32_bf16 v[84:87], v[128:131], v[204:207], v[84:87]
	v_mfma_f32_16x16x32_bf16 v[80:83], v[136:139], v[204:207], v[80:83]
	v_mfma_f32_16x16x32_bf16 v[124:127], v[132:135], v[184:187], v[124:127]
	v_mfma_f32_16x16x32_bf16 v[120:123], v[140:143], v[184:187], v[120:123]
	v_mfma_f32_16x16x32_bf16 v[116:119], v[132:135], v[192:195], v[116:119]
	v_mfma_f32_16x16x32_bf16 v[112:115], v[140:143], v[192:195], v[112:115]
	v_mfma_f32_16x16x32_bf16 v[92:95], v[132:135], v[200:203], v[92:95]
	v_mfma_f32_16x16x32_bf16 v[88:91], v[140:143], v[200:203], v[88:91]
	v_mfma_f32_16x16x32_bf16 v[84:87], v[132:135], v[208:211], v[84:87]
	v_mfma_f32_16x16x32_bf16 v[80:83], v[140:143], v[208:211], v[80:83]
	s_setprio 0
	s_setprio 1
	v_mfma_f32_16x16x32_bf16 v[108:111], v[156:159], v[180:183], v[108:111]
	v_mfma_f32_16x16x32_bf16 v[104:107], v[172:175], v[180:183], v[104:107]
	v_mfma_f32_16x16x32_bf16 v[100:103], v[156:159], v[188:191], v[100:103]
	v_mfma_f32_16x16x32_bf16 v[96:99], v[172:175], v[188:191], v[96:99]
	v_mfma_f32_16x16x32_bf16 v[76:79], v[156:159], v[196:199], v[76:79]
	v_mfma_f32_16x16x32_bf16 v[72:75], v[172:175], v[196:199], v[72:75]
	v_mfma_f32_16x16x32_bf16 v[68:71], v[156:159], v[204:207], v[68:71]
	v_mfma_f32_16x16x32_bf16 v[64:67], v[172:175], v[204:207], v[64:67]
	v_mfma_f32_16x16x32_bf16 v[108:111], v[168:171], v[184:187], v[108:111]
	v_mfma_f32_16x16x32_bf16 v[104:107], v[176:179], v[184:187], v[104:107]
	v_mfma_f32_16x16x32_bf16 v[100:103], v[168:171], v[192:195], v[100:103]
	v_mfma_f32_16x16x32_bf16 v[96:99], v[176:179], v[192:195], v[96:99]
	v_mfma_f32_16x16x32_bf16 v[76:79], v[168:171], v[200:203], v[76:79]
	v_mfma_f32_16x16x32_bf16 v[72:75], v[176:179], v[200:203], v[72:75]
	v_mfma_f32_16x16x32_bf16 v[68:71], v[168:171], v[208:211], v[68:71]
	v_mfma_f32_16x16x32_bf16 v[64:67], v[176:179], v[208:211], v[64:67]
	s_setprio 0
	s_barrier
	s_add_i32 s26, s49, s40
	v_lshl_add_u64 v[160:161], s[30:31], 0, v[144:145]
	s_mov_b32 m0, s26
	ds_read_b128 v[180:183], v167 offset:16384
	ds_read_b128 v[184:187], v167 offset:17408
	ds_read_b128 v[188:191], v167 offset:18432
	ds_read_b128 v[192:195], v167 offset:19456
	ds_read_b128 v[196:199], v167 offset:20480
	ds_read_b128 v[200:203], v167 offset:21504
	ds_read_b128 v[204:207], v167 offset:22528
	ds_read_b128 v[208:211], v167 offset:23552
	global_load_lds_dwordx4 v[160:161], off
	s_add_i32 m0, s26, 0x2000
	s_add_u32 s26, s30, 0x80000
	v_lshl_add_u64 v[212:213], s[30:31], 0, v[146:147]
	s_addc_u32 s27, s31, 0
	s_add_i32 s58, s50, s40
	global_load_lds_dwordx4 v[212:213], off
	v_lshl_add_u64 v[214:215], s[26:27], 0, v[144:145]
	s_mov_b32 m0, s58
	v_lshl_add_u64 v[216:217], s[34:35], 0, v[146:147]
	global_load_lds_dwordx4 v[214:215], off
	v_lshl_add_u64 v[214:215], s[26:27], 0, v[146:147]
	s_add_i32 m0, s58, 0x2000
	s_nop 0
	global_load_lds_dwordx4 v[214:215], off
	v_lshl_add_u64 v[214:215], s[34:35], 0, v[144:145]
	s_mov_b32 m0, s25
	s_nop 0
	global_load_lds_dwordx4 v[214:215], off
	s_mov_b32 m0, s41
	s_nop 0
	global_load_lds_dwordx4 v[216:217], off
	s_sleep 1
	s_waitcnt vmcnt(8)
	s_waitcnt lgkmcnt(0)
	s_barrier
; #define PG8_STAGE(bufoff, gbase, voff) do { _Pragma("unroll") for (int _i = 0; _i < 2; ++_i) \
;         __builtin_amdgcn_global_load_lds((const unsigned*)((const char*)(gbase) + (voff)[_i]), (PG8_LAS unsigned*)(lds + (bufoff) + ldsw + _i * 8192), 16, 0, 0); } while (0)
; #define PG8_LDA(dst, b, h) do { _Pragma("unroll") for (int m = 0; m < 4; ++m) _Pragma("unroll") for (int k = 0; k < 2; ++k) dst[m][k] = *(const PG8_LAS bf16x8*)(lds + PG8_SA(b, h) + aoff + m * 2048 + k * 1024); } while (0)
; #define PG8_LDB(dst, b, h) do { _Pragma("unroll") for (int n = 0; n < 2; ++n) _Pragma("unroll") for (int k = 0; k < 2; ++k) dst[n][k] = *(const PG8_LAS bf16x8*)(lds + PG8_SB(b, h) + boff + n * 2048 + k * 1024); } while (0)
; #define PG8_MMA(ai, bj, At, Bt) do { __builtin_amdgcn_s_setprio(1); _Pragma("unroll") for (int m = 0; m < 4; ++m) _Pragma("unroll") for (int n = 0; n < 2; ++n) _Pragma("unroll") for (int k = 0; k < 2; ++k) \
;         acc[ai][bj][m][n] = __builtin_amdgcn_mfma_f32_16x16x32_bf16(Bt[n][k], At[m][k], acc[ai][bj][m][n], 0, 0, 0); __builtin_amdgcn_s_setprio(0); } while (0)
; #define PG8_WAIT_V(n) asm volatile("s_waitcnt vmcnt(" #n ")" ::: "memory")
; #define PG8_WAIT_L(n) asm volatile("s_waitcnt lgkmcnt(" #n ")" ::: "memory")
; #define PG8_BAR __builtin_amdgcn_s_barrier()
; #define PG8_SCHED __builtin_amdgcn_sched_barrier(0)
; template <class Epi, class Sched, bool ALIGN_EPI = false, bool SP2 = false>
; __device__ __forceinline__ void gemm_phase(PG8_LAS unsigned char* lds, const Gemm g, const Sched& S, const Epi& E) {
;     ...
;             PG8_WAIT_V(8); PG8_WAIT_L(0); PG8_BAR; PG8_MMA(1, 0, At, B0); PG8_MMA(1, 1, At, B1); PG8_BAR; PG8_SCHED;
;             PG8_LDB(B0, 1, 0); PG8_LDB(B1, 1, 1); PG8_SCHED; PG8_LDA(At, 1, 0); PG8_STAGE(PG8_SA(0, 1), a2 + hstep, voffA);
;             PG8_WAIT_V(8); PG8_WAIT_L(0); PG8_BAR; PG8_MMA(0, 0, At, B0); PG8_MMA(0, 1, At, B1); PG8_BAR; PG8_SCHED;
	s_setprio 1
	s_waitcnt lgkmcnt(0)
	v_mfma_f32_16x16x32_bf16 v[60:63], v[128:131], v[180:183], v[60:63]
	v_mfma_f32_16x16x32_bf16 v[56:59], v[136:139], v[180:183], v[56:59]
	v_mfma_f32_16x16x32_bf16 v[52:55], v[128:131], v[188:191], v[52:55]
	v_mfma_f32_16x16x32_bf16 v[48:51], v[136:139], v[188:191], v[48:51]
	v_mfma_f32_16x16x32_bf16 v[36:39], v[128:131], v[196:199], v[36:39]
	v_mfma_f32_16x16x32_bf16 v[24:27], v[136:139], v[196:199], v[24:27]
	v_mfma_f32_16x16x32_bf16 v[16:19], v[128:131], v[204:207], v[16:19]
	v_mfma_f32_16x16x32_bf16 v[8:11], v[136:139], v[204:207], v[8:11]
	v_mfma_f32_16x16x32_bf16 v[60:63], v[132:135], v[184:187], v[60:63]
	v_mfma_f32_16x16x32_bf16 v[56:59], v[140:143], v[184:187], v[56:59]
	v_mfma_f32_16x16x32_bf16 v[52:55], v[132:135], v[192:195], v[52:55]
	v_mfma_f32_16x16x32_bf16 v[48:51], v[140:143], v[192:195], v[48:51]
	v_mfma_f32_16x16x32_bf16 v[36:39], v[132:135], v[200:203], v[36:39]
	v_mfma_f32_16x16x32_bf16 v[24:27], v[140:143], v[200:203], v[24:27]
	v_mfma_f32_16x16x32_bf16 v[16:19], v[132:135], v[208:211], v[16:19]
	v_mfma_f32_16x16x32_bf16 v[8:11], v[140:143], v[208:211], v[8:11]
	s_setprio 0
	s_setprio 1
	v_mfma_f32_16x16x32_bf16 v[44:47], v[156:159], v[180:183], v[44:47]
	v_mfma_f32_16x16x32_bf16 v[40:43], v[172:175], v[180:183], v[40:43]
	v_mfma_f32_16x16x32_bf16 v[32:35], v[156:159], v[188:191], v[32:35]
	v_mfma_f32_16x16x32_bf16 v[28:31], v[172:175], v[188:191], v[28:31]
	v_mfma_f32_16x16x32_bf16 v[20:23], v[156:159], v[196:199], v[20:23]
	v_mfma_f32_16x16x32_bf16 v[12:15], v[172:175], v[196:199], v[12:15]
	v_mfma_f32_16x16x32_bf16 v[4:7], v[156:159], v[204:207], v[4:7]
	v_mfma_f32_16x16x32_bf16 v[0:3], v[172:175], v[204:207], v[0:3]
	v_mfma_f32_16x16x32_bf16 v[44:47], v[168:171], v[184:187], v[44:47]
	v_mfma_f32_16x16x32_bf16 v[40:43], v[176:179], v[184:187], v[40:43]
	v_mfma_f32_16x16x32_bf16 v[32:35], v[168:171], v[192:195], v[32:35]
	v_mfma_f32_16x16x32_bf16 v[28:31], v[176:179], v[192:195], v[28:31]
	v_mfma_f32_16x16x32_bf16 v[20:23], v[168:171], v[200:203], v[20:23]
	v_mfma_f32_16x16x32_bf16 v[12:15], v[176:179], v[200:203], v[12:15]
	v_mfma_f32_16x16x32_bf16 v[4:7], v[168:171], v[208:211], v[4:7]
	v_mfma_f32_16x16x32_bf16 v[0:3], v[176:179], v[208:211], v[0:3]
	s_setprio 0
	s_barrier
	s_add_i32 s58, 0, 0x18000
	s_add_i32 s59, 0, 0x1c000
	v_add_u32_e32 v140, s58, v163
	v_add_u32_e32 v176, s59, v163
	ds_read_b128 v[128:131], v140
	ds_read_b128 v[132:135], v140 offset:1024
	ds_read_b128 v[136:139], v140 offset:2048
	ds_read_b128 v[140:143], v140 offset:3072
	ds_read_b128 v[156:159], v176
	ds_read_b128 v[168:171], v176 offset:1024
	ds_read_b128 v[172:175], v176 offset:2048
	ds_read_b128 v[176:179], v176 offset:3072
	s_add_u32 s26, s34, 0x80000
	s_addc_u32 s27, s35, 0
	s_mov_b32 m0, s42
	v_lshl_add_u64 v[218:219], s[26:27], 0, v[144:145]
	ds_read_b128 v[180:183], v167 offset:32768
	ds_read_b128 v[184:187], v167 offset:33792
	ds_read_b128 v[188:191], v167 offset:34816
	ds_read_b128 v[192:195], v167 offset:35840
	ds_read_b128 v[196:199], v167 offset:36864
	ds_read_b128 v[200:203], v167 offset:37888
	ds_read_b128 v[204:207], v167 offset:38912
	ds_read_b128 v[208:211], v167 offset:39936
	global_load_lds_dwordx4 v[218:219], off
	v_lshl_add_u64 v[218:219], s[26:27], 0, v[146:147]
	s_mov_b32 m0, s43
	s_nop 0
	global_load_lds_dwordx4 v[218:219], off
	s_sleep 1
	s_waitcnt vmcnt(8)
	s_waitcnt lgkmcnt(0)
	s_barrier
	s_setprio 1
	s_waitcnt lgkmcnt(0)
	v_mfma_f32_16x16x32_bf16 v[124:127], v[128:131], v[180:183], v[124:127]
	v_mfma_f32_16x16x32_bf16 v[120:123], v[136:139], v[180:183], v[120:123]
	v_mfma_f32_16x16x32_bf16 v[116:119], v[128:131], v[188:191], v[116:119]
	v_mfma_f32_16x16x32_bf16 v[112:115], v[136:139], v[188:191], v[112:115]
	v_mfma_f32_16x16x32_bf16 v[92:95], v[128:131], v[196:199], v[92:95]
	v_mfma_f32_16x16x32_bf16 v[88:91], v[136:139], v[196:199], v[88:91]
	v_mfma_f32_16x16x32_bf16 v[84:87], v[128:131], v[204:207], v[84:87]
	v_mfma_f32_16x16x32_bf16 v[80:83], v[136:139], v[204:207], v[80:83]
	v_mfma_f32_16x16x32_bf16 v[124:127], v[132:135], v[184:187], v[124:127]
	v_mfma_f32_16x16x32_bf16 v[120:123], v[140:143], v[184:187], v[120:123]
	v_mfma_f32_16x16x32_bf16 v[116:119], v[132:135], v[192:195], v[116:119]
	v_mfma_f32_16x16x32_bf16 v[112:115], v[140:143], v[192:195], v[112:115]
	v_mfma_f32_16x16x32_bf16 v[92:95], v[132:135], v[200:203], v[92:95]
	v_mfma_f32_16x16x32_bf16 v[88:91], v[140:143], v[200:203], v[88:91]
	v_mfma_f32_16x16x32_bf16 v[84:87], v[132:135], v[208:211], v[84:87]
	v_mfma_f32_16x16x32_bf16 v[80:83], v[140:143], v[208:211], v[80:83]
	s_setprio 0
	s_setprio 1
	v_mfma_f32_16x16x32_bf16 v[108:111], v[156:159], v[180:183], v[108:111]
	v_mfma_f32_16x16x32_bf16 v[104:107], v[172:175], v[180:183], v[104:107]
	v_mfma_f32_16x16x32_bf16 v[100:103], v[156:159], v[188:191], v[100:103]
	v_mfma_f32_16x16x32_bf16 v[96:99], v[172:175], v[188:191], v[96:99]
	v_mfma_f32_16x16x32_bf16 v[76:79], v[156:159], v[196:199], v[76:79]
	v_mfma_f32_16x16x32_bf16 v[72:75], v[172:175], v[196:199], v[72:75]
	v_mfma_f32_16x16x32_bf16 v[68:71], v[156:159], v[204:207], v[68:71]
	v_mfma_f32_16x16x32_bf16 v[64:67], v[172:175], v[204:207], v[64:67]
	v_mfma_f32_16x16x32_bf16 v[108:111], v[168:171], v[184:187], v[108:111]
	v_mfma_f32_16x16x32_bf16 v[104:107], v[176:179], v[184:187], v[104:107]
	v_mfma_f32_16x16x32_bf16 v[100:103], v[168:171], v[192:195], v[100:103]
	v_mfma_f32_16x16x32_bf16 v[96:99], v[176:179], v[192:195], v[96:99]
	v_mfma_f32_16x16x32_bf16 v[76:79], v[168:171], v[200:203], v[76:79]
	v_mfma_f32_16x16x32_bf16 v[72:75], v[176:179], v[200:203], v[72:75]
	v_mfma_f32_16x16x32_bf16 v[68:71], v[168:171], v[208:211], v[68:71]
	v_mfma_f32_16x16x32_bf16 v[64:67], v[176:179], v[208:211], v[64:67]
	s_setprio 0
	s_barrier
; #define PG8_STAGE(bufoff, gbase, voff) do { _Pragma("unroll") for (int _i = 0; _i < 2; ++_i) \
;         __builtin_amdgcn_global_load_lds((const unsigned*)((const char*)(gbase) + (voff)[_i]), (PG8_LAS unsigned*)(lds + (bufoff) + ldsw + _i * 8192), 16, 0, 0); } while (0)
; #define PG8_LDA(dst, b, h) do { _Pragma("unroll") for (int m = 0; m < 4; ++m) _Pragma("unroll") for (int k = 0; k < 2; ++k) dst[m][k] = *(const PG8_LAS bf16x8*)(lds + PG8_SA(b, h) + aoff + m * 2048 + k * 1024); } while (0)
; #define PG8_MMA(ai, bj, At, Bt) do { __builtin_amdgcn_s_setprio(1); _Pragma("unroll") for (int m = 0; m < 4; ++m) _Pragma("unroll") for (int n = 0; n < 2; ++n) _Pragma("unroll") for (int k = 0; k < 2; ++k) \
;         acc[ai][bj][m][n] = __builtin_amdgcn_mfma_f32_16x16x32_bf16(Bt[n][k], At[m][k], acc[ai][bj][m][n], 0, 0, 0); __builtin_amdgcn_s_setprio(0); } while (0)
; #define PG8_WAIT_V(n) asm volatile("s_waitcnt vmcnt(" #n ")" ::: "memory")
; #define PG8_WAIT_L(n) asm volatile("s_waitcnt lgkmcnt(" #n ")" ::: "memory")
; #define PG8_BAR __builtin_amdgcn_s_barrier()
; #define PG8_SCHED __builtin_amdgcn_sched_barrier(0)
; template <class Epi, class Sched, bool ALIGN_EPI = false, bool SP2 = false>
; __device__ __forceinline__ void gemm_phase(PG8_LAS unsigned char* lds, const Gemm g, const Sched& S, const Epi& E) {
;     ...
;             PG8_LDA(At, 1, 1); PG8_STAGE(PG8_SB(1, 0), b3, voffB); PG8_STAGE(PG8_SB(1, 1), b3 + hstep, voffB); PG8_STAGE(PG8_SA(1, 0), a3, voffA);
;             PG8_WAIT_V(8); PG8_WAIT_L(0); PG8_BAR; PG8_MMA(1, 0, At, B0); PG8_MMA(1, 1, At, B1); PG8_BAR; PG8_SCHED;
;     ...
;         if constexpr (ALIGN_EPI) { if (wr == 0) PG8_BAR; }
	s_add_i32 s26, s58, s40
	v_lshl_add_u64 v[160:161], v[160:161], 0, s[8:9]
	s_mov_b32 m0, s26
	ds_read_b128 v[180:183], v167 offset:49152
	ds_read_b128 v[184:187], v167 offset:50176
	ds_read_b128 v[188:191], v167 offset:51200
	ds_read_b128 v[192:195], v167 offset:52224
	ds_read_b128 v[196:199], v167 offset:53248
	ds_read_b128 v[200:203], v167 offset:54272
	ds_read_b128 v[204:207], v167 offset:55296
	ds_read_b128 v[208:211], v167 offset:56320
	global_load_lds_dwordx4 v[160:161], off
	s_add_i32 m0, s26, 0x2000
	s_add_u32 s26, s30, 0x80080
	v_lshl_add_u64 v[160:161], v[212:213], 0, s[8:9]
	s_addc_u32 s27, s31, 0
	s_add_i32 s30, s59, s40
	global_load_lds_dwordx4 v[160:161], off
	v_lshl_add_u64 v[160:161], s[26:27], 0, v[144:145]
	s_mov_b32 m0, s30
	s_nop 0
	global_load_lds_dwordx4 v[160:161], off
	v_lshl_add_u64 v[160:161], s[26:27], 0, v[146:147]
	s_add_i32 m0, s30, 0x2000
	s_nop 0
	global_load_lds_dwordx4 v[160:161], off
	v_lshl_add_u64 v[160:161], v[214:215], 0, s[8:9]
	s_mov_b32 m0, s47
	s_nop 0
	global_load_lds_dwordx4 v[160:161], off
	v_lshl_add_u64 v[160:161], v[216:217], 0, s[8:9]
	s_mov_b32 m0, s48
	s_nop 0
	global_load_lds_dwordx4 v[160:161], off
	s_sleep 1
	s_waitcnt vmcnt(8)
	s_waitcnt lgkmcnt(0)
	s_barrier
	s_setprio 1
	s_waitcnt lgkmcnt(0)
	v_mfma_f32_16x16x32_bf16 v[60:63], v[128:131], v[180:183], v[60:63]
	v_mfma_f32_16x16x32_bf16 v[56:59], v[136:139], v[180:183], v[56:59]
	v_mfma_f32_16x16x32_bf16 v[52:55], v[128:131], v[188:191], v[52:55]
	v_mfma_f32_16x16x32_bf16 v[48:51], v[136:139], v[188:191], v[48:51]
	v_mfma_f32_16x16x32_bf16 v[36:39], v[128:131], v[196:199], v[36:39]
	v_mfma_f32_16x16x32_bf16 v[24:27], v[136:139], v[196:199], v[24:27]
	v_mfma_f32_16x16x32_bf16 v[16:19], v[128:131], v[204:207], v[16:19]
	v_mfma_f32_16x16x32_bf16 v[8:11], v[136:139], v[204:207], v[8:11]
	v_mfma_f32_16x16x32_bf16 v[60:63], v[132:135], v[184:187], v[60:63]
	v_mfma_f32_16x16x32_bf16 v[56:59], v[140:143], v[184:187], v[56:59]
	v_mfma_f32_16x16x32_bf16 v[52:55], v[132:135], v[192:195], v[52:55]
	v_mfma_f32_16x16x32_bf16 v[48:51], v[140:143], v[192:195], v[48:51]
	v_mfma_f32_16x16x32_bf16 v[36:39], v[132:135], v[200:203], v[36:39]
	v_mfma_f32_16x16x32_bf16 v[24:27], v[140:143], v[200:203], v[24:27]
	v_mfma_f32_16x16x32_bf16 v[16:19], v[132:135], v[208:211], v[16:19]
	v_mfma_f32_16x16x32_bf16 v[8:11], v[140:143], v[208:211], v[8:11]
	s_setprio 0
	s_setprio 1
	v_mfma_f32_16x16x32_bf16 v[44:47], v[156:159], v[180:183], v[44:47]
	v_mfma_f32_16x16x32_bf16 v[40:43], v[172:175], v[180:183], v[40:43]
	v_mfma_f32_16x16x32_bf16 v[32:35], v[156:159], v[188:191], v[32:35]
	v_mfma_f32_16x16x32_bf16 v[28:31], v[172:175], v[188:191], v[28:31]
	v_mfma_f32_16x16x32_bf16 v[20:23], v[156:159], v[196:199], v[20:23]
	v_mfma_f32_16x16x32_bf16 v[12:15], v[172:175], v[196:199], v[12:15]
	v_mfma_f32_16x16x32_bf16 v[4:7], v[156:159], v[204:207], v[4:7]
	v_mfma_f32_16x16x32_bf16 v[0:3], v[172:175], v[204:207], v[0:3]
	v_mfma_f32_16x16x32_bf16 v[44:47], v[168:171], v[184:187], v[44:47]
	v_mfma_f32_16x16x32_bf16 v[40:43], v[176:179], v[184:187], v[40:43]
	v_mfma_f32_16x16x32_bf16 v[32:35], v[168:171], v[192:195], v[32:35]
	v_mfma_f32_16x16x32_bf16 v[28:31], v[176:179], v[192:195], v[28:31]
	v_mfma_f32_16x16x32_bf16 v[20:23], v[168:171], v[200:203], v[20:23]
	v_mfma_f32_16x16x32_bf16 v[12:15], v[176:179], v[200:203], v[12:15]
	v_mfma_f32_16x16x32_bf16 v[4:7], v[168:171], v[208:211], v[4:7]
	v_mfma_f32_16x16x32_bf16 v[0:3], v[176:179], v[208:211], v[0:3]
	s_setprio 0
	s_barrier
	s_add_i32 s57, s57, 2
	s_add_u32 s55, s55, 0x100
	s_addc_u32 s56, s56, 0
	s_cmp_gt_u32 s57, 29
	s_mov_b64 s[26:27], s[28:29]
	s_cbranch_scc0 .LBB0_1274
	s_and_b64 vcc, exec, s[10:11]
	s_cbranch_vccz .LBB0_1277
	s_barrier

; #define PG8_STAGE(bufoff, gbase, voff) do { _Pragma("unroll") for (int _i = 0; _i < 2; ++_i) \
;         __builtin_amdgcn_global_load_lds((const unsigned*)((const char*)(gbase) + (voff)[_i]), (PG8_LAS unsigned*)(lds + (bufoff) + ldsw + _i * 8192), 16, 0, 0); } while (0)
; #define PG8_LDA(dst, b, h) do { _Pragma("unroll") for (int m = 0; m < 4; ++m) _Pragma("unroll") for (int k = 0; k < 2; ++k) dst[m][k] = *(const PG8_LAS bf16x8*)(lds + PG8_SA(b, h) + aoff + m * 2048 + k * 1024); } while (0)
; #define PG8_LDB(dst, b, h) do { _Pragma("unroll") for (int n = 0; n < 2; ++n) _Pragma("unroll") for (int k = 0; k < 2; ++k) dst[n][k] = *(const PG8_LAS bf16x8*)(lds + PG8_SB(b, h) + boff + n * 2048 + k * 1024); } while (0)
; #define PG8_MMA(ai, bj, At, Bt) do { __builtin_amdgcn_s_setprio(1); _Pragma("unroll") for (int m = 0; m < 4; ++m) _Pragma("unroll") for (int n = 0; n < 2; ++n) _Pragma("unroll") for (int k = 0; k < 2; ++k) \
;         acc[ai][bj][m][n] = __builtin_amdgcn_mfma_f32_16x16x32_bf16(Bt[n][k], At[m][k], acc[ai][bj][m][n], 0, 0, 0); __builtin_amdgcn_s_setprio(0); } while (0)
; #define PG8_WAIT_V(n) asm volatile("s_waitcnt vmcnt(" #n ")" ::: "memory")
; #define PG8_WAIT_L(n) asm volatile("s_waitcnt lgkmcnt(" #n ")" ::: "memory")
; template <class Epi, class Sched, bool ALIGN_EPI = false, bool SP2 = false>
; __device__ __forceinline__ void gemm_phase(PG8_LAS unsigned char* lds, const Gemm g, const Sched& S, const Epi& E) {
;     ...
;             const bool last = (t == nt - 2);
;             const char* a1 = cA + (size_t)(t + 1) * kstep;
;             const char* a2 = last ? nA : cA + (size_t)(t + 2) * kstep; const char* b2 = last ? nB : cB + (size_t)(t + 2) * kstep;
;             const char* a3 = a2 + kstep; const char* b3 = b2 + kstep;
;             if (last && has_next) S.a_ready(nxt);
;             if constexpr (SP2) {
;             PG8_LDB(B0, 0, 0); PG8_LDB(B1, 0, 1); PG8_SCHED; PG8_LDA(At, 0, 0); PG8_STAGE(PG8_SA(1, 1), a1 + hstep, voffA);
;             PG8_WAIT_V(8); PG8_WAIT_L(0); PG8_BAR; PG8_MMA(0, 0, At, B0); PG8_MMA(0, 1, At, B1); PG8_BAR; PG8_SCHED;
;             PG8_LDA(At, 0, 1); PG8_STAGE(PG8_SB(0, 0), b2, voffB); PG8_STAGE(PG8_SB(0, 1), b2 + hstep, voffB); PG8_STAGE(PG8_SA(0, 0), a2, voffA);
;             PG8_WAIT_V(8); PG8_WAIT_L(0); PG8_BAR; PG8_MMA(1, 0, At, B0); PG8_MMA(1, 1, At, B1); PG8_BAR; PG8_SCHED;
.LBB0_1399:
	ds_read_b128 v[120:123], v196
	ds_read_b128 v[124:127], v196 offset:1024
	ds_read_b128 v[128:131], v196 offset:2048
	ds_read_b128 v[132:135], v196 offset:3072
	ds_read_b128 v[136:139], v197
	ds_read_b128 v[140:143], v197 offset:1024
	ds_read_b128 v[144:147], v197 offset:2048
	ds_read_b128 v[148:151], v197 offset:3072
	s_add_u32 s54, s4, 0xfff80080
	s_addc_u32 s55, s5, -1
	s_cmp_eq_u32 s81, 28
	s_cselect_b32 s57, s49, s55
	s_cselect_b32 s56, s77, s54
	s_cselect_b32 s55, s47, s80
	s_cselect_b32 s54, s78, s79
	v_lshl_add_u64 v[188:189], s[4:5], 0, v[174:175]
	s_add_i32 m0, s63, 0xc000
	ds_read_b128 v[160:163], v198
	ds_read_b128 v[164:167], v198 offset:1024
	ds_read_b128 v[180:183], v198 offset:2048
	ds_read_b128 v[184:187], v198 offset:3072
	ds_read_b128 v[202:205], v198 offset:4096
	ds_read_b128 v[206:209], v198 offset:5120
	ds_read_b128 v[210:213], v198 offset:6144
	ds_read_b128 v[214:217], v198 offset:7168
	global_load_lds_dwordx4 v[188:189], off
	v_lshl_add_u64 v[188:189], s[4:5], 0, v[172:173]
	s_add_i32 m0, s63, 0xe000
	s_nop 0
	global_load_lds_dwordx4 v[188:189], off
	s_sleep 1
	s_waitcnt vmcnt(8)
	s_waitcnt lgkmcnt(0)
	s_barrier
	s_setprio 1
	s_waitcnt lgkmcnt(0)
	v_mfma_f32_16x16x32_bf16 v[156:159], v[120:123], v[160:163], v[156:159]
	v_mfma_f32_16x16x32_bf16 v[60:63], v[128:131], v[160:163], v[60:63]
	v_mfma_f32_16x16x32_bf16 v[116:119], v[120:123], v[180:183], v[116:119]
	v_mfma_f32_16x16x32_bf16 v[52:55], v[128:131], v[180:183], v[52:55]
	v_mfma_f32_16x16x32_bf16 v[108:111], v[120:123], v[202:205], v[108:111]
	v_mfma_f32_16x16x32_bf16 v[44:47], v[128:131], v[202:205], v[44:47]
	v_mfma_f32_16x16x32_bf16 v[104:107], v[120:123], v[210:213], v[104:107]
	v_mfma_f32_16x16x32_bf16 v[40:43], v[128:131], v[210:213], v[40:43]
	v_mfma_f32_16x16x32_bf16 v[156:159], v[124:127], v[164:167], v[156:159]
	v_mfma_f32_16x16x32_bf16 v[60:63], v[132:135], v[164:167], v[60:63]
	v_mfma_f32_16x16x32_bf16 v[116:119], v[124:127], v[184:187], v[116:119]
	v_mfma_f32_16x16x32_bf16 v[52:55], v[132:135], v[184:187], v[52:55]
	v_mfma_f32_16x16x32_bf16 v[108:111], v[124:127], v[206:209], v[108:111]
	v_mfma_f32_16x16x32_bf16 v[44:47], v[132:135], v[206:209], v[44:47]
	v_mfma_f32_16x16x32_bf16 v[104:107], v[124:127], v[214:217], v[104:107]
	v_mfma_f32_16x16x32_bf16 v[40:43], v[132:135], v[214:217], v[40:43]
	s_setprio 0
	s_setprio 1
	v_mfma_f32_16x16x32_bf16 v[152:155], v[136:139], v[160:163], v[152:155]
	v_mfma_f32_16x16x32_bf16 v[56:59], v[144:147], v[160:163], v[56:59]
	v_mfma_f32_16x16x32_bf16 v[112:115], v[136:139], v[180:183], v[112:115]
	v_mfma_f32_16x16x32_bf16 v[48:51], v[144:147], v[180:183], v[48:51]
	v_mfma_f32_16x16x32_bf16 v[100:103], v[136:139], v[202:205], v[100:103]
	v_mfma_f32_16x16x32_bf16 v[36:39], v[144:147], v[202:205], v[36:39]
	v_mfma_f32_16x16x32_bf16 v[96:99], v[136:139], v[210:213], v[96:99]
	v_mfma_f32_16x16x32_bf16 v[32:35], v[144:147], v[210:213], v[32:35]
	v_mfma_f32_16x16x32_bf16 v[152:155], v[140:143], v[164:167], v[152:155]
	v_mfma_f32_16x16x32_bf16 v[56:59], v[148:151], v[164:167], v[56:59]
	v_mfma_f32_16x16x32_bf16 v[112:115], v[140:143], v[184:187], v[112:115]
	v_mfma_f32_16x16x32_bf16 v[48:51], v[148:151], v[184:187], v[48:51]
	v_mfma_f32_16x16x32_bf16 v[100:103], v[140:143], v[206:209], v[100:103]
	v_mfma_f32_16x16x32_bf16 v[36:39], v[148:151], v[206:209], v[36:39]
	v_mfma_f32_16x16x32_bf16 v[96:99], v[140:143], v[214:217], v[96:99]
	v_mfma_f32_16x16x32_bf16 v[32:35], v[148:151], v[214:217], v[32:35]
	s_setprio 0
	s_barrier
	s_add_i32 s82, s72, s62
	v_lshl_add_u64 v[188:189], s[54:55], 0, v[170:171]
	s_mov_b32 m0, s82
	ds_read_b128 v[160:163], v198 offset:16384
	ds_read_b128 v[164:167], v198 offset:17408
	ds_read_b128 v[180:183], v198 offset:18432
	ds_read_b128 v[184:187], v198 offset:19456
	ds_read_b128 v[202:205], v198 offset:20480
	ds_read_b128 v[206:209], v198 offset:21504
	ds_read_b128 v[210:213], v198 offset:22528
	ds_read_b128 v[214:217], v198 offset:23552
	global_load_lds_dwordx4 v[188:189], off
	s_add_i32 m0, s82, 0x2000
	s_add_u32 s82, s54, 0x80000
	v_lshl_add_u64 v[218:219], s[54:55], 0, v[168:169]
	s_addc_u32 s83, s55, 0
	s_add_i32 s85, s73, s62
	global_load_lds_dwordx4 v[218:219], off
	v_lshl_add_u64 v[222:223], s[82:83], 0, v[170:171]
	s_mov_b32 m0, s85
	v_lshl_add_u64 v[224:225], s[56:57], 0, v[168:169]
	global_load_lds_dwordx4 v[222:223], off
	v_lshl_add_u64 v[222:223], s[82:83], 0, v[168:169]
	s_add_i32 m0, s85, 0x2000
	s_nop 0
	global_load_lds_dwordx4 v[222:223], off
	v_lshl_add_u64 v[222:223], s[56:57], 0, v[170:171]
	s_mov_b32 m0, s63
	s_nop 0
	global_load_lds_dwordx4 v[222:223], off
	s_mov_b32 m0, s64
	s_nop 0
	global_load_lds_dwordx4 v[224:225], off
	s_sleep 1
	s_waitcnt vmcnt(8)
	s_waitcnt lgkmcnt(0)
	s_barrier
; #define PG8_STAGE(bufoff, gbase, voff) do { _Pragma("unroll") for (int _i = 0; _i < 2; ++_i) \
;         __builtin_amdgcn_global_load_lds((const unsigned*)((const char*)(gbase) + (voff)[_i]), (PG8_LAS unsigned*)(lds + (bufoff) + ldsw + _i * 8192), 16, 0, 0); } while (0)
; #define PG8_LDA(dst, b, h) do { _Pragma("unroll") for (int m = 0; m < 4; ++m) _Pragma("unroll") for (int k = 0; k < 2; ++k) dst[m][k] = *(const PG8_LAS bf16x8*)(lds + PG8_SA(b, h) + aoff + m * 2048 + k * 1024); } while (0)
; #define PG8_LDB(dst, b, h) do { _Pragma("unroll") for (int n = 0; n < 2; ++n) _Pragma("unroll") for (int k = 0; k < 2; ++k) dst[n][k] = *(const PG8_LAS bf16x8*)(lds + PG8_SB(b, h) + boff + n * 2048 + k * 1024); } while (0)
; #define PG8_MMA(ai, bj, At, Bt) do { __builtin_amdgcn_s_setprio(1); _Pragma("unroll") for (int m = 0; m < 4; ++m) _Pragma("unroll") for (int n = 0; n < 2; ++n) _Pragma("unroll") for (int k = 0; k < 2; ++k) \
;         acc[ai][bj][m][n] = __builtin_amdgcn_mfma_f32_16x16x32_bf16(Bt[n][k], At[m][k], acc[ai][bj][m][n], 0, 0, 0); __builtin_amdgcn_s_setprio(0); } while (0)
; #define PG8_WAIT_V(n) asm volatile("s_waitcnt vmcnt(" #n ")" ::: "memory")
; #define PG8_WAIT_L(n) asm volatile("s_waitcnt lgkmcnt(" #n ")" ::: "memory")
; #define PG8_BAR __builtin_amdgcn_s_barrier()
; #define PG8_SCHED __builtin_amdgcn_sched_barrier(0)
; template <class Epi, class Sched, bool ALIGN_EPI = false, bool SP2 = false>
; __device__ __forceinline__ void gemm_phase(PG8_LAS unsigned char* lds, const Gemm g, const Sched& S, const Epi& E) {
;     ...
;             PG8_WAIT_V(8); PG8_WAIT_L(0); PG8_BAR; PG8_MMA(1, 0, At, B0); PG8_MMA(1, 1, At, B1); PG8_BAR; PG8_SCHED;
;             PG8_LDB(B0, 1, 0); PG8_LDB(B1, 1, 1); PG8_SCHED; PG8_LDA(At, 1, 0); PG8_STAGE(PG8_SA(0, 1), a2 + hstep, voffA);
;             PG8_WAIT_V(8); PG8_WAIT_L(0); PG8_BAR; PG8_MMA(0, 0, At, B0); PG8_MMA(0, 1, At, B1); PG8_BAR; PG8_SCHED;
	s_setprio 1
	s_waitcnt lgkmcnt(0)
	v_mfma_f32_16x16x32_bf16 v[92:95], v[120:123], v[160:163], v[92:95]
	v_mfma_f32_16x16x32_bf16 v[28:31], v[128:131], v[160:163], v[28:31]
	v_mfma_f32_16x16x32_bf16 v[84:87], v[120:123], v[180:183], v[84:87]
	v_mfma_f32_16x16x32_bf16 v[20:23], v[128:131], v[180:183], v[20:23]
	v_mfma_f32_16x16x32_bf16 v[76:79], v[120:123], v[202:205], v[76:79]
	v_mfma_f32_16x16x32_bf16 v[12:15], v[128:131], v[202:205], v[12:15]
	v_mfma_f32_16x16x32_bf16 v[72:75], v[120:123], v[210:213], v[72:75]
	v_mfma_f32_16x16x32_bf16 v[8:11], v[128:131], v[210:213], v[8:11]
	v_mfma_f32_16x16x32_bf16 v[92:95], v[124:127], v[164:167], v[92:95]
	v_mfma_f32_16x16x32_bf16 v[28:31], v[132:135], v[164:167], v[28:31]
	v_mfma_f32_16x16x32_bf16 v[84:87], v[124:127], v[184:187], v[84:87]
	v_mfma_f32_16x16x32_bf16 v[20:23], v[132:135], v[184:187], v[20:23]
	v_mfma_f32_16x16x32_bf16 v[76:79], v[124:127], v[206:209], v[76:79]
	v_mfma_f32_16x16x32_bf16 v[12:15], v[132:135], v[206:209], v[12:15]
	v_mfma_f32_16x16x32_bf16 v[72:75], v[124:127], v[214:217], v[72:75]
	v_mfma_f32_16x16x32_bf16 v[8:11], v[132:135], v[214:217], v[8:11]
	s_setprio 0
	s_setprio 1
	v_mfma_f32_16x16x32_bf16 v[88:91], v[136:139], v[160:163], v[88:91]
	v_mfma_f32_16x16x32_bf16 v[24:27], v[144:147], v[160:163], v[24:27]
	v_mfma_f32_16x16x32_bf16 v[80:83], v[136:139], v[180:183], v[80:83]
	v_mfma_f32_16x16x32_bf16 v[16:19], v[144:147], v[180:183], v[16:19]
	v_mfma_f32_16x16x32_bf16 v[68:71], v[136:139], v[202:205], v[68:71]
	v_mfma_f32_16x16x32_bf16 v[4:7], v[144:147], v[202:205], v[4:7]
	v_mfma_f32_16x16x32_bf16 v[64:67], v[136:139], v[210:213], v[64:67]
	v_mfma_f32_16x16x32_bf16 v[0:3], v[144:147], v[210:213], v[0:3]
	v_mfma_f32_16x16x32_bf16 v[88:91], v[140:143], v[164:167], v[88:91]
	v_mfma_f32_16x16x32_bf16 v[24:27], v[148:151], v[164:167], v[24:27]
	v_mfma_f32_16x16x32_bf16 v[80:83], v[140:143], v[184:187], v[80:83]
	v_mfma_f32_16x16x32_bf16 v[16:19], v[148:151], v[184:187], v[16:19]
	v_mfma_f32_16x16x32_bf16 v[68:71], v[140:143], v[206:209], v[68:71]
	v_mfma_f32_16x16x32_bf16 v[4:7], v[148:151], v[206:209], v[4:7]
	v_mfma_f32_16x16x32_bf16 v[64:67], v[140:143], v[214:217], v[64:67]
	v_mfma_f32_16x16x32_bf16 v[0:3], v[148:151], v[214:217], v[0:3]
	s_setprio 0
	s_barrier
	s_add_i32 s82, 0, 0x18000
	s_add_i32 s83, 0, 0x1c000
	v_add_u32_e32 v132, s82, v192
	v_add_u32_e32 v148, s83, v192
	ds_read_b128 v[120:123], v132
	ds_read_b128 v[124:127], v132 offset:1024
	ds_read_b128 v[128:131], v132 offset:2048
	ds_read_b128 v[132:135], v132 offset:3072
	ds_read_b128 v[136:139], v148
	ds_read_b128 v[140:143], v148 offset:1024
	ds_read_b128 v[144:147], v148 offset:2048
	ds_read_b128 v[148:151], v148 offset:3072
	s_add_u32 s56, s56, 0x80000
	s_addc_u32 s57, s57, 0
	s_mov_b32 m0, s65
	v_lshl_add_u64 v[226:227], s[56:57], 0, v[170:171]
	ds_read_b128 v[160:163], v198 offset:32768
	ds_read_b128 v[164:167], v198 offset:33792
	ds_read_b128 v[180:183], v198 offset:34816
	ds_read_b128 v[184:187], v198 offset:35840
	ds_read_b128 v[202:205], v198 offset:36864
	ds_read_b128 v[206:209], v198 offset:37888
	ds_read_b128 v[210:213], v198 offset:38912
	ds_read_b128 v[214:217], v198 offset:39936
	global_load_lds_dwordx4 v[226:227], off
	v_lshl_add_u64 v[226:227], s[56:57], 0, v[168:169]
	s_mov_b32 m0, s66
	s_nop 0
	global_load_lds_dwordx4 v[226:227], off
	s_sleep 1
	s_waitcnt vmcnt(8)
	s_waitcnt lgkmcnt(0)
	s_barrier
	s_setprio 1
	s_waitcnt lgkmcnt(0)
	v_mfma_f32_16x16x32_bf16 v[156:159], v[120:123], v[160:163], v[156:159]
	v_mfma_f32_16x16x32_bf16 v[60:63], v[128:131], v[160:163], v[60:63]
	v_mfma_f32_16x16x32_bf16 v[116:119], v[120:123], v[180:183], v[116:119]
	v_mfma_f32_16x16x32_bf16 v[52:55], v[128:131], v[180:183], v[52:55]
	v_mfma_f32_16x16x32_bf16 v[108:111], v[120:123], v[202:205], v[108:111]
	v_mfma_f32_16x16x32_bf16 v[44:47], v[128:131], v[202:205], v[44:47]
	v_mfma_f32_16x16x32_bf16 v[104:107], v[120:123], v[210:213], v[104:107]
	v_mfma_f32_16x16x32_bf16 v[40:43], v[128:131], v[210:213], v[40:43]
	v_mfma_f32_16x16x32_bf16 v[156:159], v[124:127], v[164:167], v[156:159]
	v_mfma_f32_16x16x32_bf16 v[60:63], v[132:135], v[164:167], v[60:63]
	v_mfma_f32_16x16x32_bf16 v[116:119], v[124:127], v[184:187], v[116:119]
	v_mfma_f32_16x16x32_bf16 v[52:55], v[132:135], v[184:187], v[52:55]
	v_mfma_f32_16x16x32_bf16 v[108:111], v[124:127], v[206:209], v[108:111]
	v_mfma_f32_16x16x32_bf16 v[44:47], v[132:135], v[206:209], v[44:47]
	v_mfma_f32_16x16x32_bf16 v[104:107], v[124:127], v[214:217], v[104:107]
	v_mfma_f32_16x16x32_bf16 v[40:43], v[132:135], v[214:217], v[40:43]
	s_setprio 0
	s_setprio 1
	v_mfma_f32_16x16x32_bf16 v[152:155], v[136:139], v[160:163], v[152:155]
	v_mfma_f32_16x16x32_bf16 v[56:59], v[144:147], v[160:163], v[56:59]
	v_mfma_f32_16x16x32_bf16 v[112:115], v[136:139], v[180:183], v[112:115]
	v_mfma_f32_16x16x32_bf16 v[48:51], v[144:147], v[180:183], v[48:51]
	v_mfma_f32_16x16x32_bf16 v[100:103], v[136:139], v[202:205], v[100:103]
	v_mfma_f32_16x16x32_bf16 v[36:39], v[144:147], v[202:205], v[36:39]
	v_mfma_f32_16x16x32_bf16 v[96:99], v[136:139], v[210:213], v[96:99]
	v_mfma_f32_16x16x32_bf16 v[32:35], v[144:147], v[210:213], v[32:35]
	v_mfma_f32_16x16x32_bf16 v[152:155], v[140:143], v[164:167], v[152:155]
	v_mfma_f32_16x16x32_bf16 v[56:59], v[148:151], v[164:167], v[56:59]
	v_mfma_f32_16x16x32_bf16 v[112:115], v[140:143], v[184:187], v[112:115]
	v_mfma_f32_16x16x32_bf16 v[48:51], v[148:151], v[184:187], v[48:51]
	v_mfma_f32_16x16x32_bf16 v[100:103], v[140:143], v[206:209], v[100:103]
	v_mfma_f32_16x16x32_bf16 v[36:39], v[148:151], v[206:209], v[36:39]
	v_mfma_f32_16x16x32_bf16 v[96:99], v[140:143], v[214:217], v[96:99]
	v_mfma_f32_16x16x32_bf16 v[32:35], v[148:151], v[214:217], v[32:35]
	s_setprio 0
	s_barrier
; #define PG8_STAGE(bufoff, gbase, voff) do { _Pragma("unroll") for (int _i = 0; _i < 2; ++_i) \
;         __builtin_amdgcn_global_load_lds((const unsigned*)((const char*)(gbase) + (voff)[_i]), (PG8_LAS unsigned*)(lds + (bufoff) + ldsw + _i * 8192), 16, 0, 0); } while (0)
; #define PG8_LDA(dst, b, h) do { _Pragma("unroll") for (int m = 0; m < 4; ++m) _Pragma("unroll") for (int k = 0; k < 2; ++k) dst[m][k] = *(const PG8_LAS bf16x8*)(lds + PG8_SA(b, h) + aoff + m * 2048 + k * 1024); } while (0)
; #define PG8_MMA(ai, bj, At, Bt) do { __builtin_amdgcn_s_setprio(1); _Pragma("unroll") for (int m = 0; m < 4; ++m) _Pragma("unroll") for (int n = 0; n < 2; ++n) _Pragma("unroll") for (int k = 0; k < 2; ++k) \
;         acc[ai][bj][m][n] = __builtin_amdgcn_mfma_f32_16x16x32_bf16(Bt[n][k], At[m][k], acc[ai][bj][m][n], 0, 0, 0); __builtin_amdgcn_s_setprio(0); } while (0)
; #define PG8_WAIT_V(n) asm volatile("s_waitcnt vmcnt(" #n ")" ::: "memory")
; #define PG8_WAIT_L(n) asm volatile("s_waitcnt lgkmcnt(" #n ")" ::: "memory")
; #define PG8_BAR __builtin_amdgcn_s_barrier()
; #define PG8_SCHED __builtin_amdgcn_sched_barrier(0)
; template <class Epi, class Sched, bool ALIGN_EPI = false, bool SP2 = false>
; __device__ __forceinline__ void gemm_phase(PG8_LAS unsigned char* lds, const Gemm g, const Sched& S, const Epi& E) {
;     ...
;             PG8_LDA(At, 1, 1); PG8_STAGE(PG8_SB(1, 0), b3, voffB); PG8_STAGE(PG8_SB(1, 1), b3 + hstep, voffB); PG8_STAGE(PG8_SA(1, 0), a3, voffA);
;             PG8_WAIT_V(8); PG8_WAIT_L(0); PG8_BAR; PG8_MMA(1, 0, At, B0); PG8_MMA(1, 1, At, B1); PG8_BAR; PG8_SCHED;
;     ...
;         if constexpr (ALIGN_EPI) { if (wr == 0) PG8_BAR; }
	s_add_i32 s56, s82, s62
	v_lshl_add_u64 v[188:189], v[188:189], 0, s[26:27]
	s_mov_b32 m0, s56
	ds_read_b128 v[160:163], v198 offset:49152
	ds_read_b128 v[164:167], v198 offset:50176
	ds_read_b128 v[180:183], v198 offset:51200
	ds_read_b128 v[184:187], v198 offset:52224
	ds_read_b128 v[202:205], v198 offset:53248
	ds_read_b128 v[206:209], v198 offset:54272
	ds_read_b128 v[210:213], v198 offset:55296
	ds_read_b128 v[214:217], v198 offset:56320
	global_load_lds_dwordx4 v[188:189], off
	s_add_i32 m0, s56, 0x2000
	s_add_u32 s54, s54, 0x80080
	v_lshl_add_u64 v[188:189], v[218:219], 0, s[26:27]
	s_addc_u32 s55, s55, 0
	s_add_i32 s56, s83, s62
	global_load_lds_dwordx4 v[188:189], off
	v_lshl_add_u64 v[188:189], s[54:55], 0, v[170:171]
	s_mov_b32 m0, s56
	s_nop 0
	global_load_lds_dwordx4 v[188:189], off
	v_lshl_add_u64 v[188:189], s[54:55], 0, v[168:169]
	s_add_i32 m0, s56, 0x2000
	s_nop 0
	global_load_lds_dwordx4 v[188:189], off
	v_lshl_add_u64 v[188:189], v[222:223], 0, s[26:27]
	s_mov_b32 m0, s68
	s_nop 0
	global_load_lds_dwordx4 v[188:189], off
	v_lshl_add_u64 v[188:189], v[224:225], 0, s[26:27]
	s_mov_b32 m0, s69
	s_nop 0
	global_load_lds_dwordx4 v[188:189], off
	s_sleep 1
	s_waitcnt vmcnt(8)
	s_waitcnt lgkmcnt(0)
	s_barrier
	s_setprio 1
	s_waitcnt lgkmcnt(0)
	v_mfma_f32_16x16x32_bf16 v[92:95], v[120:123], v[160:163], v[92:95]
	v_mfma_f32_16x16x32_bf16 v[28:31], v[128:131], v[160:163], v[28:31]
	v_mfma_f32_16x16x32_bf16 v[84:87], v[120:123], v[180:183], v[84:87]
	v_mfma_f32_16x16x32_bf16 v[20:23], v[128:131], v[180:183], v[20:23]
	v_mfma_f32_16x16x32_bf16 v[76:79], v[120:123], v[202:205], v[76:79]
	v_mfma_f32_16x16x32_bf16 v[12:15], v[128:131], v[202:205], v[12:15]
	v_mfma_f32_16x16x32_bf16 v[72:75], v[120:123], v[210:213], v[72:75]
	v_mfma_f32_16x16x32_bf16 v[8:11], v[128:131], v[210:213], v[8:11]
	v_mfma_f32_16x16x32_bf16 v[92:95], v[124:127], v[164:167], v[92:95]
	v_mfma_f32_16x16x32_bf16 v[28:31], v[132:135], v[164:167], v[28:31]
	v_mfma_f32_16x16x32_bf16 v[84:87], v[124:127], v[184:187], v[84:87]
	v_mfma_f32_16x16x32_bf16 v[20:23], v[132:135], v[184:187], v[20:23]
	v_mfma_f32_16x16x32_bf16 v[76:79], v[124:127], v[206:209], v[76:79]
	v_mfma_f32_16x16x32_bf16 v[12:15], v[132:135], v[206:209], v[12:15]
	v_mfma_f32_16x16x32_bf16 v[72:75], v[124:127], v[214:217], v[72:75]
	v_mfma_f32_16x16x32_bf16 v[8:11], v[132:135], v[214:217], v[8:11]
	s_setprio 0
	s_setprio 1
	v_mfma_f32_16x16x32_bf16 v[88:91], v[136:139], v[160:163], v[88:91]
	v_mfma_f32_16x16x32_bf16 v[24:27], v[144:147], v[160:163], v[24:27]
	v_mfma_f32_16x16x32_bf16 v[80:83], v[136:139], v[180:183], v[80:83]
	v_mfma_f32_16x16x32_bf16 v[16:19], v[144:147], v[180:183], v[16:19]
	v_mfma_f32_16x16x32_bf16 v[68:71], v[136:139], v[202:205], v[68:71]
	v_mfma_f32_16x16x32_bf16 v[4:7], v[144:147], v[202:205], v[4:7]
	v_mfma_f32_16x16x32_bf16 v[64:67], v[136:139], v[210:213], v[64:67]
	v_mfma_f32_16x16x32_bf16 v[0:3], v[144:147], v[210:213], v[0:3]
	v_mfma_f32_16x16x32_bf16 v[88:91], v[140:143], v[164:167], v[88:91]
	v_mfma_f32_16x16x32_bf16 v[24:27], v[148:151], v[164:167], v[24:27]
	v_mfma_f32_16x16x32_bf16 v[80:83], v[140:143], v[184:187], v[80:83]
	v_mfma_f32_16x16x32_bf16 v[16:19], v[148:151], v[184:187], v[16:19]
	v_mfma_f32_16x16x32_bf16 v[68:71], v[140:143], v[206:209], v[68:71]
	v_mfma_f32_16x16x32_bf16 v[4:7], v[148:151], v[206:209], v[4:7]
	v_mfma_f32_16x16x32_bf16 v[64:67], v[140:143], v[214:217], v[64:67]
	v_mfma_f32_16x16x32_bf16 v[0:3], v[148:151], v[214:217], v[0:3]
	s_setprio 0
	s_barrier
	s_add_i32 s81, s81, 2
	s_add_u32 s79, s79, 0x100
	s_addc_u32 s80, s80, 0
	s_add_u32 s4, s4, 0x100
	s_addc_u32 s5, s5, 0
	s_cmp_gt_u32 s81, 29
	s_cbranch_scc0 .LBB0_1399
	s_and_b64 vcc, exec, s[28:29]
	s_cbranch_vccz .LBB0_1402
	s_barrier

; #define PG8_STAGE(bufoff, gbase, voff) do { _Pragma("unroll") for (int _i = 0; _i < 2; ++_i) \
;         __builtin_amdgcn_global_load_lds((const unsigned*)((const char*)(gbase) + (voff)[_i]), (PG8_LAS unsigned*)(lds + (bufoff) + ldsw + _i * 8192), 16, 0, 0); } while (0)
; #define PG8_LDA(dst, b, h) do { _Pragma("unroll") for (int m = 0; m < 4; ++m) _Pragma("unroll") for (int k = 0; k < 2; ++k) dst[m][k] = *(const PG8_LAS bf16x8*)(lds + PG8_SA(b, h) + aoff + m * 2048 + k * 1024); } while (0)
; #define PG8_LDB(dst, b, h) do { _Pragma("unroll") for (int n = 0; n < 2; ++n) _Pragma("unroll") for (int k = 0; k < 2; ++k) dst[n][k] = *(const PG8_LAS bf16x8*)(lds + PG8_SB(b, h) + boff + n * 2048 + k * 1024); } while (0)
; #define PG8_MMA(ai, bj, At, Bt) do { __builtin_amdgcn_s_setprio(1); _Pragma("unroll") for (int m = 0; m < 4; ++m) _Pragma("unroll") for (int n = 0; n < 2; ++n) _Pragma("unroll") for (int k = 0; k < 2; ++k) \
;         acc[ai][bj][m][n] = __builtin_amdgcn_mfma_f32_16x16x32_bf16(Bt[n][k], At[m][k], acc[ai][bj][m][n], 0, 0, 0); __builtin_amdgcn_s_setprio(0); } while (0)
; #define PG8_WAIT_V(n) asm volatile("s_waitcnt vmcnt(" #n ")" ::: "memory")
; #define PG8_WAIT_L(n) asm volatile("s_waitcnt lgkmcnt(" #n ")" ::: "memory")
; template <class Epi, class Sched, bool ALIGN_EPI = false, bool SP2 = false>
; __device__ __forceinline__ void gemm_phase(PG8_LAS unsigned char* lds, const Gemm g, const Sched& S, const Epi& E) {
;     ...
;             const bool last = (t == nt - 2);
;             const char* a1 = cA + (size_t)(t + 1) * kstep;
;             const char* a2 = last ? nA : cA + (size_t)(t + 2) * kstep; const char* b2 = last ? nB : cB + (size_t)(t + 2) * kstep;
;             const char* a3 = a2 + kstep; const char* b3 = b2 + kstep;
;             if (last && has_next) S.a_ready(nxt);
;             if constexpr (SP2) {
;             PG8_LDB(B0, 0, 0); PG8_LDB(B1, 0, 1); PG8_SCHED; PG8_LDA(At, 0, 0); PG8_STAGE(PG8_SA(1, 1), a1 + hstep, voffA);
;             PG8_WAIT_V(8); PG8_WAIT_L(0); PG8_BAR; PG8_MMA(0, 0, At, B0); PG8_MMA(0, 1, At, B1); PG8_BAR; PG8_SCHED;
;             PG8_LDA(At, 0, 1); PG8_STAGE(PG8_SB(0, 0), b2, voffB); PG8_STAGE(PG8_SB(0, 1), b2 + hstep, voffB); PG8_STAGE(PG8_SA(0, 0), a2, voffA);
;             PG8_WAIT_V(8); PG8_WAIT_L(0); PG8_BAR; PG8_MMA(1, 0, At, B0); PG8_MMA(1, 1, At, B1); PG8_BAR; PG8_SCHED;
.LBB0_1541:
	ds_read_b128 v[104:107], v195
	ds_read_b128 v[108:111], v195 offset:1024
	ds_read_b128 v[116:119], v195 offset:2048
	ds_read_b128 v[124:127], v195 offset:3072
	ds_read_b128 v[160:163], v196
	ds_read_b128 v[164:167], v196 offset:1024
	ds_read_b128 v[168:171], v196 offset:2048
	ds_read_b128 v[172:175], v196 offset:3072
	s_add_u32 s34, s30, 0x100
	s_addc_u32 s35, s31, 0
	s_cmpk_eq_i32 s63, 0x54
	s_cselect_b32 s39, s27, s35
	s_cselect_b32 s38, s26, s34
	s_cselect_b32 s37, s15, s29
	s_cselect_b32 s36, s14, s28
	s_mov_b32 m0, s51
	v_lshl_add_u64 v[192:193], s[30:31], 0, v[158:159]
	ds_read_b128 v[176:179], v197
	ds_read_b128 v[180:183], v197 offset:1024
	ds_read_b128 v[184:187], v197 offset:2048
	ds_read_b128 v[188:191], v197 offset:3072
	ds_read_b128 v[202:205], v197 offset:4096
	ds_read_b128 v[206:209], v197 offset:5120
	ds_read_b128 v[210:213], v197 offset:6144
	ds_read_b128 v[214:217], v197 offset:7168
	global_load_lds_dwordx4 v[192:193], off
	v_lshl_add_u64 v[192:193], s[30:31], 0, v[156:157]
	s_mov_b32 m0, s52
	s_nop 0
	global_load_lds_dwordx4 v[192:193], off
	s_sleep 1
	s_waitcnt vmcnt(8)
	s_waitcnt lgkmcnt(0)
	s_barrier
	s_setprio 1
	s_waitcnt lgkmcnt(0)
	v_mfma_f32_16x16x32_bf16 v[140:143], v[104:107], v[176:179], v[140:143]
	v_mfma_f32_16x16x32_bf16 v[136:139], v[116:119], v[176:179], v[136:139]
	v_mfma_f32_16x16x32_bf16 v[120:123], v[104:107], v[184:187], v[120:123]
	v_mfma_f32_16x16x32_bf16 v[112:115], v[116:119], v[184:187], v[112:115]
	v_mfma_f32_16x16x32_bf16 v[92:95], v[104:107], v[202:205], v[92:95]
	v_mfma_f32_16x16x32_bf16 v[88:91], v[116:119], v[202:205], v[88:91]
	v_mfma_f32_16x16x32_bf16 v[76:79], v[104:107], v[210:213], v[76:79]
	v_mfma_f32_16x16x32_bf16 v[72:75], v[116:119], v[210:213], v[72:75]
	v_mfma_f32_16x16x32_bf16 v[140:143], v[108:111], v[180:183], v[140:143]
	v_mfma_f32_16x16x32_bf16 v[136:139], v[124:127], v[180:183], v[136:139]
	v_mfma_f32_16x16x32_bf16 v[120:123], v[108:111], v[188:191], v[120:123]
	v_mfma_f32_16x16x32_bf16 v[112:115], v[124:127], v[188:191], v[112:115]
	v_mfma_f32_16x16x32_bf16 v[92:95], v[108:111], v[206:209], v[92:95]
	v_mfma_f32_16x16x32_bf16 v[88:91], v[124:127], v[206:209], v[88:91]
	v_mfma_f32_16x16x32_bf16 v[76:79], v[108:111], v[214:217], v[76:79]
	v_mfma_f32_16x16x32_bf16 v[72:75], v[124:127], v[214:217], v[72:75]
	s_setprio 0
	s_setprio 1
	v_mfma_f32_16x16x32_bf16 v[132:135], v[160:163], v[176:179], v[132:135]
	v_mfma_f32_16x16x32_bf16 v[128:131], v[168:171], v[176:179], v[128:131]
	v_mfma_f32_16x16x32_bf16 v[100:103], v[160:163], v[184:187], v[100:103]
	v_mfma_f32_16x16x32_bf16 v[96:99], v[168:171], v[184:187], v[96:99]
	v_mfma_f32_16x16x32_bf16 v[84:87], v[160:163], v[202:205], v[84:87]
	v_mfma_f32_16x16x32_bf16 v[80:83], v[168:171], v[202:205], v[80:83]
	v_mfma_f32_16x16x32_bf16 v[68:71], v[160:163], v[210:213], v[68:71]
	v_mfma_f32_16x16x32_bf16 v[64:67], v[168:171], v[210:213], v[64:67]
	v_mfma_f32_16x16x32_bf16 v[132:135], v[164:167], v[180:183], v[132:135]
	v_mfma_f32_16x16x32_bf16 v[128:131], v[172:175], v[180:183], v[128:131]
	v_mfma_f32_16x16x32_bf16 v[100:103], v[164:167], v[188:191], v[100:103]
	v_mfma_f32_16x16x32_bf16 v[96:99], v[172:175], v[188:191], v[96:99]
	v_mfma_f32_16x16x32_bf16 v[84:87], v[164:167], v[206:209], v[84:87]
	v_mfma_f32_16x16x32_bf16 v[80:83], v[172:175], v[206:209], v[80:83]
	v_mfma_f32_16x16x32_bf16 v[68:71], v[164:167], v[214:217], v[68:71]
	v_mfma_f32_16x16x32_bf16 v[64:67], v[172:175], v[214:217], v[64:67]
	s_setprio 0
	s_barrier
	s_mov_b32 m0, s53
	v_lshl_add_u64 v[192:193], s[36:37], 0, v[146:147]
	s_add_u32 s30, s36, 0x160000
	ds_read_b128 v[176:179], v197 offset:16384
	ds_read_b128 v[180:183], v197 offset:17408
	ds_read_b128 v[184:187], v197 offset:18432
	ds_read_b128 v[188:191], v197 offset:19456
	ds_read_b128 v[202:205], v197 offset:20480
	ds_read_b128 v[206:209], v197 offset:21504
	ds_read_b128 v[210:213], v197 offset:22528
	ds_read_b128 v[214:217], v197 offset:23552
	global_load_lds_dwordx4 v[192:193], off
	v_lshl_add_u64 v[218:219], s[36:37], 0, v[144:145]
	s_mov_b32 m0, s54
	s_addc_u32 s31, s37, 0
	global_load_lds_dwordx4 v[218:219], off
	v_lshl_add_u64 v[222:223], s[30:31], 0, v[146:147]
	s_mov_b32 m0, s55
	v_lshl_add_u64 v[224:225], s[38:39], 0, v[144:145]
	global_load_lds_dwordx4 v[222:223], off
	v_lshl_add_u64 v[222:223], s[30:31], 0, v[144:145]
	s_mov_b32 m0, s56
	s_nop 0
	global_load_lds_dwordx4 v[222:223], off
	v_lshl_add_u64 v[222:223], s[38:39], 0, v[146:147]
	s_mov_b32 m0, s43
	s_nop 0
	global_load_lds_dwordx4 v[222:223], off
	s_mov_b32 m0, s44
	s_nop 0
	global_load_lds_dwordx4 v[224:225], off
	s_sleep 1
	s_waitcnt vmcnt(8)
	s_waitcnt lgkmcnt(0)
	s_barrier
; #define PG8_STAGE(bufoff, gbase, voff) do { _Pragma("unroll") for (int _i = 0; _i < 2; ++_i) \
;         __builtin_amdgcn_global_load_lds((const unsigned*)((const char*)(gbase) + (voff)[_i]), (PG8_LAS unsigned*)(lds + (bufoff) + ldsw + _i * 8192), 16, 0, 0); } while (0)
; #define PG8_LDA(dst, b, h) do { _Pragma("unroll") for (int m = 0; m < 4; ++m) _Pragma("unroll") for (int k = 0; k < 2; ++k) dst[m][k] = *(const PG8_LAS bf16x8*)(lds + PG8_SA(b, h) + aoff + m * 2048 + k * 1024); } while (0)
; #define PG8_LDB(dst, b, h) do { _Pragma("unroll") for (int n = 0; n < 2; ++n) _Pragma("unroll") for (int k = 0; k < 2; ++k) dst[n][k] = *(const PG8_LAS bf16x8*)(lds + PG8_SB(b, h) + boff + n * 2048 + k * 1024); } while (0)
; #define PG8_MMA(ai, bj, At, Bt) do { __builtin_amdgcn_s_setprio(1); _Pragma("unroll") for (int m = 0; m < 4; ++m) _Pragma("unroll") for (int n = 0; n < 2; ++n) _Pragma("unroll") for (int k = 0; k < 2; ++k) \
;         acc[ai][bj][m][n] = __builtin_amdgcn_mfma_f32_16x16x32_bf16(Bt[n][k], At[m][k], acc[ai][bj][m][n], 0, 0, 0); __builtin_amdgcn_s_setprio(0); } while (0)
; #define PG8_WAIT_V(n) asm volatile("s_waitcnt vmcnt(" #n ")" ::: "memory")
; #define PG8_WAIT_L(n) asm volatile("s_waitcnt lgkmcnt(" #n ")" ::: "memory")
; #define PG8_BAR __builtin_amdgcn_s_barrier()
; #define PG8_SCHED __builtin_amdgcn_sched_barrier(0)
; template <class Epi, class Sched, bool ALIGN_EPI = false, bool SP2 = false>
; __device__ __forceinline__ void gemm_phase(PG8_LAS unsigned char* lds, const Gemm g, const Sched& S, const Epi& E) {
;     ...
;             PG8_WAIT_V(8); PG8_WAIT_L(0); PG8_BAR; PG8_MMA(1, 0, At, B0); PG8_MMA(1, 1, At, B1); PG8_BAR; PG8_SCHED;
;             PG8_LDB(B0, 1, 0); PG8_LDB(B1, 1, 1); PG8_SCHED; PG8_LDA(At, 1, 0); PG8_STAGE(PG8_SA(0, 1), a2 + hstep, voffA);
;             PG8_WAIT_V(8); PG8_WAIT_L(0); PG8_BAR; PG8_MMA(0, 0, At, B0); PG8_MMA(0, 1, At, B1); PG8_BAR; PG8_SCHED;
	s_setprio 1
	s_waitcnt lgkmcnt(0)
	v_mfma_f32_16x16x32_bf16 v[60:63], v[104:107], v[176:179], v[60:63]
	v_mfma_f32_16x16x32_bf16 v[56:59], v[116:119], v[176:179], v[56:59]
	v_mfma_f32_16x16x32_bf16 v[44:47], v[104:107], v[184:187], v[44:47]
	v_mfma_f32_16x16x32_bf16 v[40:43], v[116:119], v[184:187], v[40:43]
	v_mfma_f32_16x16x32_bf16 v[28:31], v[104:107], v[202:205], v[28:31]
	v_mfma_f32_16x16x32_bf16 v[24:27], v[116:119], v[202:205], v[24:27]
	v_mfma_f32_16x16x32_bf16 v[12:15], v[104:107], v[210:213], v[12:15]
	v_mfma_f32_16x16x32_bf16 v[8:11], v[116:119], v[210:213], v[8:11]
	v_mfma_f32_16x16x32_bf16 v[60:63], v[108:111], v[180:183], v[60:63]
	v_mfma_f32_16x16x32_bf16 v[56:59], v[124:127], v[180:183], v[56:59]
	v_mfma_f32_16x16x32_bf16 v[44:47], v[108:111], v[188:191], v[44:47]
	v_mfma_f32_16x16x32_bf16 v[40:43], v[124:127], v[188:191], v[40:43]
	v_mfma_f32_16x16x32_bf16 v[28:31], v[108:111], v[206:209], v[28:31]
	v_mfma_f32_16x16x32_bf16 v[24:27], v[124:127], v[206:209], v[24:27]
	v_mfma_f32_16x16x32_bf16 v[12:15], v[108:111], v[214:217], v[12:15]
	v_mfma_f32_16x16x32_bf16 v[8:11], v[124:127], v[214:217], v[8:11]
	s_setprio 0
	s_setprio 1
	v_mfma_f32_16x16x32_bf16 v[52:55], v[160:163], v[176:179], v[52:55]
	v_mfma_f32_16x16x32_bf16 v[48:51], v[168:171], v[176:179], v[48:51]
	v_mfma_f32_16x16x32_bf16 v[36:39], v[160:163], v[184:187], v[36:39]
	v_mfma_f32_16x16x32_bf16 v[32:35], v[168:171], v[184:187], v[32:35]
	v_mfma_f32_16x16x32_bf16 v[20:23], v[160:163], v[202:205], v[20:23]
	v_mfma_f32_16x16x32_bf16 v[16:19], v[168:171], v[202:205], v[16:19]
	v_mfma_f32_16x16x32_bf16 v[4:7], v[160:163], v[210:213], v[4:7]
	v_mfma_f32_16x16x32_bf16 v[0:3], v[168:171], v[210:213], v[0:3]
	v_mfma_f32_16x16x32_bf16 v[52:55], v[164:167], v[180:183], v[52:55]
	v_mfma_f32_16x16x32_bf16 v[48:51], v[172:175], v[180:183], v[48:51]
	v_mfma_f32_16x16x32_bf16 v[36:39], v[164:167], v[188:191], v[36:39]
	v_mfma_f32_16x16x32_bf16 v[32:35], v[172:175], v[188:191], v[32:35]
	v_mfma_f32_16x16x32_bf16 v[20:23], v[164:167], v[206:209], v[20:23]
	v_mfma_f32_16x16x32_bf16 v[16:19], v[172:175], v[206:209], v[16:19]
	v_mfma_f32_16x16x32_bf16 v[4:7], v[164:167], v[214:217], v[4:7]
	v_mfma_f32_16x16x32_bf16 v[0:3], v[172:175], v[214:217], v[0:3]
	s_setprio 0
	s_barrier
	ds_read_b128 v[104:107], v199
	ds_read_b128 v[108:111], v199 offset:1024
	ds_read_b128 v[116:119], v199 offset:2048
	ds_read_b128 v[124:127], v199 offset:3072
	ds_read_b128 v[160:163], v200
	ds_read_b128 v[164:167], v200 offset:1024
	ds_read_b128 v[168:171], v200 offset:2048
	ds_read_b128 v[172:175], v200 offset:3072
	s_add_u32 s30, s38, 0x160000
	s_addc_u32 s31, s39, 0
	s_mov_b32 m0, s45
	v_lshl_add_u64 v[226:227], s[30:31], 0, v[146:147]
	ds_read_b128 v[176:179], v197 offset:32768
	ds_read_b128 v[180:183], v197 offset:33792
	ds_read_b128 v[184:187], v197 offset:34816
	ds_read_b128 v[188:191], v197 offset:35840
	ds_read_b128 v[202:205], v197 offset:36864
	ds_read_b128 v[206:209], v197 offset:37888
	ds_read_b128 v[210:213], v197 offset:38912
	ds_read_b128 v[214:217], v197 offset:39936
	global_load_lds_dwordx4 v[226:227], off
	v_lshl_add_u64 v[226:227], s[30:31], 0, v[144:145]
	s_mov_b32 m0, s46
	s_nop 0
	global_load_lds_dwordx4 v[226:227], off
	s_sleep 1
	s_waitcnt vmcnt(8)
	s_waitcnt lgkmcnt(0)
	s_barrier
	s_setprio 1
	s_waitcnt lgkmcnt(0)
	v_mfma_f32_16x16x32_bf16 v[140:143], v[104:107], v[176:179], v[140:143]
	v_mfma_f32_16x16x32_bf16 v[136:139], v[116:119], v[176:179], v[136:139]
	v_mfma_f32_16x16x32_bf16 v[120:123], v[104:107], v[184:187], v[120:123]
	v_mfma_f32_16x16x32_bf16 v[112:115], v[116:119], v[184:187], v[112:115]
	v_mfma_f32_16x16x32_bf16 v[92:95], v[104:107], v[202:205], v[92:95]
	v_mfma_f32_16x16x32_bf16 v[88:91], v[116:119], v[202:205], v[88:91]
	v_mfma_f32_16x16x32_bf16 v[76:79], v[104:107], v[210:213], v[76:79]
	v_mfma_f32_16x16x32_bf16 v[72:75], v[116:119], v[210:213], v[72:75]
	v_mfma_f32_16x16x32_bf16 v[140:143], v[108:111], v[180:183], v[140:143]
	v_mfma_f32_16x16x32_bf16 v[136:139], v[124:127], v[180:183], v[136:139]
	v_mfma_f32_16x16x32_bf16 v[120:123], v[108:111], v[188:191], v[120:123]
	v_mfma_f32_16x16x32_bf16 v[112:115], v[124:127], v[188:191], v[112:115]
	v_mfma_f32_16x16x32_bf16 v[92:95], v[108:111], v[206:209], v[92:95]
	v_mfma_f32_16x16x32_bf16 v[88:91], v[124:127], v[206:209], v[88:91]
	v_mfma_f32_16x16x32_bf16 v[76:79], v[108:111], v[214:217], v[76:79]
	v_mfma_f32_16x16x32_bf16 v[72:75], v[124:127], v[214:217], v[72:75]
	s_setprio 0
	s_setprio 1
	v_mfma_f32_16x16x32_bf16 v[132:135], v[160:163], v[176:179], v[132:135]
	v_mfma_f32_16x16x32_bf16 v[128:131], v[168:171], v[176:179], v[128:131]
	v_mfma_f32_16x16x32_bf16 v[100:103], v[160:163], v[184:187], v[100:103]
	v_mfma_f32_16x16x32_bf16 v[96:99], v[168:171], v[184:187], v[96:99]
	v_mfma_f32_16x16x32_bf16 v[84:87], v[160:163], v[202:205], v[84:87]
	v_mfma_f32_16x16x32_bf16 v[80:83], v[168:171], v[202:205], v[80:83]
	v_mfma_f32_16x16x32_bf16 v[68:71], v[160:163], v[210:213], v[68:71]
	v_mfma_f32_16x16x32_bf16 v[64:67], v[168:171], v[210:213], v[64:67]
	v_mfma_f32_16x16x32_bf16 v[132:135], v[164:167], v[180:183], v[132:135]
	v_mfma_f32_16x16x32_bf16 v[128:131], v[172:175], v[180:183], v[128:131]
	v_mfma_f32_16x16x32_bf16 v[100:103], v[164:167], v[188:191], v[100:103]
	v_mfma_f32_16x16x32_bf16 v[96:99], v[172:175], v[188:191], v[96:99]
	v_mfma_f32_16x16x32_bf16 v[84:87], v[164:167], v[206:209], v[84:87]
	v_mfma_f32_16x16x32_bf16 v[80:83], v[172:175], v[206:209], v[80:83]
	v_mfma_f32_16x16x32_bf16 v[68:71], v[164:167], v[214:217], v[68:71]
	v_mfma_f32_16x16x32_bf16 v[64:67], v[172:175], v[214:217], v[64:67]
	s_setprio 0
	s_barrier
; #define PG8_STAGE(bufoff, gbase, voff) do { _Pragma("unroll") for (int _i = 0; _i < 2; ++_i) \
;         __builtin_amdgcn_global_load_lds((const unsigned*)((const char*)(gbase) + (voff)[_i]), (PG8_LAS unsigned*)(lds + (bufoff) + ldsw + _i * 8192), 16, 0, 0); } while (0)
; #define PG8_LDA(dst, b, h) do { _Pragma("unroll") for (int m = 0; m < 4; ++m) _Pragma("unroll") for (int k = 0; k < 2; ++k) dst[m][k] = *(const PG8_LAS bf16x8*)(lds + PG8_SA(b, h) + aoff + m * 2048 + k * 1024); } while (0)
; #define PG8_MMA(ai, bj, At, Bt) do { __builtin_amdgcn_s_setprio(1); _Pragma("unroll") for (int m = 0; m < 4; ++m) _Pragma("unroll") for (int n = 0; n < 2; ++n) _Pragma("unroll") for (int k = 0; k < 2; ++k) \
;         acc[ai][bj][m][n] = __builtin_amdgcn_mfma_f32_16x16x32_bf16(Bt[n][k], At[m][k], acc[ai][bj][m][n], 0, 0, 0); __builtin_amdgcn_s_setprio(0); } while (0)
; #define PG8_WAIT_V(n) asm volatile("s_waitcnt vmcnt(" #n ")" ::: "memory")
; #define PG8_WAIT_L(n) asm volatile("s_waitcnt lgkmcnt(" #n ")" ::: "memory")
; #define PG8_BAR __builtin_amdgcn_s_barrier()
; #define PG8_SCHED __builtin_amdgcn_sched_barrier(0)
; template <class Epi, class Sched, bool ALIGN_EPI = false, bool SP2 = false>
; __device__ __forceinline__ void gemm_phase(PG8_LAS unsigned char* lds, const Gemm g, const Sched& S, const Epi& E) {
;     ...
;             PG8_LDA(At, 1, 1); PG8_STAGE(PG8_SB(1, 0), b3, voffB); PG8_STAGE(PG8_SB(1, 1), b3 + hstep, voffB); PG8_STAGE(PG8_SA(1, 0), a3, voffA);
;             PG8_WAIT_V(8); PG8_WAIT_L(0); PG8_BAR; PG8_MMA(1, 0, At, B0); PG8_MMA(1, 1, At, B1); PG8_BAR; PG8_SCHED;
;     ...
;         if constexpr (ALIGN_EPI) { if (wr == 0) PG8_BAR; }
	s_mov_b32 m0, s57
	v_lshl_add_u64 v[192:193], v[192:193], 0, s[20:21]
	s_add_u32 s30, s36, 0x160080
	ds_read_b128 v[176:179], v197 offset:49152
	ds_read_b128 v[180:183], v197 offset:50176
	ds_read_b128 v[184:187], v197 offset:51200
	ds_read_b128 v[188:191], v197 offset:52224
	ds_read_b128 v[202:205], v197 offset:53248
	ds_read_b128 v[206:209], v197 offset:54272
	ds_read_b128 v[210:213], v197 offset:55296
	ds_read_b128 v[214:217], v197 offset:56320
	global_load_lds_dwordx4 v[192:193], off
	v_lshl_add_u64 v[192:193], v[218:219], 0, s[20:21]
	s_mov_b32 m0, s58
	s_addc_u32 s31, s37, 0
	global_load_lds_dwordx4 v[192:193], off
	v_lshl_add_u64 v[192:193], s[30:31], 0, v[146:147]
	s_mov_b32 m0, s59
	s_nop 0
	global_load_lds_dwordx4 v[192:193], off
	v_lshl_add_u64 v[192:193], s[30:31], 0, v[144:145]
	s_mov_b32 m0, s60
	s_nop 0
	global_load_lds_dwordx4 v[192:193], off
	v_lshl_add_u64 v[192:193], v[222:223], 0, s[20:21]
	s_mov_b32 m0, s49
	s_nop 0
	global_load_lds_dwordx4 v[192:193], off
	v_lshl_add_u64 v[192:193], v[224:225], 0, s[20:21]
	s_mov_b32 m0, s50
	s_nop 0
	global_load_lds_dwordx4 v[192:193], off
	s_sleep 1
	s_waitcnt vmcnt(8)
	s_waitcnt lgkmcnt(0)
	s_barrier
	s_setprio 1
	s_waitcnt lgkmcnt(0)
	v_mfma_f32_16x16x32_bf16 v[60:63], v[104:107], v[176:179], v[60:63]
	v_mfma_f32_16x16x32_bf16 v[56:59], v[116:119], v[176:179], v[56:59]
	v_mfma_f32_16x16x32_bf16 v[44:47], v[104:107], v[184:187], v[44:47]
	v_mfma_f32_16x16x32_bf16 v[40:43], v[116:119], v[184:187], v[40:43]
	v_mfma_f32_16x16x32_bf16 v[28:31], v[104:107], v[202:205], v[28:31]
	v_mfma_f32_16x16x32_bf16 v[24:27], v[116:119], v[202:205], v[24:27]
	v_mfma_f32_16x16x32_bf16 v[12:15], v[104:107], v[210:213], v[12:15]
	v_mfma_f32_16x16x32_bf16 v[8:11], v[116:119], v[210:213], v[8:11]
	v_mfma_f32_16x16x32_bf16 v[60:63], v[108:111], v[180:183], v[60:63]
	v_mfma_f32_16x16x32_bf16 v[56:59], v[124:127], v[180:183], v[56:59]
	v_mfma_f32_16x16x32_bf16 v[44:47], v[108:111], v[188:191], v[44:47]
	v_mfma_f32_16x16x32_bf16 v[40:43], v[124:127], v[188:191], v[40:43]
	v_mfma_f32_16x16x32_bf16 v[28:31], v[108:111], v[206:209], v[28:31]
	v_mfma_f32_16x16x32_bf16 v[24:27], v[124:127], v[206:209], v[24:27]
	v_mfma_f32_16x16x32_bf16 v[12:15], v[108:111], v[214:217], v[12:15]
	v_mfma_f32_16x16x32_bf16 v[8:11], v[124:127], v[214:217], v[8:11]
	s_setprio 0
	s_setprio 1
	v_mfma_f32_16x16x32_bf16 v[52:55], v[160:163], v[176:179], v[52:55]
	v_mfma_f32_16x16x32_bf16 v[48:51], v[168:171], v[176:179], v[48:51]
	v_mfma_f32_16x16x32_bf16 v[36:39], v[160:163], v[184:187], v[36:39]
	v_mfma_f32_16x16x32_bf16 v[32:35], v[168:171], v[184:187], v[32:35]
	v_mfma_f32_16x16x32_bf16 v[20:23], v[160:163], v[202:205], v[20:23]
	v_mfma_f32_16x16x32_bf16 v[16:19], v[168:171], v[202:205], v[16:19]
	v_mfma_f32_16x16x32_bf16 v[4:7], v[160:163], v[210:213], v[4:7]
	v_mfma_f32_16x16x32_bf16 v[0:3], v[168:171], v[210:213], v[0:3]
	v_mfma_f32_16x16x32_bf16 v[52:55], v[164:167], v[180:183], v[52:55]
	v_mfma_f32_16x16x32_bf16 v[48:51], v[172:175], v[180:183], v[48:51]
	v_mfma_f32_16x16x32_bf16 v[36:39], v[164:167], v[188:191], v[36:39]
	v_mfma_f32_16x16x32_bf16 v[32:35], v[172:175], v[188:191], v[32:35]
	v_mfma_f32_16x16x32_bf16 v[20:23], v[164:167], v[206:209], v[20:23]
	v_mfma_f32_16x16x32_bf16 v[16:19], v[172:175], v[206:209], v[16:19]
	v_mfma_f32_16x16x32_bf16 v[4:7], v[164:167], v[214:217], v[4:7]
	v_mfma_f32_16x16x32_bf16 v[0:3], v[172:175], v[214:217], v[0:3]
	s_setprio 0
	s_barrier
	s_add_i32 s63, s63, 2
	s_add_u32 s28, s28, 0x100
	s_addc_u32 s29, s29, 0
	s_cmpk_gt_u32 s63, 0x55
	s_mov_b64 s[30:31], s[34:35]
	s_cbranch_scc0 .LBB0_1541
	s_and_b64 vcc, exec, s[22:23]
	s_cbranch_vccz .LBB0_1544
	s_barrier

; #define PG8_STAGE(bufoff, gbase, voff) do { _Pragma("unroll") for (int _i = 0; _i < 2; ++_i) \
;         __builtin_amdgcn_global_load_lds((const unsigned*)((const char*)(gbase) + (voff)[_i]), (PG8_LAS unsigned*)(lds + (bufoff) + ldsw + _i * 8192), 16, 0, 0); } while (0)
; #define PG8_LDA(dst, b, h) do { _Pragma("unroll") for (int m = 0; m < 4; ++m) _Pragma("unroll") for (int k = 0; k < 2; ++k) dst[m][k] = *(const PG8_LAS bf16x8*)(lds + PG8_SA(b, h) + aoff + m * 2048 + k * 1024); } while (0)
; #define PG8_LDB(dst, b, h) do { _Pragma("unroll") for (int n = 0; n < 2; ++n) _Pragma("unroll") for (int k = 0; k < 2; ++k) dst[n][k] = *(const PG8_LAS bf16x8*)(lds + PG8_SB(b, h) + boff + n * 2048 + k * 1024); } while (0)
; #define PG8_MMA(ai, bj, At, Bt) do { __builtin_amdgcn_s_setprio(1); _Pragma("unroll") for (int m = 0; m < 4; ++m) _Pragma("unroll") for (int n = 0; n < 2; ++n) _Pragma("unroll") for (int k = 0; k < 2; ++k) \
;         acc[ai][bj][m][n] = __builtin_amdgcn_mfma_f32_16x16x32_bf16(Bt[n][k], At[m][k], acc[ai][bj][m][n], 0, 0, 0); __builtin_amdgcn_s_setprio(0); } while (0)
; #define PG8_WAIT_V(n) asm volatile("s_waitcnt vmcnt(" #n ")" ::: "memory")
; #define PG8_WAIT_L(n) asm volatile("s_waitcnt lgkmcnt(" #n ")" ::: "memory")
; template <class Epi, class Sched, bool ALIGN_EPI = false, bool SP2 = false>
; __device__ __forceinline__ void gemm_phase(PG8_LAS unsigned char* lds, const Gemm g, const Sched& S, const Epi& E) {
;     ...
;             const bool last = (t == nt - 2);
;             const char* a1 = cA + (size_t)(t + 1) * kstep;
;             const char* a2 = last ? nA : cA + (size_t)(t + 2) * kstep; const char* b2 = last ? nB : cB + (size_t)(t + 2) * kstep;
;             const char* a3 = a2 + kstep; const char* b3 = b2 + kstep;
;             if (last && has_next) S.a_ready(nxt);
;             if constexpr (SP2) {
;             PG8_LDB(B0, 0, 0); PG8_LDB(B1, 0, 1); PG8_SCHED; PG8_LDA(At, 0, 0); PG8_STAGE(PG8_SA(1, 1), a1 + hstep, voffA);
;             PG8_WAIT_V(8); PG8_WAIT_L(0); PG8_BAR; PG8_MMA(0, 0, At, B0); PG8_MMA(0, 1, At, B1); PG8_BAR; PG8_SCHED;
;             PG8_LDA(At, 0, 1); PG8_STAGE(PG8_SB(0, 0), b2, voffB); PG8_STAGE(PG8_SB(0, 1), b2 + hstep, voffB); PG8_STAGE(PG8_SA(0, 0), a2, voffA);
;             PG8_WAIT_V(8); PG8_WAIT_L(0); PG8_BAR; PG8_MMA(1, 0, At, B0); PG8_MMA(1, 1, At, B1); PG8_BAR; PG8_SCHED;
.LBB0_1597:
	ds_read_b128 v[128:131], v165
	ds_read_b128 v[132:135], v165 offset:1024
	ds_read_b128 v[136:139], v165 offset:2048
	ds_read_b128 v[140:143], v165 offset:3072
	ds_read_b128 v[156:159], v166
	ds_read_b128 v[168:171], v166 offset:1024
	ds_read_b128 v[172:175], v166 offset:2048
	ds_read_b128 v[176:179], v166 offset:3072
	s_add_u32 s22, s20, 0x100
	s_addc_u32 s23, s21, 0
	s_cmpk_eq_i32 s53, 0x54
	s_cselect_b32 s27, s7, s23
	s_cselect_b32 s26, s6, s22
	s_cselect_b32 s25, s19, s52
	s_cselect_b32 s24, s18, s51
	v_lshl_add_u64 v[160:161], s[20:21], 0, v[150:151]
	s_add_i32 m0, s35, 0xc000
	ds_read_b128 v[180:183], v167
	ds_read_b128 v[184:187], v167 offset:1024
	ds_read_b128 v[188:191], v167 offset:2048
	ds_read_b128 v[192:195], v167 offset:3072
	ds_read_b128 v[196:199], v167 offset:4096
	ds_read_b128 v[200:203], v167 offset:5120
	ds_read_b128 v[204:207], v167 offset:6144
	ds_read_b128 v[208:211], v167 offset:7168
	global_load_lds_dwordx4 v[160:161], off
	v_lshl_add_u64 v[160:161], s[20:21], 0, v[148:149]
	s_add_i32 m0, s35, 0xe000
	s_nop 0
	global_load_lds_dwordx4 v[160:161], off
	s_sleep 1
	s_waitcnt vmcnt(8)
	s_waitcnt lgkmcnt(0)
	s_barrier
	s_setprio 1
	s_waitcnt lgkmcnt(0)
	v_mfma_f32_16x16x32_bf16 v[124:127], v[128:131], v[180:183], v[124:127]
	v_mfma_f32_16x16x32_bf16 v[120:123], v[136:139], v[180:183], v[120:123]
	v_mfma_f32_16x16x32_bf16 v[116:119], v[128:131], v[188:191], v[116:119]
	v_mfma_f32_16x16x32_bf16 v[112:115], v[136:139], v[188:191], v[112:115]
	v_mfma_f32_16x16x32_bf16 v[92:95], v[128:131], v[196:199], v[92:95]
	v_mfma_f32_16x16x32_bf16 v[88:91], v[136:139], v[196:199], v[88:91]
	v_mfma_f32_16x16x32_bf16 v[84:87], v[128:131], v[204:207], v[84:87]
	v_mfma_f32_16x16x32_bf16 v[80:83], v[136:139], v[204:207], v[80:83]
	v_mfma_f32_16x16x32_bf16 v[124:127], v[132:135], v[184:187], v[124:127]
	v_mfma_f32_16x16x32_bf16 v[120:123], v[140:143], v[184:187], v[120:123]
	v_mfma_f32_16x16x32_bf16 v[116:119], v[132:135], v[192:195], v[116:119]
	v_mfma_f32_16x16x32_bf16 v[112:115], v[140:143], v[192:195], v[112:115]
	v_mfma_f32_16x16x32_bf16 v[92:95], v[132:135], v[200:203], v[92:95]
	v_mfma_f32_16x16x32_bf16 v[88:91], v[140:143], v[200:203], v[88:91]
	v_mfma_f32_16x16x32_bf16 v[84:87], v[132:135], v[208:211], v[84:87]
	v_mfma_f32_16x16x32_bf16 v[80:83], v[140:143], v[208:211], v[80:83]
	s_setprio 0
	s_setprio 1
	v_mfma_f32_16x16x32_bf16 v[108:111], v[156:159], v[180:183], v[108:111]
	v_mfma_f32_16x16x32_bf16 v[104:107], v[172:175], v[180:183], v[104:107]
	v_mfma_f32_16x16x32_bf16 v[100:103], v[156:159], v[188:191], v[100:103]
	v_mfma_f32_16x16x32_bf16 v[96:99], v[172:175], v[188:191], v[96:99]
	v_mfma_f32_16x16x32_bf16 v[76:79], v[156:159], v[196:199], v[76:79]
	v_mfma_f32_16x16x32_bf16 v[72:75], v[172:175], v[196:199], v[72:75]
	v_mfma_f32_16x16x32_bf16 v[68:71], v[156:159], v[204:207], v[68:71]
	v_mfma_f32_16x16x32_bf16 v[64:67], v[172:175], v[204:207], v[64:67]
	v_mfma_f32_16x16x32_bf16 v[108:111], v[168:171], v[184:187], v[108:111]
	v_mfma_f32_16x16x32_bf16 v[104:107], v[176:179], v[184:187], v[104:107]
	v_mfma_f32_16x16x32_bf16 v[100:103], v[168:171], v[192:195], v[100:103]
	v_mfma_f32_16x16x32_bf16 v[96:99], v[176:179], v[192:195], v[96:99]
	v_mfma_f32_16x16x32_bf16 v[76:79], v[168:171], v[200:203], v[76:79]
	v_mfma_f32_16x16x32_bf16 v[72:75], v[176:179], v[200:203], v[72:75]
	v_mfma_f32_16x16x32_bf16 v[68:71], v[168:171], v[208:211], v[68:71]
	v_mfma_f32_16x16x32_bf16 v[64:67], v[176:179], v[208:211], v[64:67]
	s_setprio 0
	s_barrier
	s_add_i32 s20, s44, s34
	v_lshl_add_u64 v[160:161], s[24:25], 0, v[144:145]
	s_mov_b32 m0, s20
	ds_read_b128 v[180:183], v167 offset:16384
	ds_read_b128 v[184:187], v167 offset:17408
	ds_read_b128 v[188:191], v167 offset:18432
	ds_read_b128 v[192:195], v167 offset:19456
	ds_read_b128 v[196:199], v167 offset:20480
	ds_read_b128 v[200:203], v167 offset:21504
	ds_read_b128 v[204:207], v167 offset:22528
	ds_read_b128 v[208:211], v167 offset:23552
	global_load_lds_dwordx4 v[160:161], off
	s_add_i32 m0, s20, 0x2000
	s_add_u32 s20, s24, 0x160000
	v_lshl_add_u64 v[212:213], s[24:25], 0, v[146:147]
	s_addc_u32 s21, s25, 0
	s_add_i32 s54, s45, s34
	global_load_lds_dwordx4 v[212:213], off
	v_lshl_add_u64 v[214:215], s[20:21], 0, v[144:145]
	s_mov_b32 m0, s54
	v_lshl_add_u64 v[216:217], s[26:27], 0, v[146:147]
	global_load_lds_dwordx4 v[214:215], off
	v_lshl_add_u64 v[214:215], s[20:21], 0, v[146:147]
	s_add_i32 m0, s54, 0x2000
	s_nop 0
	global_load_lds_dwordx4 v[214:215], off
	v_lshl_add_u64 v[214:215], s[26:27], 0, v[144:145]
	s_mov_b32 m0, s35
	s_nop 0
	global_load_lds_dwordx4 v[214:215], off
	s_mov_b32 m0, s36
	s_nop 0
	global_load_lds_dwordx4 v[216:217], off
	s_sleep 1
	s_waitcnt vmcnt(8)
	s_waitcnt lgkmcnt(0)
	s_barrier
; #define PG8_STAGE(bufoff, gbase, voff) do { _Pragma("unroll") for (int _i = 0; _i < 2; ++_i) \
;         __builtin_amdgcn_global_load_lds((const unsigned*)((const char*)(gbase) + (voff)[_i]), (PG8_LAS unsigned*)(lds + (bufoff) + ldsw + _i * 8192), 16, 0, 0); } while (0)
; #define PG8_LDA(dst, b, h) do { _Pragma("unroll") for (int m = 0; m < 4; ++m) _Pragma("unroll") for (int k = 0; k < 2; ++k) dst[m][k] = *(const PG8_LAS bf16x8*)(lds + PG8_SA(b, h) + aoff + m * 2048 + k * 1024); } while (0)
; #define PG8_LDB(dst, b, h) do { _Pragma("unroll") for (int n = 0; n < 2; ++n) _Pragma("unroll") for (int k = 0; k < 2; ++k) dst[n][k] = *(const PG8_LAS bf16x8*)(lds + PG8_SB(b, h) + boff + n * 2048 + k * 1024); } while (0)
; #define PG8_MMA(ai, bj, At, Bt) do { __builtin_amdgcn_s_setprio(1); _Pragma("unroll") for (int m = 0; m < 4; ++m) _Pragma("unroll") for (int n = 0; n < 2; ++n) _Pragma("unroll") for (int k = 0; k < 2; ++k) \
;         acc[ai][bj][m][n] = __builtin_amdgcn_mfma_f32_16x16x32_bf16(Bt[n][k], At[m][k], acc[ai][bj][m][n], 0, 0, 0); __builtin_amdgcn_s_setprio(0); } while (0)
; #define PG8_WAIT_V(n) asm volatile("s_waitcnt vmcnt(" #n ")" ::: "memory")
; #define PG8_WAIT_L(n) asm volatile("s_waitcnt lgkmcnt(" #n ")" ::: "memory")
; #define PG8_BAR __builtin_amdgcn_s_barrier()
; #define PG8_SCHED __builtin_amdgcn_sched_barrier(0)
; template <class Epi, class Sched, bool ALIGN_EPI = false, bool SP2 = false>
; __device__ __forceinline__ void gemm_phase(PG8_LAS unsigned char* lds, const Gemm g, const Sched& S, const Epi& E) {
;     ...
;             PG8_WAIT_V(8); PG8_WAIT_L(0); PG8_BAR; PG8_MMA(1, 0, At, B0); PG8_MMA(1, 1, At, B1); PG8_BAR; PG8_SCHED;
;             PG8_LDB(B0, 1, 0); PG8_LDB(B1, 1, 1); PG8_SCHED; PG8_LDA(At, 1, 0); PG8_STAGE(PG8_SA(0, 1), a2 + hstep, voffA);
;             PG8_WAIT_V(8); PG8_WAIT_L(0); PG8_BAR; PG8_MMA(0, 0, At, B0); PG8_MMA(0, 1, At, B1); PG8_BAR; PG8_SCHED;
	s_setprio 1
	s_waitcnt lgkmcnt(0)
	v_mfma_f32_16x16x32_bf16 v[60:63], v[128:131], v[180:183], v[60:63]
	v_mfma_f32_16x16x32_bf16 v[56:59], v[136:139], v[180:183], v[56:59]
	v_mfma_f32_16x16x32_bf16 v[52:55], v[128:131], v[188:191], v[52:55]
	v_mfma_f32_16x16x32_bf16 v[48:51], v[136:139], v[188:191], v[48:51]
	v_mfma_f32_16x16x32_bf16 v[36:39], v[128:131], v[196:199], v[36:39]
	v_mfma_f32_16x16x32_bf16 v[24:27], v[136:139], v[196:199], v[24:27]
	v_mfma_f32_16x16x32_bf16 v[16:19], v[128:131], v[204:207], v[16:19]
	v_mfma_f32_16x16x32_bf16 v[8:11], v[136:139], v[204:207], v[8:11]
	v_mfma_f32_16x16x32_bf16 v[60:63], v[132:135], v[184:187], v[60:63]
	v_mfma_f32_16x16x32_bf16 v[56:59], v[140:143], v[184:187], v[56:59]
	v_mfma_f32_16x16x32_bf16 v[52:55], v[132:135], v[192:195], v[52:55]
	v_mfma_f32_16x16x32_bf16 v[48:51], v[140:143], v[192:195], v[48:51]
	v_mfma_f32_16x16x32_bf16 v[36:39], v[132:135], v[200:203], v[36:39]
	v_mfma_f32_16x16x32_bf16 v[24:27], v[140:143], v[200:203], v[24:27]
	v_mfma_f32_16x16x32_bf16 v[16:19], v[132:135], v[208:211], v[16:19]
	v_mfma_f32_16x16x32_bf16 v[8:11], v[140:143], v[208:211], v[8:11]
	s_setprio 0
	s_setprio 1
	v_mfma_f32_16x16x32_bf16 v[44:47], v[156:159], v[180:183], v[44:47]
	v_mfma_f32_16x16x32_bf16 v[40:43], v[172:175], v[180:183], v[40:43]
	v_mfma_f32_16x16x32_bf16 v[32:35], v[156:159], v[188:191], v[32:35]
	v_mfma_f32_16x16x32_bf16 v[28:31], v[172:175], v[188:191], v[28:31]
	v_mfma_f32_16x16x32_bf16 v[20:23], v[156:159], v[196:199], v[20:23]
	v_mfma_f32_16x16x32_bf16 v[12:15], v[172:175], v[196:199], v[12:15]
	v_mfma_f32_16x16x32_bf16 v[4:7], v[156:159], v[204:207], v[4:7]
	v_mfma_f32_16x16x32_bf16 v[0:3], v[172:175], v[204:207], v[0:3]
	v_mfma_f32_16x16x32_bf16 v[44:47], v[168:171], v[184:187], v[44:47]
	v_mfma_f32_16x16x32_bf16 v[40:43], v[176:179], v[184:187], v[40:43]
	v_mfma_f32_16x16x32_bf16 v[32:35], v[168:171], v[192:195], v[32:35]
	v_mfma_f32_16x16x32_bf16 v[28:31], v[176:179], v[192:195], v[28:31]
	v_mfma_f32_16x16x32_bf16 v[20:23], v[168:171], v[200:203], v[20:23]
	v_mfma_f32_16x16x32_bf16 v[12:15], v[176:179], v[200:203], v[12:15]
	v_mfma_f32_16x16x32_bf16 v[4:7], v[168:171], v[208:211], v[4:7]
	v_mfma_f32_16x16x32_bf16 v[0:3], v[176:179], v[208:211], v[0:3]
	s_setprio 0
	s_barrier
	s_add_i32 s54, 0, 0x18000
	s_add_i32 s55, 0, 0x1c000
	v_add_u32_e32 v140, s54, v163
	v_add_u32_e32 v176, s55, v163
	ds_read_b128 v[128:131], v140
	ds_read_b128 v[132:135], v140 offset:1024
	ds_read_b128 v[136:139], v140 offset:2048
	ds_read_b128 v[140:143], v140 offset:3072
	ds_read_b128 v[156:159], v176
	ds_read_b128 v[168:171], v176 offset:1024
	ds_read_b128 v[172:175], v176 offset:2048
	ds_read_b128 v[176:179], v176 offset:3072
	s_add_u32 s20, s26, 0x160000
	s_addc_u32 s21, s27, 0
	s_mov_b32 m0, s37
	v_lshl_add_u64 v[218:219], s[20:21], 0, v[144:145]
	ds_read_b128 v[180:183], v167 offset:32768
	ds_read_b128 v[184:187], v167 offset:33792
	ds_read_b128 v[188:191], v167 offset:34816
	ds_read_b128 v[192:195], v167 offset:35840
	ds_read_b128 v[196:199], v167 offset:36864
	ds_read_b128 v[200:203], v167 offset:37888
	ds_read_b128 v[204:207], v167 offset:38912
	ds_read_b128 v[208:211], v167 offset:39936
	global_load_lds_dwordx4 v[218:219], off
	v_lshl_add_u64 v[218:219], s[20:21], 0, v[146:147]
	s_mov_b32 m0, s38
	s_nop 0
	global_load_lds_dwordx4 v[218:219], off
	s_sleep 1
	s_waitcnt vmcnt(8)
	s_waitcnt lgkmcnt(0)
	s_barrier
	s_setprio 1
	s_waitcnt lgkmcnt(0)
	v_mfma_f32_16x16x32_bf16 v[124:127], v[128:131], v[180:183], v[124:127]
	v_mfma_f32_16x16x32_bf16 v[120:123], v[136:139], v[180:183], v[120:123]
	v_mfma_f32_16x16x32_bf16 v[116:119], v[128:131], v[188:191], v[116:119]
	v_mfma_f32_16x16x32_bf16 v[112:115], v[136:139], v[188:191], v[112:115]
	v_mfma_f32_16x16x32_bf16 v[92:95], v[128:131], v[196:199], v[92:95]
	v_mfma_f32_16x16x32_bf16 v[88:91], v[136:139], v[196:199], v[88:91]
	v_mfma_f32_16x16x32_bf16 v[84:87], v[128:131], v[204:207], v[84:87]
	v_mfma_f32_16x16x32_bf16 v[80:83], v[136:139], v[204:207], v[80:83]
	v_mfma_f32_16x16x32_bf16 v[124:127], v[132:135], v[184:187], v[124:127]
	v_mfma_f32_16x16x32_bf16 v[120:123], v[140:143], v[184:187], v[120:123]
	v_mfma_f32_16x16x32_bf16 v[116:119], v[132:135], v[192:195], v[116:119]
	v_mfma_f32_16x16x32_bf16 v[112:115], v[140:143], v[192:195], v[112:115]
	v_mfma_f32_16x16x32_bf16 v[92:95], v[132:135], v[200:203], v[92:95]
	v_mfma_f32_16x16x32_bf16 v[88:91], v[140:143], v[200:203], v[88:91]
	v_mfma_f32_16x16x32_bf16 v[84:87], v[132:135], v[208:211], v[84:87]
	v_mfma_f32_16x16x32_bf16 v[80:83], v[140:143], v[208:211], v[80:83]
	s_setprio 0
	s_setprio 1
	v_mfma_f32_16x16x32_bf16 v[108:111], v[156:159], v[180:183], v[108:111]
	v_mfma_f32_16x16x32_bf16 v[104:107], v[172:175], v[180:183], v[104:107]
	v_mfma_f32_16x16x32_bf16 v[100:103], v[156:159], v[188:191], v[100:103]
	v_mfma_f32_16x16x32_bf16 v[96:99], v[172:175], v[188:191], v[96:99]
	v_mfma_f32_16x16x32_bf16 v[76:79], v[156:159], v[196:199], v[76:79]
	v_mfma_f32_16x16x32_bf16 v[72:75], v[172:175], v[196:199], v[72:75]
	v_mfma_f32_16x16x32_bf16 v[68:71], v[156:159], v[204:207], v[68:71]
	v_mfma_f32_16x16x32_bf16 v[64:67], v[172:175], v[204:207], v[64:67]
	v_mfma_f32_16x16x32_bf16 v[108:111], v[168:171], v[184:187], v[108:111]
	v_mfma_f32_16x16x32_bf16 v[104:107], v[176:179], v[184:187], v[104:107]
	v_mfma_f32_16x16x32_bf16 v[100:103], v[168:171], v[192:195], v[100:103]
	v_mfma_f32_16x16x32_bf16 v[96:99], v[176:179], v[192:195], v[96:99]
	v_mfma_f32_16x16x32_bf16 v[76:79], v[168:171], v[200:203], v[76:79]
	v_mfma_f32_16x16x32_bf16 v[72:75], v[176:179], v[200:203], v[72:75]
	v_mfma_f32_16x16x32_bf16 v[68:71], v[168:171], v[208:211], v[68:71]
	v_mfma_f32_16x16x32_bf16 v[64:67], v[176:179], v[208:211], v[64:67]
	s_setprio 0
	s_barrier
; #define PG8_STAGE(bufoff, gbase, voff) do { _Pragma("unroll") for (int _i = 0; _i < 2; ++_i) \
;         __builtin_amdgcn_global_load_lds((const unsigned*)((const char*)(gbase) + (voff)[_i]), (PG8_LAS unsigned*)(lds + (bufoff) + ldsw + _i * 8192), 16, 0, 0); } while (0)
; #define PG8_LDA(dst, b, h) do { _Pragma("unroll") for (int m = 0; m < 4; ++m) _Pragma("unroll") for (int k = 0; k < 2; ++k) dst[m][k] = *(const PG8_LAS bf16x8*)(lds + PG8_SA(b, h) + aoff + m * 2048 + k * 1024); } while (0)
; #define PG8_MMA(ai, bj, At, Bt) do { __builtin_amdgcn_s_setprio(1); _Pragma("unroll") for (int m = 0; m < 4; ++m) _Pragma("unroll") for (int n = 0; n < 2; ++n) _Pragma("unroll") for (int k = 0; k < 2; ++k) \
;         acc[ai][bj][m][n] = __builtin_amdgcn_mfma_f32_16x16x32_bf16(Bt[n][k], At[m][k], acc[ai][bj][m][n], 0, 0, 0); __builtin_amdgcn_s_setprio(0); } while (0)
; #define PG8_WAIT_V(n) asm volatile("s_waitcnt vmcnt(" #n ")" ::: "memory")
; #define PG8_WAIT_L(n) asm volatile("s_waitcnt lgkmcnt(" #n ")" ::: "memory")
; #define PG8_BAR __builtin_amdgcn_s_barrier()
; #define PG8_SCHED __builtin_amdgcn_sched_barrier(0)
; template <class Epi, class Sched, bool ALIGN_EPI = false, bool SP2 = false>
; __device__ __forceinline__ void gemm_phase(PG8_LAS unsigned char* lds, const Gemm g, const Sched& S, const Epi& E) {
;     ...
;             PG8_LDA(At, 1, 1); PG8_STAGE(PG8_SB(1, 0), b3, voffB); PG8_STAGE(PG8_SB(1, 1), b3 + hstep, voffB); PG8_STAGE(PG8_SA(1, 0), a3, voffA);
;             PG8_WAIT_V(8); PG8_WAIT_L(0); PG8_BAR; PG8_MMA(1, 0, At, B0); PG8_MMA(1, 1, At, B1); PG8_BAR; PG8_SCHED;
;     ...
;         if constexpr (ALIGN_EPI) { if (wr == 0) PG8_BAR; }
	s_add_i32 s20, s54, s34
	v_lshl_add_u64 v[160:161], v[160:161], 0, s[12:13]
	s_mov_b32 m0, s20
	ds_read_b128 v[180:183], v167 offset:49152
	ds_read_b128 v[184:187], v167 offset:50176
	ds_read_b128 v[188:191], v167 offset:51200
	ds_read_b128 v[192:195], v167 offset:52224
	ds_read_b128 v[196:199], v167 offset:53248
	ds_read_b128 v[200:203], v167 offset:54272
	ds_read_b128 v[204:207], v167 offset:55296
	ds_read_b128 v[208:211], v167 offset:56320
	global_load_lds_dwordx4 v[160:161], off
	s_add_i32 m0, s20, 0x2000
	s_add_u32 s20, s24, 0x160080
	v_lshl_add_u64 v[160:161], v[212:213], 0, s[12:13]
	s_addc_u32 s21, s25, 0
	s_add_i32 s24, s55, s34
	global_load_lds_dwordx4 v[160:161], off
	v_lshl_add_u64 v[160:161], s[20:21], 0, v[144:145]
	s_mov_b32 m0, s24
	s_nop 0
	global_load_lds_dwordx4 v[160:161], off
	v_lshl_add_u64 v[160:161], s[20:21], 0, v[146:147]
	s_add_i32 m0, s24, 0x2000
	s_nop 0
	global_load_lds_dwordx4 v[160:161], off
	v_lshl_add_u64 v[160:161], v[214:215], 0, s[12:13]
	s_mov_b32 m0, s42
	s_nop 0
	global_load_lds_dwordx4 v[160:161], off
	v_lshl_add_u64 v[160:161], v[216:217], 0, s[12:13]
	s_mov_b32 m0, s43
	s_nop 0
	global_load_lds_dwordx4 v[160:161], off
	s_sleep 1
	s_waitcnt vmcnt(8)
	s_waitcnt lgkmcnt(0)
	s_barrier
	s_setprio 1
	s_waitcnt lgkmcnt(0)
	v_mfma_f32_16x16x32_bf16 v[60:63], v[128:131], v[180:183], v[60:63]
	v_mfma_f32_16x16x32_bf16 v[56:59], v[136:139], v[180:183], v[56:59]
	v_mfma_f32_16x16x32_bf16 v[52:55], v[128:131], v[188:191], v[52:55]
	v_mfma_f32_16x16x32_bf16 v[48:51], v[136:139], v[188:191], v[48:51]
	v_mfma_f32_16x16x32_bf16 v[36:39], v[128:131], v[196:199], v[36:39]
	v_mfma_f32_16x16x32_bf16 v[24:27], v[136:139], v[196:199], v[24:27]
	v_mfma_f32_16x16x32_bf16 v[16:19], v[128:131], v[204:207], v[16:19]
	v_mfma_f32_16x16x32_bf16 v[8:11], v[136:139], v[204:207], v[8:11]
	v_mfma_f32_16x16x32_bf16 v[60:63], v[132:135], v[184:187], v[60:63]
	v_mfma_f32_16x16x32_bf16 v[56:59], v[140:143], v[184:187], v[56:59]
	v_mfma_f32_16x16x32_bf16 v[52:55], v[132:135], v[192:195], v[52:55]
	v_mfma_f32_16x16x32_bf16 v[48:51], v[140:143], v[192:195], v[48:51]
	v_mfma_f32_16x16x32_bf16 v[36:39], v[132:135], v[200:203], v[36:39]
	v_mfma_f32_16x16x32_bf16 v[24:27], v[140:143], v[200:203], v[24:27]
	v_mfma_f32_16x16x32_bf16 v[16:19], v[132:135], v[208:211], v[16:19]
	v_mfma_f32_16x16x32_bf16 v[8:11], v[140:143], v[208:211], v[8:11]
	s_setprio 0
	s_setprio 1
	v_mfma_f32_16x16x32_bf16 v[44:47], v[156:159], v[180:183], v[44:47]
	v_mfma_f32_16x16x32_bf16 v[40:43], v[172:175], v[180:183], v[40:43]
	v_mfma_f32_16x16x32_bf16 v[32:35], v[156:159], v[188:191], v[32:35]
	v_mfma_f32_16x16x32_bf16 v[28:31], v[172:175], v[188:191], v[28:31]
	v_mfma_f32_16x16x32_bf16 v[20:23], v[156:159], v[196:199], v[20:23]
	v_mfma_f32_16x16x32_bf16 v[12:15], v[172:175], v[196:199], v[12:15]
	v_mfma_f32_16x16x32_bf16 v[4:7], v[156:159], v[204:207], v[4:7]
	v_mfma_f32_16x16x32_bf16 v[0:3], v[172:175], v[204:207], v[0:3]
	v_mfma_f32_16x16x32_bf16 v[44:47], v[168:171], v[184:187], v[44:47]
	v_mfma_f32_16x16x32_bf16 v[40:43], v[176:179], v[184:187], v[40:43]
	v_mfma_f32_16x16x32_bf16 v[32:35], v[168:171], v[192:195], v[32:35]
	v_mfma_f32_16x16x32_bf16 v[28:31], v[176:179], v[192:195], v[28:31]
	v_mfma_f32_16x16x32_bf16 v[20:23], v[168:171], v[200:203], v[20:23]
	v_mfma_f32_16x16x32_bf16 v[12:15], v[176:179], v[200:203], v[12:15]
	v_mfma_f32_16x16x32_bf16 v[4:7], v[168:171], v[208:211], v[4:7]
	v_mfma_f32_16x16x32_bf16 v[0:3], v[176:179], v[208:211], v[0:3]
	s_setprio 0
	s_barrier
	s_add_i32 s53, s53, 2
	s_add_u32 s51, s51, 0x100
	s_addc_u32 s52, s52, 0
	s_cmpk_gt_u32 s53, 0x55
	s_mov_b64 s[20:21], s[22:23]
	s_cbranch_scc0 .LBB0_1597
	s_and_b64 vcc, exec, s[14:15]
	s_cbranch_vccz .LBB0_1600
	s_barrier
